# v58 + prep-phase packed f32 ops split into scalar pairs (bit-identical)
# baseline (speedup 1.0000x reference)
; DI float bf2f(bf16_t b) { return __uint_as_float(((unsigned)b) << 16); }
; DI unsigned pk2(float lo, float hi) { f32x2 v = {lo, hi}; bfv2 b = __builtin_convertvector(v, bfv2); return __builtin_bit_cast(unsigned, b); }
; DI void prep_load(PrepIn& I, const Params& p, int j, int item, int tid) {
;     const bf16_t* H = (const bf16_t*)(p.ws + WS_H);
;     const int c = item >> 2, h = item & 3; const size_t row0 = (size_t)c * 64;
;     const int dir = tid >> 8, kk = tid & 255;
;     { const int t = tid >> 3, sg = tid & 7; I.rr = *(const u32x2*)(H + (row0 + t) * HE + 8192 + sg * 4); }
;     const float* wgf = p.in[9]; const float* wgb = p.in[11]; const float* bgf = p.in[10]; const float* bgb = p.in[12];
;     const float* wg = (dir ? wgb : wgf) + (size_t)j * 16 * 1024 + h * 256 + kk;
; #pragma unroll
;     for (int i = 0; i < 16; ++i) I.w[i] = wg[i * 1024];
;     I.bias = (dir ? bgb : bgf)[j * 1024 + h * 256 + kk];
; #pragma unroll
;     for (int it = 0; it < 4; ++it) { const int idx = it * 512 + tid; const int t = idx >> 5, seg = idx & 31;
;         I.q[it] = *(const u32x4*)(H + (row0 + t) * HE + 2048 + h * 256 + seg * 8);
;         I.k[it] = *(const u32x4*)(H + (row0 + t) * HE + h * 256 + seg * 8);
;         I.v[it] = *(const u32x4*)(H + (row0 + t) * HE + 1024 + h * 256 + seg * 8); }
; }
; DI void phase_prep(const Params& p, int j, unsigned char* lds) {
;     ...
;         ((float*)(p.ws + WS_DD))[(size_t)(item * 2 + dir) * 256 + kk] = dlast;
;         { const int nitem = item + (int)gridDim.x; prep_load(I, p, j, nitem < NCH * 4 ? nitem : item, tid); }
;         {
;             bf16_t* KHp = (bf16_t*)(p.ws + WS_KH) + (size_t)(item * 2 + dir) * 16384;
;             const int w8 = kk >> 5, r = kk & 31;
; #pragma unroll
;             for (int tg = 0; tg < 8; ++tg) {
;                 float val[8];
; #pragma unroll
;                 for (int i = 0; i < 8; ++i) val[i] = bf2f(kt[(dir * 64 + 8 * tg + i) * 264 + kk]) * dlast;
;                 u32x4 pk; pk.x = pk2(val[0], val[1]); pk.y = pk2(val[2], val[3]); pk.z = pk2(val[4], val[5]); pk.w = pk2(val[6], val[7]);
;                 const int s = tg >> 1, hh = tg & 1;
;                 *(u32x4*)(KHp + ((w8 * 4 + s) * 64 + hh * 32 + r) * 8) = pk;
.LBB0_353:
	s_or_b64 exec, exec, s[56:57]
	s_lshl_b32 s58, s54, 1
	s_add_i32 s81, s54, s71
	s_cmpk_lt_i32 s81, 0x820
	s_cselect_b64 s[56:57], -1, 0
	s_and_b64 s[60:61], s[56:57], exec
	v_add_u32_e32 v116, s58, v1
	s_cselect_b32 s52, s81, s54
	v_ashrrev_i32_e32 v117, 31, v116
	s_ashr_i32 s60, s52, 2
	v_lshlrev_b64 v[18:19], 10, v[116:117]
	s_ashr_i32 s61, s60, 31
	v_lshl_add_u64 v[18:19], v[94:95], 0, v[18:19]
	s_lshl_b64 s[60:61], s[60:61], 6
	global_store_dword v[18:19], v112, off
	v_lshl_add_u64 v[18:19], s[60:61], 0, v[66:67]
	v_mov_b64_e32 v[38:39], s[50:51]
	v_mad_u64_u32 v[20:21], s[82:83], v18, s33, v[38:39]
	v_mad_i32_i24 v21, v19, s33, v21
	v_lshl_add_u64 v[18:19], v[20:21], 0, v[68:69]
	s_lshl_b32 s52, s52, 8
	v_add_co_u32_e32 v18, vcc, s62, v18
	s_and_b32 s55, s52, 0x300
	s_nop 0
	v_addc_co_u32_e32 v19, vcc, 0, v19, vcc
	s_lshl_b32 s52, s55, 2
	global_load_dwordx2 v[114:115], v[18:19], off
	v_lshl_add_u64 v[18:19], v[96:97], 0, s[52:53]
	v_add_co_u32_e32 v20, vcc, s64, v18
	s_lshl_b32 s52, s55, 1
	s_nop 0
	v_addc_co_u32_e32 v21, vcc, 0, v19, vcc
	v_add_co_u32_e32 v22, vcc, s62, v18
	v_mov_b32_e32 v101, v69
	s_nop 0
	v_addc_co_u32_e32 v23, vcc, 0, v19, vcc
	v_add_co_u32_e32 v24, vcc, s65, v18
	v_lshlrev_b64 v[116:117], 15, v[116:117]
	s_nop 0
	v_addc_co_u32_e32 v25, vcc, 0, v19, vcc
	v_add_co_u32_e32 v26, vcc, s66, v18
	s_ashr_i32 s59, s58, 31
	s_nop 0
	v_addc_co_u32_e32 v27, vcc, 0, v19, vcc
	global_load_dword v76, v[20:21], off offset:-4096
	global_load_dword v83, v[20:21], off
	global_load_dword v77, v[22:23], off offset:-4096
	global_load_dword v74, v[22:23], off
	global_load_dword v78, v[24:25], off offset:-4096
	global_load_dword v75, v[24:25], off
	global_load_dword v79, v[26:27], off offset:-4096
	global_load_dword v80, v[26:27], off
	v_add_co_u32_e32 v20, vcc, s67, v18
	s_nop 1
	v_addc_co_u32_e32 v21, vcc, 0, v19, vcc
	v_add_co_u32_e32 v22, vcc, s68, v18
	s_nop 1
	v_addc_co_u32_e32 v23, vcc, 0, v19, vcc
	v_add_co_u32_e32 v24, vcc, s69, v18
	s_nop 1
	v_addc_co_u32_e32 v25, vcc, 0, v19, vcc
	global_load_dword v90, v[20:21], off offset:-4096
	global_load_dword v81, v[20:21], off
	global_load_dword v91, v[22:23], off offset:-4096
	global_load_dword v88, v[22:23], off
	global_load_dword v92, v[24:25], off offset:-4096
	global_load_dword v89, v[24:25], off
	v_add_co_u32_e32 v20, vcc, s70, v18
	s_nop 1
	v_addc_co_u32_e32 v21, vcc, 0, v19, vcc
	global_load_dword v85, v[18:19], off
	global_load_dword v93, v[20:21], off
	v_or_b32_sdwa v18, s55, v254 dst_sel:DWORD dst_unused:UNUSED_PAD src0_sel:DWORD src1_sel:BYTE_0
	v_lshlrev_b32_e32 v18, 2, v18
	v_mov_b32_e32 v19, v69
	v_lshl_add_u64 v[18:19], v[70:71], 0, v[18:19]
	global_load_dword v123, v[18:19], off
	v_or_b32_e32 v18, s60, v72
	v_mad_u64_u32 v[18:19], s[82:83], v18, s33, v[38:39]
	v_mad_i32_i24 v19, s61, v73, v19
	v_lshl_add_u64 v[18:19], v[18:19], 0, s[52:53]
	v_lshl_add_u64 v[22:23], v[18:19], 0, v[100:101]
	v_add_co_u32_e32 v24, vcc, s63, v22
	global_load_dwordx4 v[18:21], v[22:23], off
	global_load_dwordx4 v[50:53], v[22:23], off offset:2048
	v_or_b32_e32 v22, s60, v82
	v_addc_co_u32_e32 v25, vcc, 0, v23, vcc
	v_mad_u64_u32 v[22:23], s[82:83], v22, s33, v[38:39]
	v_mad_i32_i24 v23, s61, v73, v23
	v_lshl_add_u64 v[22:23], v[22:23], 0, s[52:53]
	v_lshl_add_u64 v[34:35], v[22:23], 0, v[100:101]
	v_add_co_u32_e32 v30, vcc, s63, v34
	s_nop 1
	v_addc_co_u32_e32 v31, vcc, 0, v35, vcc
	global_load_dwordx4 v[22:25], v[24:25], off
	s_nop 0
	global_load_dwordx4 v[26:29], v[34:35], off
	s_nop 0
	global_load_dwordx4 v[30:33], v[30:31], off
	s_nop 0
	global_load_dwordx4 v[54:57], v[34:35], off offset:2048
	v_or_b32_e32 v34, s60, v84
	v_mad_u64_u32 v[34:35], s[82:83], v34, s33, v[38:39]
	v_mad_i32_i24 v35, s61, v73, v35
	v_lshl_add_u64 v[34:35], v[34:35], 0, s[52:53]
	v_lshl_add_u64 v[40:41], v[34:35], 0, v[100:101]
	v_add_co_u32_e32 v42, vcc, s63, v40
	global_load_dwordx4 v[34:37], v[40:41], off
	global_load_dwordx4 v[58:61], v[40:41], off offset:2048
	v_addc_co_u32_e32 v43, vcc, 0, v41, vcc
	v_lshl_add_u64 v[40:41], s[60:61], 0, v[86:87]
	v_mad_u64_u32 v[38:39], s[60:61], v40, s33, v[38:39]
	v_mad_i32_i24 v39, v41, s33, v39
	v_lshl_add_u64 v[38:39], v[38:39], 0, s[52:53]
	v_lshl_add_u64 v[62:63], v[38:39], 0, v[100:101]
	v_add_co_u32_e32 v46, vcc, s63, v62
	s_lshl_b64 s[60:61], s[58:59], 15
	s_nop 0
	v_addc_co_u32_e32 v47, vcc, 0, v63, vcc
	global_load_dwordx4 v[38:41], v[42:43], off
	s_nop 0
	global_load_dwordx4 v[42:45], v[62:63], off
	s_nop 0
	global_load_dwordx4 v[46:49], v[46:47], off
	s_nop 0
	global_load_dwordx4 v[62:65], v[62:63], off offset:2048
	ds_read_u16 v101, v134
	ds_read_u16 v103, v134 offset:528
	ds_read_u16 v105, v134 offset:1056
	ds_read_u16 v107, v134 offset:1584
	ds_read_u16 v109, v134 offset:2112
	ds_read_u16 v111, v134 offset:2640
	ds_read_u16 v162, v134 offset:3168
	s_waitcnt lgkmcnt(4)
	v_lshlrev_b32_e32 v156, 16, v105
	s_waitcnt lgkmcnt(3)
	v_lshlrev_b32_e32 v157, 16, v107
	v_lshlrev_b32_e32 v119, 16, v103
	ds_read_u16 v103, v134 offset:33264
	v_lshlrev_b32_e32 v118, 16, v101
	v_mul_f32_e64 v158, v112, v156
	v_mul_f32_e64 v159, v112, v157
	s_waitcnt lgkmcnt(2)
	v_lshlrev_b32_e32 v157, 16, v111
	v_lshlrev_b32_e32 v156, 16, v109
	ds_read_u16 v101, v134 offset:3696
	ds_read_u16 v105, v134 offset:4224
	ds_read_u16 v107, v134 offset:4752
	ds_read_u16 v109, v134 offset:5280
	ds_read_u16 v111, v134 offset:5808
	ds_read_u16 v164, v134 offset:6336
	ds_read_u16 v165, v134 offset:6864
	ds_read_u16 v166, v134 offset:7392
	v_mul_f32_e64 v160, v112, v156
	v_mul_f32_e64 v161, v112, v157
	s_waitcnt lgkmcnt(7)
; DI float bf2f(bf16_t b) { return __uint_as_float(((unsigned)b) << 16); }
; DI unsigned pk2(float lo, float hi) { f32x2 v = {lo, hi}; bfv2 b = __builtin_convertvector(v, bfv2); return __builtin_bit_cast(unsigned, b); }
; DI void phase_prep(const Params& p, int j, unsigned char* lds) {
;     ...
;             bf16_t* KHp = (bf16_t*)(p.ws + WS_KH) + (size_t)(item * 2 + dir) * 16384;
;             const int w8 = kk >> 5, r = kk & 31;
; #pragma unroll
;             for (int tg = 0; tg < 8; ++tg) {
;                 float val[8];
; #pragma unroll
;                 for (int i = 0; i < 8; ++i) val[i] = bf2f(kt[(dir * 64 + 8 * tg + i) * 264 + kk]) * dlast;
;                 u32x4 pk; pk.x = pk2(val[0], val[1]); pk.y = pk2(val[2], val[3]); pk.z = pk2(val[4], val[5]); pk.w = pk2(val[6], val[7]);
;                 const int s = tg >> 1, hh = tg & 1;
;                 *(u32x4*)(KHp + ((w8 * 4 + s) * 64 + hh * 32 + r) * 8) = pk;
;             }
	v_lshlrev_b32_e32 v157, 16, v101
	v_lshlrev_b32_e32 v156, 16, v162
	v_mul_f32_e64 v118, v112, v118
	v_mul_f32_e64 v119, v112, v119
	v_mul_f32_e64 v162, v112, v156
	v_mul_f32_e64 v163, v112, v157
	v_cvt_pk_bf16_f32 v156, v118, v119
	v_cvt_pk_bf16_f32 v157, v158, v159
	v_cvt_pk_bf16_f32 v158, v160, v161
	v_cvt_pk_bf16_f32 v159, v162, v163
	v_lshl_add_u64 v[160:161], v[98:99], 0, v[116:117]
	global_store_dwordx4 v[160:161], v[156:159], off
	s_waitcnt lgkmcnt(5)
	v_lshlrev_b32_e32 v117, 16, v107
	v_lshlrev_b32_e32 v116, 16, v105
	s_waitcnt lgkmcnt(3)
	v_lshlrev_b32_e32 v119, 16, v111
	v_lshlrev_b32_e32 v118, 16, v109
	s_waitcnt lgkmcnt(1)
	v_lshlrev_b32_e32 v157, 16, v165
	v_lshlrev_b32_e32 v156, 16, v164
	ds_read_u16 v101, v134 offset:7920
	ds_read_u16 v105, v134 offset:8448
	ds_read_u16 v107, v134 offset:8976
	ds_read_u16 v109, v134 offset:9504
	ds_read_u16 v111, v134 offset:10032
	ds_read_u16 v162, v134 offset:10560
	ds_read_u16 v163, v134 offset:11088
	ds_read_u16 v164, v134 offset:11616
	s_waitcnt lgkmcnt(7)
	v_lshlrev_b32_e32 v159, 16, v101
	v_lshlrev_b32_e32 v158, 16, v166
	v_mul_f32_e64 v116, v112, v116
	v_mul_f32_e64 v117, v112, v117
	v_mul_f32_e64 v118, v112, v118
	v_mul_f32_e64 v119, v112, v119
	v_mul_f32_e64 v156, v112, v156
	v_mul_f32_e64 v157, v112, v157
	v_mul_f32_e64 v158, v112, v158
	v_mul_f32_e64 v159, v112, v159
	v_cvt_pk_bf16_f32 v116, v116, v117
	v_cvt_pk_bf16_f32 v117, v118, v119
	v_cvt_pk_bf16_f32 v118, v156, v157
	v_cvt_pk_bf16_f32 v119, v158, v159
	global_store_dwordx4 v[160:161], v[116:119], off offset:512
	s_waitcnt lgkmcnt(1)
	v_lshlrev_b32_e32 v157, 16, v163
	v_lshlrev_b32_e32 v156, 16, v162
	v_lshlrev_b32_e32 v117, 16, v107
	v_lshlrev_b32_e32 v116, 16, v105
	v_lshlrev_b32_e32 v119, 16, v111
	v_lshlrev_b32_e32 v118, 16, v109
	ds_read_u16 v101, v134 offset:12144
	ds_read_u16 v105, v134 offset:12672
	ds_read_u16 v107, v134 offset:13200
	ds_read_u16 v109, v134 offset:13728
	ds_read_u16 v111, v134 offset:14256
	ds_read_u16 v162, v134 offset:14784
	ds_read_u16 v163, v134 offset:15312
	ds_read_u16 v165, v134 offset:15840
	s_waitcnt lgkmcnt(7)
	v_lshlrev_b32_e32 v159, 16, v101
	v_lshlrev_b32_e32 v158, 16, v164
	v_mul_f32_e64 v116, v112, v116
	v_mul_f32_e64 v117, v112, v117
	v_mul_f32_e64 v118, v112, v118
	v_mul_f32_e64 v119, v112, v119
	v_mul_f32_e64 v156, v112, v156
	v_mul_f32_e64 v157, v112, v157
	v_mul_f32_e64 v158, v112, v158
	v_mul_f32_e64 v159, v112, v159
	v_cvt_pk_bf16_f32 v116, v116, v117
	v_cvt_pk_bf16_f32 v117, v118, v119
	v_cvt_pk_bf16_f32 v118, v156, v157
	v_cvt_pk_bf16_f32 v119, v158, v159
	global_store_dwordx4 v[160:161], v[116:119], off offset:1024
	s_waitcnt lgkmcnt(1)
	v_lshlrev_b32_e32 v157, 16, v163
	v_lshlrev_b32_e32 v156, 16, v162
	v_lshlrev_b32_e32 v117, 16, v107
	v_lshlrev_b32_e32 v116, 16, v105
	v_lshlrev_b32_e32 v119, 16, v111
	v_lshlrev_b32_e32 v118, 16, v109
	ds_read_u16 v101, v134 offset:16368
	ds_read_u16 v105, v134 offset:16896
	ds_read_u16 v107, v134 offset:17424
	ds_read_u16 v109, v134 offset:17952
	ds_read_u16 v111, v134 offset:18480
	ds_read_u16 v162, v134 offset:19008
	ds_read_u16 v163, v134 offset:19536
	ds_read_u16 v164, v134 offset:20064
	s_waitcnt lgkmcnt(7)
	v_lshlrev_b32_e32 v159, 16, v101
	v_lshlrev_b32_e32 v158, 16, v165
	v_mul_f32_e64 v116, v112, v116
	v_mul_f32_e64 v117, v112, v117
	v_mul_f32_e64 v118, v112, v118
	v_mul_f32_e64 v119, v112, v119
	v_mul_f32_e64 v156, v112, v156
	v_mul_f32_e64 v157, v112, v157
	v_mul_f32_e64 v158, v112, v158
	v_mul_f32_e64 v159, v112, v159
	v_cvt_pk_bf16_f32 v116, v116, v117
	v_cvt_pk_bf16_f32 v117, v118, v119
	v_cvt_pk_bf16_f32 v118, v156, v157
	v_cvt_pk_bf16_f32 v119, v158, v159
	global_store_dwordx4 v[160:161], v[116:119], off offset:1536
	s_waitcnt lgkmcnt(1)
	v_lshlrev_b32_e32 v157, 16, v163
	v_lshlrev_b32_e32 v156, 16, v162
	v_lshlrev_b32_e32 v117, 16, v107
	v_lshlrev_b32_e32 v116, 16, v105
	v_lshlrev_b32_e32 v119, 16, v111
	v_lshlrev_b32_e32 v118, 16, v109
	ds_read_u16 v101, v134 offset:20592
	ds_read_u16 v105, v134 offset:21120
	ds_read_u16 v107, v134 offset:21648
	ds_read_u16 v109, v134 offset:22176
	ds_read_u16 v111, v134 offset:22704
	ds_read_u16 v162, v134 offset:23232
	ds_read_u16 v163, v134 offset:23760
	ds_read_u16 v165, v134 offset:24288
	s_waitcnt lgkmcnt(7)
	v_lshlrev_b32_e32 v159, 16, v101
	v_lshlrev_b32_e32 v158, 16, v164
	v_mul_f32_e64 v116, v112, v116
	v_mul_f32_e64 v117, v112, v117
	v_mul_f32_e64 v118, v112, v118
	v_mul_f32_e64 v119, v112, v119
	v_mul_f32_e64 v156, v112, v156
	v_mul_f32_e64 v157, v112, v157
	v_mul_f32_e64 v158, v112, v158
	v_mul_f32_e64 v159, v112, v159
	v_cvt_pk_bf16_f32 v116, v116, v117
	v_cvt_pk_bf16_f32 v117, v118, v119
	v_cvt_pk_bf16_f32 v118, v156, v157
	v_cvt_pk_bf16_f32 v119, v158, v159
	global_store_dwordx4 v[160:161], v[116:119], off offset:2048
	s_waitcnt lgkmcnt(1)
	v_lshlrev_b32_e32 v157, 16, v163
	v_lshlrev_b32_e32 v156, 16, v162
	v_lshlrev_b32_e32 v117, 16, v107
	v_lshlrev_b32_e32 v116, 16, v105
	v_lshlrev_b32_e32 v119, 16, v111
	v_lshlrev_b32_e32 v118, 16, v109
	ds_read_u16 v101, v134 offset:24816
	ds_read_u16 v105, v134 offset:25344
	ds_read_u16 v107, v134 offset:25872
	ds_read_u16 v109, v134 offset:26400
	ds_read_u16 v111, v134 offset:26928
	ds_read_u16 v162, v134 offset:27456
	ds_read_u16 v163, v134 offset:27984
	ds_read_u16 v164, v134 offset:28512
	s_waitcnt lgkmcnt(7)
	v_lshlrev_b32_e32 v159, 16, v101
	v_lshlrev_b32_e32 v158, 16, v165
	v_mul_f32_e64 v116, v112, v116
	v_mul_f32_e64 v117, v112, v117
	v_mul_f32_e64 v118, v112, v118
	v_mul_f32_e64 v119, v112, v119
	v_mul_f32_e64 v156, v112, v156
	v_mul_f32_e64 v157, v112, v157
	v_mul_f32_e64 v158, v112, v158
	v_mul_f32_e64 v159, v112, v159
	v_cvt_pk_bf16_f32 v116, v116, v117
	v_cvt_pk_bf16_f32 v117, v118, v119
	v_cvt_pk_bf16_f32 v118, v156, v157
	v_cvt_pk_bf16_f32 v119, v158, v159
	global_store_dwordx4 v[160:161], v[116:119], off offset:2560
	s_waitcnt lgkmcnt(1)
; DI float bf2f(bf16_t b) { return __uint_as_float(((unsigned)b) << 16); }
; DI void phase_prep(const Params& p, int j, unsigned char* lds) {
;     ...
;             bf16_t* KHp = (bf16_t*)(p.ws + WS_KH) + (size_t)(item * 2 + dir) * 16384;
;             const int w8 = kk >> 5, r = kk & 31;
; #pragma unroll
;             for (int tg = 0; tg < 8; ++tg) {
;                 float val[8];
; #pragma unroll
;                 for (int i = 0; i < 8; ++i) val[i] = bf2f(kt[(dir * 64 + 8 * tg + i) * 264 + kk]) * dlast;
;                 u32x4 pk; pk.x = pk2(val[0], val[1]); pk.y = pk2(val[2], val[3]); pk.z = pk2(val[4], val[5]); pk.w = pk2(val[6], val[7]);
;                 const int s = tg >> 1, hh = tg & 1;
;                 *(u32x4*)(KHp + ((w8 * 4 + s) * 64 + hh * 32 + r) * 8) = pk;
;             }
;         }
;         __syncthreads();
;         {
;             bf16_t* QTp = (bf16_t*)(p.ws + WS_U) + (size_t)(item * 2) * 16384;
; #pragma unroll
;             for (int it = 0; it < 8; ++it) {
;                 const int idx = it * 512 + tid; const int d2 = idx >> 11, f = (idx >> 6) & 31, ln = idx & 63;
;                 const int w8 = f >> 2, mb = (f >> 1) & 1, s = f & 1, rr = ln & 31, hh = ln >> 5;
;                 const bf16_t* sp = qt + (d2 * 64 + 32 * mb + rr) * 264 + 32 * w8 + 16 * s + 4 * hh;
;                 const u32x2 lo = *(const u32x2*)sp, hi = *(const u32x2*)(sp + 8);
;                 u32x4 o; o.x = lo.x; o.y = lo.y; o.z = hi.x; o.w = hi.y;
;                 *(u32x4*)(QTp + (size_t)d2 * 16384 + (f * 64 + ln) * 8) = o;
;             }
;         }
;         float amask[4][4];
;         {
;             const int d2 = wave >> 2, wd = wave & 3, fr = lane & 15, fq = lane >> 4;
;             f32x4 acc[4];
; #pragma unroll
;             for (int nb = 0; nb < 4; ++nb) acc[nb] = (f32x4){0.f, 0.f, 0.f, 0.f};
;             const bf16_t* qb = qt + (d2 * 64 + 16 * wd + fr) * 264 + 8 * fq;
;             const bf16_t* kb = kt + (d2 * 64 + fr) * 264 + 8 * fq;
; #pragma unroll
;             for (int ks = 0; ks < 8; ++ks) {
;                 const bf16x8 a = *(const bf16x8*)(qb + 32 * ks);
; #pragma unroll
;                 for (int nb = 0; nb < 4; ++nb) { const bf16x8 b = *(const bf16x8*)(kb + nb * 16 * 264 + 32 * ks); acc[nb] = __builtin_amdgcn_mfma_f32_16x16x32_bf16(a, b, acc[nb], 0, 0, 0); }
;             }
	v_lshlrev_b32_e32 v157, 16, v163
	v_lshlrev_b32_e32 v156, 16, v162
	v_lshlrev_b32_e32 v117, 16, v107
	v_lshlrev_b32_e32 v116, 16, v105
	v_lshlrev_b32_e32 v119, 16, v111
	v_lshlrev_b32_e32 v118, 16, v109
	ds_read_u16 v101, v134 offset:29040
	ds_read_u16 v105, v134 offset:29568
	ds_read_u16 v107, v134 offset:30096
	ds_read_u16 v109, v134 offset:30624
	ds_read_u16 v111, v134 offset:31152
	ds_read_u16 v162, v134 offset:31680
	ds_read_u16 v163, v134 offset:32208
	ds_read_u16 v165, v134 offset:32736
	s_waitcnt lgkmcnt(7)
	v_lshlrev_b32_e32 v159, 16, v101
	v_lshlrev_b32_e32 v158, 16, v164
	v_mul_f32_e64 v116, v112, v116
	v_mul_f32_e64 v117, v112, v117
	v_mul_f32_e64 v118, v112, v118
	v_mul_f32_e64 v119, v112, v119
	v_mul_f32_e64 v156, v112, v156
	v_mul_f32_e64 v157, v112, v157
	v_mul_f32_e64 v158, v112, v158
	v_mul_f32_e64 v159, v112, v159
	v_cvt_pk_bf16_f32 v116, v116, v117
	v_cvt_pk_bf16_f32 v117, v118, v119
	v_cvt_pk_bf16_f32 v118, v156, v157
	v_cvt_pk_bf16_f32 v119, v158, v159
	global_store_dwordx4 v[160:161], v[116:119], off offset:3072
	s_waitcnt lgkmcnt(1)
	v_lshlrev_b32_e32 v157, 16, v163
	v_lshlrev_b32_e32 v156, 16, v162
	v_lshlrev_b32_e32 v117, 16, v107
	v_lshlrev_b32_e32 v116, 16, v105
	v_lshlrev_b32_e32 v119, 16, v111
	v_lshlrev_b32_e32 v118, 16, v109
	v_lshlrev_b32_e32 v159, 16, v103
	s_waitcnt lgkmcnt(0)
	v_lshlrev_b32_e32 v158, 16, v165
	v_mul_f32_e64 v116, v112, v116
	v_mul_f32_e64 v117, v112, v117
	v_mul_f32_e64 v118, v112, v118
	v_mul_f32_e64 v119, v112, v119
	v_mul_f32_e64 v156, v112, v156
	v_mul_f32_e64 v157, v112, v157
	v_mul_f32_e64 v158, v112, v158
	v_mul_f32_e64 v159, v112, v159
	v_cvt_pk_bf16_f32 v116, v116, v117
	v_cvt_pk_bf16_f32 v117, v118, v119
	v_cvt_pk_bf16_f32 v118, v156, v157
	v_cvt_pk_bf16_f32 v119, v158, v159
	global_store_dwordx4 v[160:161], v[116:119], off offset:3584
	s_barrier
	ds_read_b128 v[116:119], v121 offset:8192
	ds_read_b128 v[156:159], v122
	ds_read_b128 v[160:163], v121 offset:8256
	ds_read_b128 v[164:167], v122 offset:64
	ds_read_b128 v[168:171], v122 offset:8448
	ds_read_b128 v[172:175], v122 offset:8512
	s_waitcnt lgkmcnt(4)
	v_mfma_f32_16x16x32_bf16 v[156:159], v[116:119], v[156:159], 0
	ds_read_b128 v[176:179], v122 offset:16896
	ds_read_b128 v[180:183], v122 offset:16960
	ds_read_b128 v[184:187], v122 offset:25344
	ds_read_b128 v[188:191], v122 offset:25408
	v_add_u32_e32 v101, 0x2000, v135
	s_waitcnt lgkmcnt(5)
	v_mfma_f32_16x16x32_bf16 v[168:171], v[116:119], v[168:171], 0
	s_add_u32 s60, s72, s60
	s_addc_u32 s61, s73, s61
	v_mov_b32_e32 v105, v69
	v_mfma_f32_16x16x32_bf16 v[156:159], v[160:163], v[164:167], v[156:159]
	v_mov_b32_e32 v107, v69
	s_add_u32 s82, s60, 0x8000
	s_addc_u32 s83, s61, 0
	s_waitcnt lgkmcnt(4)
	v_mfma_f32_16x16x32_bf16 v[164:167], v[160:163], v[172:175], v[168:171]
	ds_read_b128 v[172:175], v121 offset:8320
	v_mov_b32_e32 v109, v69
	v_mov_b32_e32 v111, v69
	s_waitcnt lgkmcnt(4)
	v_mfma_f32_16x16x32_bf16 v[176:179], v[116:119], v[176:179], 0
	s_lshl_b64 s[58:59], s[58:59], 13
	s_add_u32 s58, s74, s58
	v_mov_b32_e32 v103, v69
	s_waitcnt lgkmcnt(2)
	v_mfma_f32_16x16x32_bf16 v[116:119], v[116:119], v[184:187], 0
	s_addc_u32 s59, s75, s59
	s_ashr_i32 s55, s54, 31
	s_lshl_b64 s[54:55], s[54:55], 15
	v_mfma_f32_16x16x32_bf16 v[168:171], v[160:163], v[180:183], v[176:179]
	s_add_u32 s54, s76, s54
	s_addc_u32 s55, s77, s55
	s_waitcnt lgkmcnt(1)
	v_mfma_f32_16x16x32_bf16 v[116:119], v[160:163], v[188:191], v[116:119]
	ds_read_b128 v[160:163], v122 offset:128
	ds_read_b128 v[176:179], v121 offset:8384
	ds_read_b128 v[180:183], v122 offset:192
	s_waitcnt lgkmcnt(2)
	v_mfma_f32_16x16x32_bf16 v[156:159], v[172:175], v[160:163], v[156:159]
	ds_read_b128 v[160:163], v122 offset:8576
	ds_read_b128 v[184:187], v122 offset:8640
	s_waitcnt lgkmcnt(1)
	v_mfma_f32_16x16x32_bf16 v[160:163], v[172:175], v[160:163], v[164:167]
	s_nop 2
	ds_read_b128 v[164:167], v122 offset:17024
	ds_read_b128 v[188:191], v122 offset:17088
	s_waitcnt lgkmcnt(1)
	v_mfma_f32_16x16x32_bf16 v[164:167], v[172:175], v[164:167], v[168:171]
	s_nop 2
	ds_read_b128 v[168:171], v122 offset:25472
	ds_read_b128 v[192:195], v122 offset:25536
	s_waitcnt lgkmcnt(1)
	v_mfma_f32_16x16x32_bf16 v[116:119], v[172:175], v[168:171], v[116:119]
	ds_read_b128 v[168:171], v121 offset:8448
	ds_read_b128 v[172:175], v122 offset:256
	v_mfma_f32_16x16x32_bf16 v[156:159], v[176:179], v[180:183], v[156:159]
	v_mfma_f32_16x16x32_bf16 v[160:163], v[176:179], v[184:187], v[160:163]
	v_mfma_f32_16x16x32_bf16 v[164:167], v[176:179], v[188:191], v[164:167]
	s_waitcnt lgkmcnt(2)
	v_mfma_f32_16x16x32_bf16 v[116:119], v[176:179], v[192:195], v[116:119]
	ds_read_b128 v[176:179], v122 offset:8704
	ds_read_b128 v[180:183], v121 offset:8512
	ds_read_b128 v[184:187], v122 offset:320
	s_waitcnt lgkmcnt(3)
	v_mfma_f32_16x16x32_bf16 v[156:159], v[168:171], v[172:175], v[156:159]
	ds_read_b128 v[172:175], v122 offset:17152
	ds_read_b128 v[188:191], v122 offset:8768
	s_waitcnt lgkmcnt(4)
	v_mfma_f32_16x16x32_bf16 v[160:163], v[168:171], v[176:179], v[160:163]
	ds_read_b128 v[176:179], v122 offset:25600
	ds_read_b128 v[192:195], v122 offset:17216
	s_waitcnt lgkmcnt(3)
	v_mfma_f32_16x16x32_bf16 v[164:167], v[168:171], v[172:175], v[164:167]
	ds_read2_b64 v[172:175], v101 offset1:2
	ds_read2_b64 v[196:199], v150 offset1:2
	ds_read_b128 v[200:203], v122 offset:25664
	v_add_u32_e32 v101, 0xa000, v135
	s_waitcnt lgkmcnt(2)
	global_store_dwordx4 v102, v[172:175], s[60:61]
	v_mfma_f32_16x16x32_bf16 v[116:119], v[168:171], v[176:179], v[116:119]
	ds_read2_b64 v[168:171], v151 offset1:2
	s_waitcnt lgkmcnt(2)
	global_store_dwordx4 v140, v[196:199], s[60:61]
	s_waitcnt lgkmcnt(0)
; DI void phase_prep(const Params& p, int j, unsigned char* lds) {
;     ...
;             bf16_t* QTp = (bf16_t*)(p.ws + WS_U) + (size_t)(item * 2) * 16384;
; #pragma unroll
;             for (int it = 0; it < 8; ++it) {
;                 const int idx = it * 512 + tid; const int d2 = idx >> 11, f = (idx >> 6) & 31, ln = idx & 63;
;                 const int w8 = f >> 2, mb = (f >> 1) & 1, s = f & 1, rr = ln & 31, hh = ln >> 5;
;                 const bf16_t* sp = qt + (d2 * 64 + 32 * mb + rr) * 264 + 32 * w8 + 16 * s + 4 * hh;
;                 const u32x2 lo = *(const u32x2*)sp, hi = *(const u32x2*)(sp + 8);
;                 u32x4 o; o.x = lo.x; o.y = lo.y; o.z = hi.x; o.w = hi.y;
;                 *(u32x4*)(QTp + (size_t)d2 * 16384 + (f * 64 + ln) * 8) = o;
;             }
;         }
;         float amask[4][4];
;         {
;             const int d2 = wave >> 2, wd = wave & 3, fr = lane & 15, fq = lane >> 4;
;             f32x4 acc[4];
; #pragma unroll
;             for (int nb = 0; nb < 4; ++nb) acc[nb] = (f32x4){0.f, 0.f, 0.f, 0.f};
;             const bf16_t* qb = qt + (d2 * 64 + 16 * wd + fr) * 264 + 8 * fq;
;             const bf16_t* kb = kt + (d2 * 64 + fr) * 264 + 8 * fq;
; #pragma unroll
;             for (int ks = 0; ks < 8; ++ks) {
;                 const bf16x8 a = *(const bf16x8*)(qb + 32 * ks);
; #pragma unroll
;                 for (int nb = 0; nb < 4; ++nb) { const bf16x8 b = *(const bf16x8*)(kb + nb * 16 * 264 + 32 * ks); acc[nb] = __builtin_amdgcn_mfma_f32_16x16x32_bf16(a, b, acc[nb], 0, 0, 0); }
;             }
; #pragma unroll
;             for (int nb = 0; nb < 4; ++nb)
; #pragma unroll
;                 for (int jx = 0; jx < 4; ++jx) {
;                     const int i = 16 * wd + 4 * fq + jx, jt = 16 * nb + fr;
;                     const bool keep = d2 ? (jt >= i) : (jt <= i);
;                     amask[nb][jx] = keep ? acc[nb][jx] : 0.f;
;                 }
;         }
;         __syncthreads();
	global_store_dwordx4 v141, v[168:171], s[60:61]
	ds_read_b128 v[172:175], v121 offset:8576
	ds_read2_b64 v[168:171], v152 offset1:2
	v_lshl_add_u64 v[176:177], s[60:61], 0, v[104:105]
	v_mfma_f32_16x16x32_bf16 v[164:167], v[180:183], v[192:195], v[164:167]
	v_lshl_add_u64 v[192:193], v[176:177], 0, v[106:107]
	ds_read_b128 v[176:179], v122 offset:384
	v_mfma_f32_16x16x32_bf16 v[156:159], v[180:183], v[184:187], v[156:159]
	v_mfma_f32_16x16x32_bf16 v[160:163], v[180:183], v[188:191], v[160:163]
	v_mfma_f32_16x16x32_bf16 v[116:119], v[180:183], v[200:203], v[116:119]
	ds_read_b128 v[180:183], v122 offset:8832
	ds_read_b128 v[184:187], v121 offset:8640
	ds_read_b128 v[188:191], v122 offset:448
	s_waitcnt lgkmcnt(4)
	global_store_dwordx4 v[192:193], v[168:171], off
	s_waitcnt lgkmcnt(3)
	v_mfma_f32_16x16x32_bf16 v[156:159], v[172:175], v[176:179], v[156:159]
	ds_read_b128 v[168:171], v122 offset:17280
	ds_read_b128 v[176:179], v122 offset:8896
	s_waitcnt lgkmcnt(4)
	v_mfma_f32_16x16x32_bf16 v[160:163], v[172:175], v[180:183], v[160:163]
	ds_read_b128 v[180:183], v122 offset:25728
	ds_read_b128 v[192:195], v122 offset:17344
	ds_read_b128 v[196:199], v122 offset:25792
	s_waitcnt lgkmcnt(4)
	v_mfma_f32_16x16x32_bf16 v[164:167], v[172:175], v[168:171], v[164:167]
	ds_read2_b64 v[168:171], v101 offset0:128 offset1:130
	s_waitcnt lgkmcnt(3)
	v_mfma_f32_16x16x32_bf16 v[116:119], v[172:175], v[180:183], v[116:119]
	ds_read2_b64 v[172:175], v153 offset0:128 offset1:130
	ds_read2_b64 v[180:183], v154 offset0:128 offset1:130
	s_waitcnt lgkmcnt(2)
	global_store_dwordx4 v102, v[168:171], s[82:83]
	s_waitcnt lgkmcnt(1)
	global_store_dwordx4 v142, v[172:175], s[82:83]
	s_waitcnt lgkmcnt(0)
	global_store_dwordx4 v143, v[180:183], s[82:83]
	v_mfma_f32_16x16x32_bf16 v[156:159], v[184:187], v[188:191], v[156:159]
	ds_read2_b64 v[168:171], v155 offset1:2
	v_lshl_add_u64 v[172:173], s[60:61], 0, v[108:109]
	v_lshl_add_u64 v[172:173], v[172:173], 0, v[110:111]
	v_mfma_f32_16x16x32_bf16 v[160:163], v[184:187], v[176:179], v[160:163]
	s_waitcnt lgkmcnt(0)
	global_store_dwordx4 v[172:173], v[168:171], off
	s_nop 1
	v_cvt_pk_bf16_f32 v101, v156, s0
	v_mfma_f32_16x16x32_bf16 v[164:167], v[184:187], v[192:195], v[164:167]
	v_cvt_pk_bf16_f32 v105, v157, s0
	v_cvt_pk_bf16_f32 v107, v158, s0
	v_cvt_pk_bf16_f32 v109, v159, s0
	v_mfma_f32_16x16x32_bf16 v[116:119], v[184:187], v[196:199], v[116:119]
	v_cvt_pk_bf16_f32 v111, v160, s0
	v_cvt_pk_bf16_f32 v112, v161, s0
	v_cvt_pk_bf16_f32 v156, v162, s0
	v_cvt_pk_bf16_f32 v157, v163, s0
	v_cvt_pk_bf16_f32 v158, v164, s0
	v_cvt_pk_bf16_f32 v159, v165, s0
	v_cvt_pk_bf16_f32 v160, v166, s0
	v_cvt_pk_bf16_f32 v161, v167, s0
	v_cvt_pk_bf16_f32 v116, v116, s0
	v_cvt_pk_bf16_f32 v117, v117, s0
	v_cvt_pk_bf16_f32 v118, v118, s0
	v_cvt_pk_bf16_f32 v119, v119, s0
	v_cndmask_b32_e64 v101, 0, v101, s[6:7]
	v_cndmask_b32_e64 v105, 0, v105, s[8:9]
	v_cndmask_b32_e64 v107, 0, v107, s[10:11]
	v_cndmask_b32_e64 v109, 0, v109, s[12:13]
	v_cndmask_b32_e64 v111, 0, v111, s[14:15]
	v_cndmask_b32_e64 v112, 0, v112, s[16:17]
	v_cndmask_b32_e64 v156, 0, v156, s[18:19]
	v_cndmask_b32_e64 v157, 0, v157, s[20:21]
	v_cndmask_b32_e64 v158, 0, v158, s[22:23]
	v_cndmask_b32_e64 v159, 0, v159, s[24:25]
	v_cndmask_b32_e64 v160, 0, v160, s[26:27]
	v_cndmask_b32_e64 v161, 0, v161, s[28:29]
	v_cndmask_b32_e64 v116, 0, v116, s[30:31]
	v_cndmask_b32_e64 v117, 0, v117, s[34:35]
	v_cndmask_b32_e64 v118, 0, v118, s[36:37]
	v_cndmask_b32_e64 v119, 0, v119, s[38:39]
	s_barrier
; DI bf16_t f2bf(float f) { return (bf16_t)(pk2(f, 0.f) & 0xffffu); }
; DI void phase_prep(const Params& p, int j, unsigned char* lds) {
;     ...
;         {
; #pragma unroll
;             for (int it = 0; it < 4; ++it) { const int idx = it * 512 + tid; const int t = idx >> 5, seg = idx & 31; *(u32x4*)(qt + t * 264 + seg * 8) = vcur[it]; }
;         }
;         {
;             const int d2 = wave >> 2, wd = wave & 3, fr = lane & 15, fq = lane >> 4;
; #pragma unroll
;             for (int nb = 0; nb < 4; ++nb)
; #pragma unroll
;                 for (int jx = 0; jx < 4; ++jx) {
;                     const int i = 16 * wd + 4 * fq + jx, jt = 16 * nb + fr;
;                     const int mb = i >> 5, r = i & 31, hh = (jt >> 3) & 1, jj = jt & 7;
;                     kt[d2 * 4096 + ((nb * 2 + mb) * 64 + hh * 32 + r) * 8 + jj] = f2bf(amask[nb][jx]);
;                 }
;         }
;         __syncthreads();
;         {
;             bf16_t* AMp = (bf16_t*)(p.ws + WS_AM) + (size_t)(item * 2) * 4096;
;             *(u32x4*)(AMp + tid * 8) = *(const u32x4*)(kt + tid * 8);
;             *(u32x4*)(AMp + 4096 + tid * 8) = *(const u32x4*)(kt + 4096 + tid * 8);
;         }
;         {
;             bf16_t* VTp = (bf16_t*)(p.ws + WS_VT) + (size_t)item * 16384;
; #pragma unroll
;             for (int it = 0; it < 4; ++it) {
;                 const int idx = it * 512 + tid; const int f = idx >> 6, ln = idx & 63; const int sl = f >> 2, s = f & 3, rr = ln & 31, hh = ln >> 5;
;                 const bf16_t* sp = qt + (16 * s + 8 * hh) * 264 + 32 * sl + rr;
;                 unsigned e[8];
; #pragma unroll
;                 for (int jj = 0; jj < 8; ++jj) e[jj] = sp[jj * 264];
;                 u32x4 o; o.x = e[0] | (e[1] << 16); o.y = e[2] | (e[3] << 16); o.z = e[4] | (e[5] << 16); o.w = e[6] | (e[7] << 16);
;                 *(u32x4*)(VTp + (f * 64 + ln) * 8) = o;
;             }
;         }
;         __syncthreads();
	ds_write_b128 v144, v[2:5] offset:8192
	ds_write_b128 v145, v[6:9] offset:8192
	ds_write_b128 v146, v[10:13] offset:8192
	ds_write_b128 v147, v[14:17] offset:8192
	ds_write_b16 v148, v101
	ds_write_b16 v148, v105 offset:16
	ds_write_b16 v148, v107 offset:32
	ds_write_b16 v148, v109 offset:48
	ds_write_b16 v148, v111 offset:2048
	ds_write_b16 v148, v112 offset:2064
	ds_write_b16 v148, v156 offset:2080
	ds_write_b16 v148, v157 offset:2096
	ds_write_b16 v148, v158 offset:4096
	ds_write_b16 v148, v159 offset:4112
	ds_write_b16 v148, v160 offset:4128
	ds_write_b16 v148, v161 offset:4144
	ds_write_b16 v148, v116 offset:6144
	ds_write_b16 v148, v117 offset:6160
	ds_write_b16 v148, v118 offset:6176
	ds_write_b16 v148, v119 offset:6192
	s_waitcnt lgkmcnt(0)
	s_barrier
	ds_read_b128 v[2:5], v124
	ds_read_b128 v[6:9], v125
	v_lshl_add_u64 v[10:11], s[58:59], 0, v[102:103]
	s_waitcnt vmcnt(16)
	v_mov_b64_e32 v[14:15], v[62:63]
	v_mov_b64_e32 v[16:17], v[64:65]
	s_waitcnt lgkmcnt(1)
	global_store_dwordx4 v102, v[2:5], s[58:59]
	s_nop 1
	v_add_co_u32_e32 v2, vcc, s64, v10
	s_nop 1
	v_addc_co_u32_e32 v3, vcc, 0, v11, vcc
	s_waitcnt lgkmcnt(0)
	global_store_dwordx4 v[2:3], v[6:9], off
	ds_read_u16 v2, v136 offset:8192
	ds_read_u16 v3, v136 offset:8720
	ds_read_u16 v4, v136 offset:9248
	ds_read_u16 v5, v136 offset:9776
	ds_read_u16 v6, v136 offset:10304
	ds_read_u16 v7, v136 offset:10832
	ds_read_u16 v8, v136 offset:11360
	ds_read_u16 v9, v136 offset:11888
	s_waitcnt lgkmcnt(6)
	v_lshl_or_b32 v2, v3, 16, v2
	s_waitcnt lgkmcnt(4)
	v_lshl_or_b32 v3, v5, 16, v4
	s_waitcnt lgkmcnt(2)
	v_lshl_or_b32 v4, v7, 16, v6
	s_and_b64 vcc, s[56:57], exec
	s_waitcnt lgkmcnt(0)
	v_lshl_or_b32 v5, v9, 16, v8
	ds_read_u16 v6, v137 offset:8192
	ds_read_u16 v7, v137 offset:8720
	ds_read_u16 v8, v137 offset:9248
	ds_read_u16 v9, v137 offset:9776
	ds_read_u16 v10, v137 offset:10304
	ds_read_u16 v11, v137 offset:10832
	ds_read_u16 v12, v137 offset:11360
	ds_read_u16 v13, v137 offset:11888
	global_store_dwordx4 v102, v[2:5], s[54:55]
	s_waitcnt lgkmcnt(6)
	s_nop 0
	v_lshl_or_b32 v2, v7, 16, v6
	s_waitcnt lgkmcnt(4)
	v_lshl_or_b32 v3, v9, 16, v8
	s_waitcnt lgkmcnt(2)
	v_lshl_or_b32 v4, v11, 16, v10
	s_waitcnt lgkmcnt(0)
	v_lshl_or_b32 v5, v13, 16, v12
	ds_read_u16 v6, v138 offset:8192
	ds_read_u16 v7, v138 offset:8720
	ds_read_u16 v8, v138 offset:9248
	ds_read_u16 v9, v138 offset:9776
	ds_read_u16 v10, v138 offset:10304
	ds_read_u16 v11, v138 offset:10832
	ds_read_u16 v12, v138 offset:11360
	ds_read_u16 v13, v138 offset:11888
	global_store_dwordx4 v140, v[2:5], s[54:55]
	s_waitcnt lgkmcnt(6)
	s_nop 0
	v_lshl_or_b32 v2, v7, 16, v6
	s_waitcnt lgkmcnt(4)
	v_lshl_or_b32 v3, v9, 16, v8
	s_waitcnt lgkmcnt(2)
	v_lshl_or_b32 v4, v11, 16, v10
	s_waitcnt lgkmcnt(0)
	v_lshl_or_b32 v5, v13, 16, v12
	ds_read_u16 v6, v139 offset:8192
	ds_read_u16 v7, v139 offset:8720
	ds_read_u16 v8, v139 offset:9248
	ds_read_u16 v9, v139 offset:9776
	ds_read_u16 v10, v139 offset:10304
	ds_read_u16 v11, v139 offset:10832
	ds_read_u16 v12, v139 offset:11360
	ds_read_u16 v13, v139 offset:11888
	global_store_dwordx4 v141, v[2:5], s[54:55]
	s_waitcnt lgkmcnt(6)
	s_nop 0
	v_lshl_or_b32 v2, v7, 16, v6
	s_waitcnt lgkmcnt(4)
	v_lshl_or_b32 v3, v9, 16, v8
	s_waitcnt lgkmcnt(2)
	v_lshl_or_b32 v4, v11, 16, v10
	s_waitcnt lgkmcnt(0)
	v_lshl_or_b32 v5, v13, 16, v12
	global_store_dwordx4 v149, v[2:5], s[54:55]
	v_mov_b64_e32 v[6:7], v[54:55]
	v_mov_b64_e32 v[10:11], v[58:59]
	v_mov_b64_e32 v[2:3], v[50:51]
	v_mov_b64_e32 v[4:5], v[52:53]
	v_mov_b64_e32 v[8:9], v[56:57]
	v_mov_b64_e32 v[12:13], v[60:61]
	s_mov_b32 s54, s81
	s_barrier
	s_cbranch_vccz .LBB0_361

; template <int DIR>
; DI float prep_gate_loop(const float* r_s, bf16_t* qt, bf16_t* kt, const float (&w)[16], float bias, int kk) {
;     ...
;         for (int i = 0; i < 16; ++i) {
;             const int tt = blk * 16 + i; const int t = DIR ? 63 - tt : tt;
;             const f32x4* rr = (const f32x4*)(r_s + t * 32 + DIR * 16);
;             const f32x4 r0 = rr[0], r1 = rr[1], r2 = rr[2], r3 = rr[3];
;             float s0 = __builtin_fmaf(r0[0], w[0], bias), s1 = r0[1] * w[1], s2 = r0[2] * w[2], s3 = r0[3] * w[3];
;             s0 = __builtin_fmaf(r1[0], w[4], s0); s1 = __builtin_fmaf(r1[1], w[5], s1); s2 = __builtin_fmaf(r1[2], w[6], s2); s3 = __builtin_fmaf(r1[3], w[7], s3);
;             s0 = __builtin_fmaf(r2[0], w[8], s0); s1 = __builtin_fmaf(r2[1], w[9], s1); s2 = __builtin_fmaf(r2[2], w[10], s2); s3 = __builtin_fmaf(r2[3], w[11], s3);
;             s0 = __builtin_fmaf(r3[0], w[12], s0); s1 = __builtin_fmaf(r3[1], w[13], s1); s2 = __builtin_fmaf(r3[2], w[14], s2); s3 = __builtin_fmaf(r3[3], w[15], s3);
;             const float pre = (s0 + s1) + (s2 + s3);
;             const float ex = __builtin_amdgcn_exp2f(-fabsf(pre) * LOG2E);
;             la[i] = (fminf(pre, 0.f) * LOG2E - __builtin_amdgcn_logf(1.f + ex)) * 0.0625f;
;         }
.LBB0_356:
	v_mov_b32_e32 v32, s55
	ds_read_b128 v[18:21], v32 offset:1920
	ds_read_b128 v[22:25], v32 offset:1936
	ds_read_b128 v[26:29], v32 offset:1952
	ds_read_b128 v[34:37], v32 offset:1968
	s_addk_i32 s55, 0xf800
	s_waitcnt lgkmcnt(3)
	v_fma_f32 v18, v18, v85, v123
	v_mul_f32_e32 v19, v76, v19
	v_mul_f32_e32 v20, v83, v20
	v_mul_f32_e32 v21, v77, v21
	s_waitcnt lgkmcnt(2)
	v_fmac_f32_e32 v18, v22, v74
	v_fmac_f32_e32 v19, v23, v78
	v_fmac_f32_e32 v20, v24, v75
	v_fmac_f32_e32 v21, v25, v79
	s_waitcnt lgkmcnt(1)
	v_fmac_f32_e32 v18, v26, v80
	v_fmac_f32_e32 v19, v27, v90
	v_fmac_f32_e32 v20, v28, v81
	v_fmac_f32_e32 v21, v29, v91
	s_waitcnt lgkmcnt(0)
	v_fmac_f32_e32 v18, v34, v88
	v_fmac_f32_e32 v19, v35, v92
	v_fmac_f32_e32 v20, v36, v89
	v_fmac_f32_e32 v21, v37, v93
	v_add_f32_e32 v18, v18, v19
	v_add_f32_e32 v19, v20, v21
	v_add_f32_e32 v18, v18, v19
	v_mul_f32_e64 v19, |v18|, s79
	v_exp_f32_e32 v19, v19
	v_min_f32_e32 v18, 0, v18
	v_add_f32_e32 v19, 1.0, v19
	v_log_f32_e32 v19, v19
	s_nop 0
	v_fma_f32 v38, v18, s80, -v19
	ds_read_b128 v[18:21], v32 offset:1792
	ds_read_b128 v[22:25], v32 offset:1808
	ds_read_b128 v[26:29], v32 offset:1824
	ds_read_b128 v[34:37], v32 offset:1840
	v_fmac_f32_e32 v33, 0x3d800000, v38
	s_waitcnt lgkmcnt(3)
	v_fma_f32 v18, v18, v85, v123
	v_mul_f32_e32 v19, v76, v19
	v_mul_f32_e32 v20, v83, v20
	v_mul_f32_e32 v21, v77, v21
	s_waitcnt lgkmcnt(2)
	v_fmac_f32_e32 v18, v22, v74
	v_fmac_f32_e32 v19, v23, v78
	v_fmac_f32_e32 v20, v24, v75
	v_fmac_f32_e32 v21, v25, v79
	s_waitcnt lgkmcnt(1)
	v_fmac_f32_e32 v18, v26, v80
	v_fmac_f32_e32 v19, v27, v90
	v_fmac_f32_e32 v20, v28, v81
	v_fmac_f32_e32 v21, v29, v91
	s_waitcnt lgkmcnt(0)
	v_fmac_f32_e32 v18, v34, v88
	v_fmac_f32_e32 v19, v35, v92
	v_fmac_f32_e32 v20, v36, v89
	v_fmac_f32_e32 v21, v37, v93
	v_add_f32_e32 v18, v18, v19
	v_add_f32_e32 v19, v20, v21
	v_add_f32_e32 v18, v18, v19
	v_mul_f32_e64 v19, |v18|, s79
	v_exp_f32_e32 v19, v19
	v_min_f32_e32 v18, 0, v18
	v_add_f32_e32 v19, 1.0, v19
	v_log_f32_e32 v19, v19
	s_nop 0
	v_fma_f32 v39, v18, s80, -v19
	ds_read_b128 v[18:21], v32 offset:1664
	ds_read_b128 v[22:25], v32 offset:1680
	ds_read_b128 v[26:29], v32 offset:1696
	ds_read_b128 v[34:37], v32 offset:1712
	s_waitcnt lgkmcnt(3)
	v_fma_f32 v18, v18, v85, v123
	v_mul_f32_e32 v19, v76, v19
	v_mul_f32_e32 v20, v83, v20
	v_mul_f32_e32 v21, v77, v21
	s_waitcnt lgkmcnt(2)
	v_fmac_f32_e32 v18, v22, v74
	v_fmac_f32_e32 v19, v23, v78
	v_fmac_f32_e32 v20, v24, v75
	v_fmac_f32_e32 v21, v25, v79
	s_waitcnt lgkmcnt(1)
	v_fmac_f32_e32 v18, v26, v80
	v_fmac_f32_e32 v19, v27, v90
	v_fmac_f32_e32 v20, v28, v81
	v_fmac_f32_e32 v21, v29, v91
	s_waitcnt lgkmcnt(0)
	v_fmac_f32_e32 v18, v34, v88
	v_fmac_f32_e32 v19, v35, v92
	v_fmac_f32_e32 v20, v36, v89
	v_fmac_f32_e32 v21, v37, v93
	v_add_f32_e32 v18, v18, v19
	v_add_f32_e32 v19, v20, v21
	v_add_f32_e32 v18, v18, v19
	v_mul_f32_e64 v19, |v18|, s79
	v_exp_f32_e32 v19, v19
	v_min_f32_e32 v18, 0, v18
	v_add_f32_e32 v19, 1.0, v19
	v_log_f32_e32 v19, v19
	s_nop 0
	v_fma_f32 v40, v18, s80, -v19
	ds_read_b128 v[18:21], v32 offset:1536
	ds_read_b128 v[22:25], v32 offset:1552
	ds_read_b128 v[26:29], v32 offset:1568
	ds_read_b128 v[34:37], v32 offset:1584
	s_waitcnt lgkmcnt(3)
	v_fma_f32 v18, v18, v85, v123
	v_mul_f32_e32 v19, v76, v19
	v_mul_f32_e32 v20, v83, v20
	v_mul_f32_e32 v21, v77, v21
	s_waitcnt lgkmcnt(2)
	v_fmac_f32_e32 v18, v22, v74
	v_fmac_f32_e32 v19, v23, v78
	v_fmac_f32_e32 v20, v24, v75
	v_fmac_f32_e32 v21, v25, v79
	s_waitcnt lgkmcnt(1)
	v_fmac_f32_e32 v18, v26, v80
	v_fmac_f32_e32 v19, v27, v90
	v_fmac_f32_e32 v20, v28, v81
	v_fmac_f32_e32 v21, v29, v91
	s_waitcnt lgkmcnt(0)
	v_fmac_f32_e32 v18, v34, v88
	v_fmac_f32_e32 v19, v35, v92
	v_fmac_f32_e32 v20, v36, v89
	v_fmac_f32_e32 v21, v37, v93
	v_add_f32_e32 v18, v18, v19
	v_add_f32_e32 v19, v20, v21
	v_add_f32_e32 v18, v18, v19
	v_mul_f32_e64 v19, |v18|, s79
	v_exp_f32_e32 v19, v19
	v_min_f32_e32 v18, 0, v18
	v_add_f32_e32 v19, 1.0, v19
	v_log_f32_e32 v19, v19
	s_nop 0
	v_fma_f32 v41, v18, s80, -v19
	ds_read_b128 v[18:21], v32 offset:1408
	ds_read_b128 v[22:25], v32 offset:1424
	ds_read_b128 v[26:29], v32 offset:1440
	ds_read_b128 v[34:37], v32 offset:1456
	s_waitcnt lgkmcnt(3)
	v_fma_f32 v18, v18, v85, v123
	v_mul_f32_e32 v19, v76, v19
	v_mul_f32_e32 v20, v83, v20
	v_mul_f32_e32 v21, v77, v21
	s_waitcnt lgkmcnt(2)
	v_fmac_f32_e32 v18, v22, v74
	v_fmac_f32_e32 v19, v23, v78
	v_fmac_f32_e32 v20, v24, v75
	v_fmac_f32_e32 v21, v25, v79
	s_waitcnt lgkmcnt(1)
	v_fmac_f32_e32 v18, v26, v80
	v_fmac_f32_e32 v19, v27, v90
	v_fmac_f32_e32 v20, v28, v81
	v_fmac_f32_e32 v21, v29, v91
	s_waitcnt lgkmcnt(0)
	v_fmac_f32_e32 v18, v34, v88
	v_fmac_f32_e32 v19, v35, v92
	v_fmac_f32_e32 v20, v36, v89
	v_fmac_f32_e32 v21, v37, v93
	v_add_f32_e32 v18, v18, v19
	v_add_f32_e32 v19, v20, v21
	v_add_f32_e32 v18, v18, v19
	v_mul_f32_e64 v19, |v18|, s79
	v_exp_f32_e32 v19, v19
	v_min_f32_e32 v18, 0, v18
	v_add_f32_e32 v19, 1.0, v19
	v_log_f32_e32 v19, v19
	s_nop 0
	v_fma_f32 v42, v18, s80, -v19
	ds_read_b128 v[18:21], v32 offset:1280
	ds_read_b128 v[22:25], v32 offset:1296
	ds_read_b128 v[26:29], v32 offset:1312
	ds_read_b128 v[34:37], v32 offset:1328
	s_waitcnt lgkmcnt(3)
	v_fma_f32 v18, v18, v85, v123
	v_mul_f32_e32 v19, v76, v19
	v_mul_f32_e32 v20, v83, v20
	v_mul_f32_e32 v21, v77, v21
	s_waitcnt lgkmcnt(2)
	v_fmac_f32_e32 v18, v22, v74
	v_fmac_f32_e32 v19, v23, v78
	v_fmac_f32_e32 v20, v24, v75
	v_fmac_f32_e32 v21, v25, v79
	s_waitcnt lgkmcnt(1)
	v_fmac_f32_e32 v18, v26, v80
	v_fmac_f32_e32 v19, v27, v90
	v_fmac_f32_e32 v20, v28, v81
	v_fmac_f32_e32 v21, v29, v91
	s_waitcnt lgkmcnt(0)
; template <int DIR>
; DI float prep_gate_loop(const float* r_s, bf16_t* qt, bf16_t* kt, const float (&w)[16], float bias, int kk) {
;     ...
;         for (int i = 0; i < 16; ++i) {
;             const int tt = blk * 16 + i; const int t = DIR ? 63 - tt : tt;
;             const f32x4* rr = (const f32x4*)(r_s + t * 32 + DIR * 16);
;             const f32x4 r0 = rr[0], r1 = rr[1], r2 = rr[2], r3 = rr[3];
;             float s0 = __builtin_fmaf(r0[0], w[0], bias), s1 = r0[1] * w[1], s2 = r0[2] * w[2], s3 = r0[3] * w[3];
;             s0 = __builtin_fmaf(r1[0], w[4], s0); s1 = __builtin_fmaf(r1[1], w[5], s1); s2 = __builtin_fmaf(r1[2], w[6], s2); s3 = __builtin_fmaf(r1[3], w[7], s3);
;             s0 = __builtin_fmaf(r2[0], w[8], s0); s1 = __builtin_fmaf(r2[1], w[9], s1); s2 = __builtin_fmaf(r2[2], w[10], s2); s3 = __builtin_fmaf(r2[3], w[11], s3);
;             s0 = __builtin_fmaf(r3[0], w[12], s0); s1 = __builtin_fmaf(r3[1], w[13], s1); s2 = __builtin_fmaf(r3[2], w[14], s2); s3 = __builtin_fmaf(r3[3], w[15], s3);
;             const float pre = (s0 + s1) + (s2 + s3);
;             const float ex = __builtin_amdgcn_exp2f(-fabsf(pre) * LOG2E);
;             la[i] = (fminf(pre, 0.f) * LOG2E - __builtin_amdgcn_logf(1.f + ex)) * 0.0625f;
;         }
	v_fmac_f32_e32 v18, v34, v88
	v_fmac_f32_e32 v19, v35, v92
	v_fmac_f32_e32 v20, v36, v89
	v_fmac_f32_e32 v21, v37, v93
	v_add_f32_e32 v18, v18, v19
	v_add_f32_e32 v19, v20, v21
	v_add_f32_e32 v18, v18, v19
	v_mul_f32_e64 v19, |v18|, s79
	v_exp_f32_e32 v19, v19
	v_min_f32_e32 v18, 0, v18
	v_add_f32_e32 v19, 1.0, v19
	v_log_f32_e32 v19, v19
	s_nop 0
	v_fma_f32 v43, v18, s80, -v19
	ds_read_b128 v[18:21], v32 offset:1152
	ds_read_b128 v[22:25], v32 offset:1168
	ds_read_b128 v[26:29], v32 offset:1184
	ds_read_b128 v[34:37], v32 offset:1200
	s_waitcnt lgkmcnt(3)
	v_fma_f32 v18, v18, v85, v123
	v_mul_f32_e32 v19, v76, v19
	v_mul_f32_e32 v20, v83, v20
	v_mul_f32_e32 v21, v77, v21
	s_waitcnt lgkmcnt(2)
	v_fmac_f32_e32 v18, v22, v74
	v_fmac_f32_e32 v19, v23, v78
	v_fmac_f32_e32 v20, v24, v75
	v_fmac_f32_e32 v21, v25, v79
	s_waitcnt lgkmcnt(1)
	v_fmac_f32_e32 v18, v26, v80
	v_fmac_f32_e32 v19, v27, v90
	v_fmac_f32_e32 v20, v28, v81
	v_fmac_f32_e32 v21, v29, v91
	s_waitcnt lgkmcnt(0)
	v_fmac_f32_e32 v18, v34, v88
	v_fmac_f32_e32 v19, v35, v92
	v_fmac_f32_e32 v20, v36, v89
	v_fmac_f32_e32 v21, v37, v93
	v_add_f32_e32 v18, v18, v19
	v_add_f32_e32 v19, v20, v21
	v_add_f32_e32 v18, v18, v19
	v_mul_f32_e64 v19, |v18|, s79
	v_exp_f32_e32 v19, v19
	v_min_f32_e32 v18, 0, v18
	v_add_f32_e32 v19, 1.0, v19
	v_log_f32_e32 v19, v19
	s_nop 0
	v_fma_f32 v44, v18, s80, -v19
	ds_read_b128 v[18:21], v32 offset:1024
	ds_read_b128 v[22:25], v32 offset:1040
	ds_read_b128 v[26:29], v32 offset:1056
	ds_read_b128 v[34:37], v32 offset:1072
	s_waitcnt lgkmcnt(3)
	v_fma_f32 v18, v18, v85, v123
	v_mul_f32_e32 v19, v76, v19
	v_mul_f32_e32 v20, v83, v20
	v_mul_f32_e32 v21, v77, v21
	s_waitcnt lgkmcnt(2)
	v_fmac_f32_e32 v18, v22, v74
	v_fmac_f32_e32 v19, v23, v78
	v_fmac_f32_e32 v20, v24, v75
	v_fmac_f32_e32 v21, v25, v79
	s_waitcnt lgkmcnt(1)
	v_fmac_f32_e32 v18, v26, v80
	v_fmac_f32_e32 v19, v27, v90
	v_fmac_f32_e32 v20, v28, v81
	v_fmac_f32_e32 v21, v29, v91
	s_waitcnt lgkmcnt(0)
	v_fmac_f32_e32 v18, v34, v88
	v_fmac_f32_e32 v19, v35, v92
	v_fmac_f32_e32 v20, v36, v89
	v_fmac_f32_e32 v21, v37, v93
	v_add_f32_e32 v18, v18, v19
	v_add_f32_e32 v19, v20, v21
	v_add_f32_e32 v18, v18, v19
	v_mul_f32_e64 v19, |v18|, s79
	v_exp_f32_e32 v19, v19
	v_min_f32_e32 v18, 0, v18
	v_add_f32_e32 v19, 1.0, v19
	v_log_f32_e32 v19, v19
	s_nop 0
	v_fma_f32 v45, v18, s80, -v19
	ds_read_b128 v[18:21], v32 offset:896
	ds_read_b128 v[22:25], v32 offset:912
	ds_read_b128 v[26:29], v32 offset:928
	ds_read_b128 v[34:37], v32 offset:944
	s_waitcnt lgkmcnt(3)
	v_fma_f32 v18, v18, v85, v123
	v_mul_f32_e32 v19, v76, v19
	v_mul_f32_e32 v20, v83, v20
	v_mul_f32_e32 v21, v77, v21
	s_waitcnt lgkmcnt(2)
	v_fmac_f32_e32 v18, v22, v74
	v_fmac_f32_e32 v19, v23, v78
	v_fmac_f32_e32 v20, v24, v75
	v_fmac_f32_e32 v21, v25, v79
	s_waitcnt lgkmcnt(1)
	v_fmac_f32_e32 v18, v26, v80
	v_fmac_f32_e32 v19, v27, v90
	v_fmac_f32_e32 v20, v28, v81
	v_fmac_f32_e32 v21, v29, v91
	s_waitcnt lgkmcnt(0)
	v_fmac_f32_e32 v18, v34, v88
	v_fmac_f32_e32 v19, v35, v92
	v_fmac_f32_e32 v20, v36, v89
	v_fmac_f32_e32 v21, v37, v93
	v_add_f32_e32 v18, v18, v19
	v_add_f32_e32 v19, v20, v21
	v_add_f32_e32 v18, v18, v19
	v_mul_f32_e64 v19, |v18|, s79
	v_exp_f32_e32 v19, v19
	v_min_f32_e32 v18, 0, v18
	v_add_f32_e32 v19, 1.0, v19
	v_log_f32_e32 v19, v19
	s_nop 0
	v_fma_f32 v46, v18, s80, -v19
	ds_read_b128 v[18:21], v32 offset:768
	ds_read_b128 v[22:25], v32 offset:784
	ds_read_b128 v[26:29], v32 offset:800
	ds_read_b128 v[34:37], v32 offset:816
	s_waitcnt lgkmcnt(3)
	v_mul_f32_e32 v31, v83, v20
	v_mov_b32_e32 v20, v19
	v_fma_f32 v30, v18, v85, v123
	v_mul_f32_e64 v18, v76, v20
	v_mul_f32_e64 v19, v77, v21
	s_waitcnt lgkmcnt(2)
	v_mov_b32_e32 v20, v22
	v_mov_b32_e32 v21, v24
	v_mov_b32_e32 v24, v23
	v_fma_f32 v20, v20, v74, v30
	v_fma_f32 v21, v21, v75, v31
	v_fma_f32 v18, v24, v78, v18
	v_fma_f32 v19, v25, v79, v19
	s_waitcnt lgkmcnt(1)
	v_mov_b32_e32 v22, v26
	v_mov_b32_e32 v23, v28
	v_mov_b32_e32 v28, v27
	v_fma_f32 v20, v22, v80, v20
	v_fma_f32 v21, v23, v81, v21
	v_fma_f32 v18, v28, v90, v18
	v_fma_f32 v19, v29, v91, v19
	s_waitcnt lgkmcnt(0)
	v_mov_b32_e32 v22, v34
	v_mov_b32_e32 v23, v36
	v_mov_b32_e32 v36, v35
	v_fma_f32 v20, v22, v88, v20
	v_fma_f32 v21, v23, v89, v21
	v_fma_f32 v18, v36, v92, v18
	v_fma_f32 v19, v37, v93, v19
	s_nop 0
	v_add_f32_e64 v18, v20, v18
	v_add_f32_e64 v19, v21, v19
	s_nop 0
	v_add_f32_e32 v18, v18, v19
	v_mul_f32_e64 v19, |v18|, s79
	v_exp_f32_e32 v19, v19
	v_min_f32_e32 v18, 0, v18
	v_add_f32_e32 v19, 1.0, v19
	v_log_f32_e32 v19, v19
	s_nop 0
	v_fma_f32 v47, v18, s80, -v19
	ds_read_b128 v[18:21], v32 offset:640
	ds_read_b128 v[22:25], v32 offset:656
	ds_read_b128 v[26:29], v32 offset:672
	ds_read_b128 v[34:37], v32 offset:688
	s_waitcnt lgkmcnt(3)
	v_mul_f32_e32 v31, v83, v20
	v_mov_b32_e32 v20, v19
	v_fma_f32 v30, v18, v85, v123
	v_mul_f32_e64 v18, v76, v20
	v_mul_f32_e64 v19, v77, v21
	s_waitcnt lgkmcnt(2)
	v_mov_b32_e32 v20, v22
	v_mov_b32_e32 v21, v24
	v_mov_b32_e32 v24, v23
	v_fma_f32 v20, v20, v74, v30
	v_fma_f32 v21, v21, v75, v31
	v_fma_f32 v18, v24, v78, v18
	v_fma_f32 v19, v25, v79, v19
	s_waitcnt lgkmcnt(1)
	v_mov_b32_e32 v22, v26
	v_mov_b32_e32 v23, v28
	v_mov_b32_e32 v28, v27
	v_fma_f32 v20, v22, v80, v20
	v_fma_f32 v21, v23, v81, v21
	v_fma_f32 v18, v28, v90, v18
	v_fma_f32 v19, v29, v91, v19
	s_waitcnt lgkmcnt(0)
; template <int DIR>
; DI float prep_gate_loop(const float* r_s, bf16_t* qt, bf16_t* kt, const float (&w)[16], float bias, int kk) {
;     ...
;         for (int i = 0; i < 16; ++i) {
;             const int tt = blk * 16 + i; const int t = DIR ? 63 - tt : tt;
;             const f32x4* rr = (const f32x4*)(r_s + t * 32 + DIR * 16);
;             const f32x4 r0 = rr[0], r1 = rr[1], r2 = rr[2], r3 = rr[3];
;             float s0 = __builtin_fmaf(r0[0], w[0], bias), s1 = r0[1] * w[1], s2 = r0[2] * w[2], s3 = r0[3] * w[3];
;             s0 = __builtin_fmaf(r1[0], w[4], s0); s1 = __builtin_fmaf(r1[1], w[5], s1); s2 = __builtin_fmaf(r1[2], w[6], s2); s3 = __builtin_fmaf(r1[3], w[7], s3);
;             s0 = __builtin_fmaf(r2[0], w[8], s0); s1 = __builtin_fmaf(r2[1], w[9], s1); s2 = __builtin_fmaf(r2[2], w[10], s2); s3 = __builtin_fmaf(r2[3], w[11], s3);
;             s0 = __builtin_fmaf(r3[0], w[12], s0); s1 = __builtin_fmaf(r3[1], w[13], s1); s2 = __builtin_fmaf(r3[2], w[14], s2); s3 = __builtin_fmaf(r3[3], w[15], s3);
;             const float pre = (s0 + s1) + (s2 + s3);
;             const float ex = __builtin_amdgcn_exp2f(-fabsf(pre) * LOG2E);
;             la[i] = (fminf(pre, 0.f) * LOG2E - __builtin_amdgcn_logf(1.f + ex)) * 0.0625f;
;         }
	v_mov_b32_e32 v22, v34
	v_mov_b32_e32 v23, v36
	v_mov_b32_e32 v36, v35
	v_fma_f32 v20, v22, v88, v20
	v_fma_f32 v21, v23, v89, v21
	v_fma_f32 v18, v36, v92, v18
	v_fma_f32 v19, v37, v93, v19
	s_nop 0
	v_add_f32_e64 v18, v20, v18
	v_add_f32_e64 v19, v21, v19
	s_nop 0
	v_add_f32_e32 v18, v18, v19
	v_mul_f32_e64 v19, |v18|, s79
	v_exp_f32_e32 v19, v19
	v_min_f32_e32 v18, 0, v18
	v_add_f32_e32 v19, 1.0, v19
	v_log_f32_e32 v19, v19
	s_nop 0
	v_fma_f32 v48, v18, s80, -v19
	ds_read_b128 v[18:21], v32 offset:512
	ds_read_b128 v[22:25], v32 offset:528
	ds_read_b128 v[26:29], v32 offset:544
	ds_read_b128 v[34:37], v32 offset:560
	s_waitcnt lgkmcnt(3)
	v_mul_f32_e32 v31, v83, v20
	v_mov_b32_e32 v20, v19
	v_fma_f32 v30, v18, v85, v123
	v_mul_f32_e64 v18, v76, v20
	v_mul_f32_e64 v19, v77, v21
	s_waitcnt lgkmcnt(2)
	v_mov_b32_e32 v20, v22
	v_mov_b32_e32 v21, v24
	v_mov_b32_e32 v24, v23
	v_fma_f32 v20, v20, v74, v30
	v_fma_f32 v21, v21, v75, v31
	v_fma_f32 v18, v24, v78, v18
	v_fma_f32 v19, v25, v79, v19
	s_waitcnt lgkmcnt(1)
	v_mov_b32_e32 v22, v26
	v_mov_b32_e32 v23, v28
	v_mov_b32_e32 v28, v27
	v_fma_f32 v20, v22, v80, v20
	v_fma_f32 v21, v23, v81, v21
	v_fma_f32 v18, v28, v90, v18
	v_fma_f32 v19, v29, v91, v19
	s_waitcnt lgkmcnt(0)
	v_mov_b32_e32 v22, v34
	v_mov_b32_e32 v23, v36
	v_mov_b32_e32 v36, v35
	v_fma_f32 v20, v22, v88, v20
	v_fma_f32 v21, v23, v89, v21
	v_fma_f32 v18, v36, v92, v18
	v_fma_f32 v19, v37, v93, v19
	s_nop 0
	v_add_f32_e64 v18, v20, v18
	v_add_f32_e64 v19, v21, v19
	s_nop 0
	v_add_f32_e32 v18, v18, v19
	v_mul_f32_e64 v19, |v18|, s79
	v_exp_f32_e32 v19, v19
	v_min_f32_e32 v18, 0, v18
	v_add_f32_e32 v19, 1.0, v19
	v_log_f32_e32 v19, v19
	s_nop 0
	v_fma_f32 v49, v18, s80, -v19
	ds_read_b128 v[18:21], v32 offset:384
	ds_read_b128 v[22:25], v32 offset:400
	ds_read_b128 v[26:29], v32 offset:416
	ds_read_b128 v[34:37], v32 offset:432
	s_waitcnt lgkmcnt(3)
	v_mul_f32_e32 v31, v83, v20
	v_mov_b32_e32 v20, v19
	v_fma_f32 v30, v18, v85, v123
	v_mul_f32_e64 v18, v76, v20
	v_mul_f32_e64 v19, v77, v21
	s_waitcnt lgkmcnt(2)
	v_mov_b32_e32 v20, v22
	v_mov_b32_e32 v21, v24
	v_mov_b32_e32 v24, v23
	v_fma_f32 v20, v20, v74, v30
	v_fma_f32 v21, v21, v75, v31
	v_fma_f32 v18, v24, v78, v18
	v_fma_f32 v19, v25, v79, v19
	s_waitcnt lgkmcnt(1)
	v_mov_b32_e32 v22, v26
	v_mov_b32_e32 v23, v28
	v_mov_b32_e32 v28, v27
	v_fma_f32 v20, v22, v80, v20
	v_fma_f32 v21, v23, v81, v21
	v_fma_f32 v18, v28, v90, v18
	v_fma_f32 v19, v29, v91, v19
	s_waitcnt lgkmcnt(0)
	v_mov_b32_e32 v22, v34
	v_mov_b32_e32 v23, v36
	v_mov_b32_e32 v36, v35
	v_fma_f32 v20, v22, v88, v20
	v_fma_f32 v21, v23, v89, v21
	v_fma_f32 v18, v36, v92, v18
	v_fma_f32 v19, v37, v93, v19
	s_nop 0
	v_add_f32_e64 v18, v20, v18
	v_add_f32_e64 v19, v21, v19
	s_nop 0
	v_add_f32_e32 v18, v18, v19
	v_mul_f32_e64 v19, |v18|, s79
	v_exp_f32_e32 v19, v19
	v_min_f32_e32 v18, 0, v18
	v_add_f32_e32 v19, 1.0, v19
	v_log_f32_e32 v19, v19
	s_nop 0
	v_fma_f32 v50, v18, s80, -v19
	ds_read_b128 v[18:21], v32 offset:256
	ds_read_b128 v[22:25], v32 offset:272
	ds_read_b128 v[26:29], v32 offset:288
	ds_read_b128 v[34:37], v32 offset:304
	s_waitcnt lgkmcnt(3)
	v_mul_f32_e32 v31, v83, v20
	v_mov_b32_e32 v20, v19
	v_fma_f32 v30, v18, v85, v123
	v_mul_f32_e64 v18, v76, v20
	v_mul_f32_e64 v19, v77, v21
	s_waitcnt lgkmcnt(2)
	v_mov_b32_e32 v20, v22
	v_mov_b32_e32 v21, v24
	v_mov_b32_e32 v24, v23
	v_fma_f32 v20, v20, v74, v30
	v_fma_f32 v21, v21, v75, v31
	v_fma_f32 v18, v24, v78, v18
	v_fma_f32 v19, v25, v79, v19
	s_waitcnt lgkmcnt(1)
	v_mov_b32_e32 v22, v26
	v_mov_b32_e32 v23, v28
	v_mov_b32_e32 v28, v27
	v_fma_f32 v20, v22, v80, v20
	v_fma_f32 v21, v23, v81, v21
	v_fma_f32 v18, v28, v90, v18
	v_fma_f32 v19, v29, v91, v19
	s_waitcnt lgkmcnt(0)
	v_mov_b32_e32 v22, v34
	v_mov_b32_e32 v23, v36
	v_mov_b32_e32 v36, v35
	v_fma_f32 v20, v22, v88, v20
	v_fma_f32 v21, v23, v89, v21
	v_fma_f32 v18, v36, v92, v18
	v_fma_f32 v19, v37, v93, v19
	s_nop 0
	v_add_f32_e64 v18, v20, v18
	v_add_f32_e64 v19, v21, v19
	s_nop 0
	v_add_f32_e32 v18, v18, v19
	v_mul_f32_e64 v19, |v18|, s79
	v_exp_f32_e32 v19, v19
	v_min_f32_e32 v18, 0, v18
	v_add_f32_e32 v19, 1.0, v19
	v_log_f32_e32 v19, v19
	s_nop 0
	v_fma_f32 v51, v18, s80, -v19
	ds_read_b128 v[18:21], v32 offset:128
	ds_read_b128 v[22:25], v32 offset:144
	ds_read_b128 v[26:29], v32 offset:160
	ds_read_b128 v[34:37], v32 offset:176
	s_waitcnt lgkmcnt(3)
	v_mul_f32_e32 v31, v83, v20
	v_mov_b32_e32 v20, v19
	v_fma_f32 v30, v18, v85, v123
	v_mul_f32_e64 v18, v76, v20
	v_mul_f32_e64 v19, v77, v21
	s_waitcnt lgkmcnt(2)
	v_mov_b32_e32 v20, v22
	v_mov_b32_e32 v21, v24
	v_mov_b32_e32 v24, v23
	v_fma_f32 v20, v20, v74, v30
	v_fma_f32 v21, v21, v75, v31
	v_fma_f32 v18, v24, v78, v18
	v_fma_f32 v19, v25, v79, v19
	s_waitcnt lgkmcnt(1)
	v_mov_b32_e32 v22, v26
	v_mov_b32_e32 v23, v28
	v_mov_b32_e32 v28, v27
	v_fma_f32 v20, v22, v80, v20
	v_fma_f32 v21, v23, v81, v21
	v_fma_f32 v18, v28, v90, v18
	v_fma_f32 v19, v29, v91, v19
	s_waitcnt lgkmcnt(0)
	v_mov_b32_e32 v22, v34
	v_mov_b32_e32 v23, v36
	v_mov_b32_e32 v36, v35
	v_fma_f32 v20, v22, v88, v20
	v_fma_f32 v21, v23, v89, v21
	v_fma_f32 v18, v36, v92, v18
	v_fma_f32 v19, v37, v93, v19
	s_nop 0
	v_add_f32_e64 v18, v20, v18
	v_add_f32_e64 v19, v21, v19
	s_nop 0
	v_add_f32_e32 v18, v18, v19
	v_mul_f32_e64 v19, |v18|, s79
	v_exp_f32_e32 v19, v19
	v_min_f32_e32 v18, 0, v18
	v_add_f32_e32 v19, 1.0, v19
	v_log_f32_e32 v19, v19
	s_nop 0
	v_fma_f32 v52, v18, s80, -v19
	ds_read_b128 v[18:21], v32
	ds_read_b128 v[22:25], v32 offset:16
	ds_read_b128 v[26:29], v32 offset:32
	ds_read_b128 v[34:37], v32 offset:48
	v_fmamk_f32 v32, v39, 0x3d800000, v33
	s_waitcnt lgkmcnt(3)
; DI float bf2f(bf16_t b) { return __uint_as_float(((unsigned)b) << 16); }
; DI bf16_t f2bf(float f) { return (bf16_t)(pk2(f, 0.f) & 0xffffu); }
; template <int DIR>
; DI float prep_gate_loop(const float* r_s, bf16_t* qt, bf16_t* kt, const float (&w)[16], float bias, int kk) {
;     ...
;             const int tt = blk * 16 + i; const int t = DIR ? 63 - tt : tt;
;             const f32x4* rr = (const f32x4*)(r_s + t * 32 + DIR * 16);
;             const f32x4 r0 = rr[0], r1 = rr[1], r2 = rr[2], r3 = rr[3];
;             float s0 = __builtin_fmaf(r0[0], w[0], bias), s1 = r0[1] * w[1], s2 = r0[2] * w[2], s3 = r0[3] * w[3];
;             s0 = __builtin_fmaf(r1[0], w[4], s0); s1 = __builtin_fmaf(r1[1], w[5], s1); s2 = __builtin_fmaf(r1[2], w[6], s2); s3 = __builtin_fmaf(r1[3], w[7], s3);
;             s0 = __builtin_fmaf(r2[0], w[8], s0); s1 = __builtin_fmaf(r2[1], w[9], s1); s2 = __builtin_fmaf(r2[2], w[10], s2); s3 = __builtin_fmaf(r2[3], w[11], s3);
;             s0 = __builtin_fmaf(r3[0], w[12], s0); s1 = __builtin_fmaf(r3[1], w[13], s1); s2 = __builtin_fmaf(r3[2], w[14], s2); s3 = __builtin_fmaf(r3[3], w[15], s3);
;             const float pre = (s0 + s1) + (s2 + s3);
;             const float ex = __builtin_amdgcn_exp2f(-fabsf(pre) * LOG2E);
;             la[i] = (fminf(pre, 0.f) * LOG2E - __builtin_amdgcn_logf(1.f + ex)) * 0.0625f;
;         }
; #pragma unroll
;         for (int i = 0; i < 16; ++i) { g += la[i]; la[i] = g; }
; #pragma unroll
;         for (int i = 0; i < 16; ++i) {
;             const int tt = blk * 16 + i; const int t = DIR ? 63 - tt : tt;
;             const float e = __builtin_amdgcn_exp2f(la[i]);
;             bf16_t* qp = qt + (DIR * 64 + t) * 264 + kk; bf16_t* kp = kt + (DIR * 64 + t) * 264 + kk;
;             const float qv = bf2f(*qp), kv = bf2f(*kp);
;             *qp = f2bf(qv * 0.0625f * e);
;             *kp = f2bf(kv * __builtin_amdgcn_rcpf(e));
;         }
	v_mul_f32_e32 v31, v83, v20
	v_mov_b32_e32 v20, v19
	v_fma_f32 v30, v18, v85, v123
	v_mul_f32_e64 v18, v76, v20
	v_mul_f32_e64 v19, v77, v21
	s_waitcnt lgkmcnt(2)
	v_mov_b32_e32 v20, v22
	v_mov_b32_e32 v21, v24
	v_fma_f32 v20, v20, v74, v30
	v_fma_f32 v21, v21, v75, v31
	v_mov_b32_e32 v24, v23
	s_waitcnt lgkmcnt(1)
	v_mov_b32_e32 v22, v26
	v_mov_b32_e32 v23, v28
	v_fma_f32 v18, v24, v78, v18
	v_fma_f32 v19, v25, v79, v19
	v_fma_f32 v20, v22, v80, v20
	v_fma_f32 v21, v23, v81, v21
	v_mov_b32_e32 v28, v27
	s_waitcnt lgkmcnt(0)
	v_mov_b32_e32 v22, v34
	v_add_u32_e32 v34, s52, v120
	v_fma_f32 v18, v28, v90, v18
	v_fma_f32 v19, v29, v91, v19
	v_mov_b32_e32 v23, v36
	v_mov_b32_e32 v36, v35
	v_add_u32_e32 v35, 0x125f0, v34
	v_fma_f32 v18, v36, v92, v18
	v_fma_f32 v19, v37, v93, v19
	ds_read_u16 v37, v35
	v_exp_f32_e32 v33, v33
	v_add_u32_e32 v36, 0x22df0, v34
	ds_read_u16 v38, v36
	v_fmamk_f32 v31, v40, 0x3d800000, v32
	s_waitcnt lgkmcnt(1)
	v_lshlrev_b32_e32 v37, 16, v37
	v_mul_f32_e32 v37, 0x3d800000, v37
	v_mul_f32_e32 v37, v33, v37
	v_rcp_f32_e32 v33, v33
	s_waitcnt lgkmcnt(0)
	v_lshlrev_b32_e32 v38, 16, v38
	v_cvt_pk_bf16_f32 v37, v37, s0
	v_exp_f32_e32 v32, v32
	v_mul_f32_e32 v33, v33, v38
	v_cvt_pk_bf16_f32 v33, v33, s0
	ds_write_b16 v36, v33
	v_add_u32_e32 v33, 0x123e0, v34
	ds_read_u16 v36, v33
	ds_write_b16 v35, v37
	v_add_u32_e32 v35, 0x22be0, v34
	ds_read_u16 v37, v35
	v_fmamk_f32 v30, v41, 0x3d800000, v31
	s_waitcnt lgkmcnt(2)
	v_lshlrev_b32_e32 v36, 16, v36
	v_mul_f32_e32 v36, 0x3d800000, v36
	v_mul_f32_e32 v36, v32, v36
	v_rcp_f32_e32 v32, v32
	s_waitcnt lgkmcnt(0)
	v_lshlrev_b32_e32 v37, 16, v37
	v_cvt_pk_bf16_f32 v36, v36, s0
	v_exp_f32_e32 v31, v31
	v_mul_f32_e32 v32, v32, v37
	v_cvt_pk_bf16_f32 v32, v32, s0
	ds_write_b16 v35, v32
	v_add_u32_e32 v32, 0x121d0, v34
	ds_read_u16 v35, v32
	ds_write_b16 v33, v36
	v_add_u32_e32 v33, 0x229d0, v34
	ds_read_u16 v36, v33
	v_fmamk_f32 v29, v42, 0x3d800000, v30
	s_waitcnt lgkmcnt(2)
	v_lshlrev_b32_e32 v35, 16, v35
	v_mul_f32_e32 v35, 0x3d800000, v35
	v_mul_f32_e32 v35, v31, v35
	v_rcp_f32_e32 v31, v31
	s_waitcnt lgkmcnt(0)
	v_lshlrev_b32_e32 v36, 16, v36
	v_cvt_pk_bf16_f32 v35, v35, s0
	v_exp_f32_e32 v30, v30
	v_mul_f32_e32 v31, v31, v36
	v_cvt_pk_bf16_f32 v31, v31, s0
	ds_write_b16 v33, v31
	v_add_u32_e32 v31, 0x11fc0, v34
	ds_read_u16 v33, v31
	ds_write_b16 v32, v35
	v_add_u32_e32 v32, 0x227c0, v34
	ds_read_u16 v35, v32
	v_fmamk_f32 v28, v43, 0x3d800000, v29
	s_waitcnt lgkmcnt(2)
	v_lshlrev_b32_e32 v33, 16, v33
	v_mul_f32_e32 v33, 0x3d800000, v33
	v_mul_f32_e32 v33, v30, v33
	v_rcp_f32_e32 v30, v30
	s_waitcnt lgkmcnt(0)
	v_lshlrev_b32_e32 v35, 16, v35
	v_cvt_pk_bf16_f32 v33, v33, s0
	v_exp_f32_e32 v29, v29
	v_mul_f32_e32 v30, v30, v35
	v_cvt_pk_bf16_f32 v30, v30, s0
	ds_write_b16 v32, v30
	v_add_u32_e32 v30, 0x11db0, v34
	ds_read_u16 v32, v30
	ds_write_b16 v31, v33
	v_add_u32_e32 v31, 0x225b0, v34
	ds_read_u16 v33, v31
	v_fmamk_f32 v27, v44, 0x3d800000, v28
	s_waitcnt lgkmcnt(2)
	v_lshlrev_b32_e32 v32, 16, v32
	v_mul_f32_e32 v32, 0x3d800000, v32
	v_mul_f32_e32 v32, v29, v32
	v_rcp_f32_e32 v29, v29
	s_waitcnt lgkmcnt(0)
	v_lshlrev_b32_e32 v33, 16, v33
	v_cvt_pk_bf16_f32 v32, v32, s0
	v_exp_f32_e32 v28, v28
	v_mul_f32_e32 v29, v29, v33
	v_cvt_pk_bf16_f32 v29, v29, s0
	ds_write_b16 v31, v29
	v_add_u32_e32 v29, 0x11ba0, v34
	ds_read_u16 v31, v29
	ds_write_b16 v30, v32
	v_add_u32_e32 v30, 0x223a0, v34
	ds_read_u16 v32, v30
	v_fmamk_f32 v26, v45, 0x3d800000, v27
	s_waitcnt lgkmcnt(2)
	v_lshlrev_b32_e32 v31, 16, v31
	v_mul_f32_e32 v31, 0x3d800000, v31
	v_mul_f32_e32 v31, v28, v31
	v_rcp_f32_e32 v28, v28
	s_waitcnt lgkmcnt(0)
	v_lshlrev_b32_e32 v32, 16, v32
	v_cvt_pk_bf16_f32 v31, v31, s0
	v_exp_f32_e32 v27, v27
	v_mul_f32_e32 v28, v28, v32
	v_cvt_pk_bf16_f32 v28, v28, s0
	ds_write_b16 v30, v28
	v_add_u32_e32 v28, 0x11990, v34
	ds_read_u16 v30, v28
	ds_write_b16 v29, v31
	v_add_u32_e32 v29, 0x22190, v34
	ds_read_u16 v31, v29
	v_fmamk_f32 v25, v46, 0x3d800000, v26
	s_waitcnt lgkmcnt(2)
	v_lshlrev_b32_e32 v30, 16, v30
	v_mul_f32_e32 v30, 0x3d800000, v30
	v_mul_f32_e32 v30, v27, v30
	v_rcp_f32_e32 v27, v27
	s_waitcnt lgkmcnt(0)
	v_lshlrev_b32_e32 v31, 16, v31
	v_cvt_pk_bf16_f32 v30, v30, s0
	v_exp_f32_e32 v26, v26
	v_mul_f32_e32 v27, v27, v31
	v_cvt_pk_bf16_f32 v27, v27, s0
	ds_write_b16 v29, v27
	v_add_u32_e32 v27, 0x11780, v34
	ds_read_u16 v29, v27
	ds_write_b16 v28, v30
	v_add_u32_e32 v28, 0x21f80, v34
	ds_read_u16 v30, v28
	v_fmamk_f32 v24, v47, 0x3d800000, v25
	s_waitcnt lgkmcnt(2)
	v_lshlrev_b32_e32 v29, 16, v29
	v_mul_f32_e32 v29, 0x3d800000, v29
	v_mul_f32_e32 v29, v26, v29
	v_rcp_f32_e32 v26, v26
	s_waitcnt lgkmcnt(0)
; DI float bf2f(bf16_t b) { return __uint_as_float(((unsigned)b) << 16); }
; DI bf16_t f2bf(float f) { return (bf16_t)(pk2(f, 0.f) & 0xffffu); }
; template <int DIR>
; DI float prep_gate_loop(const float* r_s, bf16_t* qt, bf16_t* kt, const float (&w)[16], float bias, int kk) {
;     ...
;             const float pre = (s0 + s1) + (s2 + s3);
;             const float ex = __builtin_amdgcn_exp2f(-fabsf(pre) * LOG2E);
;             la[i] = (fminf(pre, 0.f) * LOG2E - __builtin_amdgcn_logf(1.f + ex)) * 0.0625f;
;         }
; #pragma unroll
;         for (int i = 0; i < 16; ++i) { g += la[i]; la[i] = g; }
; #pragma unroll
;         for (int i = 0; i < 16; ++i) {
;             const int tt = blk * 16 + i; const int t = DIR ? 63 - tt : tt;
;             const float e = __builtin_amdgcn_exp2f(la[i]);
;             bf16_t* qp = qt + (DIR * 64 + t) * 264 + kk; bf16_t* kp = kt + (DIR * 64 + t) * 264 + kk;
;             const float qv = bf2f(*qp), kv = bf2f(*kp);
;             *qp = f2bf(qv * 0.0625f * e);
;             *kp = f2bf(kv * __builtin_amdgcn_rcpf(e));
;         }
	v_lshlrev_b32_e32 v30, 16, v30
	v_cvt_pk_bf16_f32 v29, v29, s0
	v_exp_f32_e32 v25, v25
	v_mul_f32_e32 v26, v26, v30
	v_cvt_pk_bf16_f32 v26, v26, s0
	ds_write_b16 v28, v26
	v_add_u32_e32 v26, 0x11570, v34
	ds_read_u16 v28, v26
	ds_write_b16 v27, v29
	v_add_u32_e32 v27, 0x21d70, v34
	ds_read_u16 v29, v27
	v_fma_f32 v20, v22, v88, v20
	v_fma_f32 v21, v23, v89, v21
	s_waitcnt lgkmcnt(2)
	v_lshlrev_b32_e32 v28, 16, v28
	v_mul_f32_e32 v28, 0x3d800000, v28
	v_mul_f32_e32 v28, v25, v28
	v_rcp_f32_e32 v25, v25
	s_waitcnt lgkmcnt(0)
	v_lshlrev_b32_e32 v29, 16, v29
	v_fmamk_f32 v23, v48, 0x3d800000, v24
	v_cvt_pk_bf16_f32 v28, v28, s0
	v_mul_f32_e32 v25, v25, v29
	v_cvt_pk_bf16_f32 v25, v25, s0
	ds_write_b16 v27, v25
	v_add_u32_e32 v25, 0x11360, v34
	ds_read_u16 v27, v25
	v_exp_f32_e32 v24, v24
	ds_write_b16 v26, v28
	v_add_u32_e32 v26, 0x21b60, v34
	ds_read_u16 v28, v26
	s_waitcnt lgkmcnt(2)
	v_lshlrev_b32_e32 v27, 16, v27
	v_mul_f32_e32 v27, 0x3d800000, v27
	v_mul_f32_e32 v27, v24, v27
	v_rcp_f32_e32 v24, v24
	s_waitcnt lgkmcnt(0)
	v_lshlrev_b32_e32 v28, 16, v28
	v_fmamk_f32 v22, v49, 0x3d800000, v23
	v_cvt_pk_bf16_f32 v27, v27, s0
	v_mul_f32_e32 v24, v24, v28
	v_cvt_pk_bf16_f32 v24, v24, s0
	ds_write_b16 v26, v24
	v_add_u32_e32 v24, 0x11150, v34
	ds_read_u16 v26, v24
	v_exp_f32_e32 v23, v23
	ds_write_b16 v25, v27
	v_add_u32_e32 v25, 0x21950, v34
	ds_read_u16 v27, v25
	s_waitcnt lgkmcnt(2)
	v_lshlrev_b32_e32 v26, 16, v26
	v_mul_f32_e32 v26, 0x3d800000, v26
	v_mul_f32_e32 v26, v23, v26
	v_rcp_f32_e32 v23, v23
	s_waitcnt lgkmcnt(0)
	v_lshlrev_b32_e32 v27, 16, v27
	v_add_f32_e64 v18, v20, v18
	v_add_f32_e64 v19, v21, v19
	v_fmamk_f32 v21, v50, 0x3d800000, v22
	v_mul_f32_e32 v23, v23, v27
	v_cvt_pk_bf16_f32 v23, v23, s0
	ds_write_b16 v25, v23
	v_add_u32_e32 v23, 0x10f40, v34
	ds_read_u16 v25, v23
	v_cvt_pk_bf16_f32 v26, v26, s0
	v_exp_f32_e32 v22, v22
	ds_write_b16 v24, v26
	v_add_u32_e32 v24, 0x21740, v34
	ds_read_u16 v26, v24
	s_waitcnt lgkmcnt(2)
	v_lshlrev_b32_e32 v25, 16, v25
	v_mul_f32_e32 v25, 0x3d800000, v25
	v_mul_f32_e32 v25, v22, v25
	v_rcp_f32_e32 v22, v22
	s_waitcnt lgkmcnt(0)
	v_lshlrev_b32_e32 v26, 16, v26
	v_fmamk_f32 v20, v51, 0x3d800000, v21
	v_cvt_pk_bf16_f32 v25, v25, s0
	v_mul_f32_e32 v22, v22, v26
	v_cvt_pk_bf16_f32 v22, v22, s0
	ds_write_b16 v24, v22
	v_add_u32_e32 v22, 0x10d30, v34
	ds_read_u16 v24, v22
	v_exp_f32_e32 v21, v21
	ds_write_b16 v23, v25
	v_add_u32_e32 v23, 0x21530, v34
	ds_read_u16 v25, v23
	s_waitcnt lgkmcnt(2)
	v_lshlrev_b32_e32 v24, 16, v24
	v_add_f32_e32 v18, v18, v19
	v_mul_f32_e32 v24, 0x3d800000, v24
	v_mul_f32_e64 v19, |v18|, s79
	v_mul_f32_e32 v24, v21, v24
	v_rcp_f32_e32 v21, v21
	v_exp_f32_e32 v19, v19
	s_waitcnt lgkmcnt(0)
	v_lshlrev_b32_e32 v25, 16, v25
	v_min_f32_e32 v18, 0, v18
	v_mul_f32_e32 v21, v21, v25
	v_add_f32_e32 v19, 1.0, v19
	v_cvt_pk_bf16_f32 v21, v21, s0
	v_log_f32_e32 v19, v19
	ds_write_b16 v23, v21
	v_add_u32_e32 v21, 0x10b20, v34
	ds_read_u16 v23, v21
	v_fma_f32 v18, v18, s80, -v19
	v_fmamk_f32 v19, v52, 0x3d800000, v20
	v_cvt_pk_bf16_f32 v24, v24, s0
	v_exp_f32_e32 v20, v20
	ds_write_b16 v22, v24
	v_add_u32_e32 v22, 0x21320, v34
	ds_read_u16 v24, v22
	s_waitcnt lgkmcnt(2)
	v_lshlrev_b32_e32 v23, 16, v23
	v_mul_f32_e32 v23, 0x3d800000, v23
	v_mul_f32_e32 v23, v20, v23
	v_rcp_f32_e32 v20, v20
	s_waitcnt lgkmcnt(0)
	v_lshlrev_b32_e32 v24, 16, v24
	v_fmamk_f32 v18, v18, 0x3d800000, v19
	v_cvt_pk_bf16_f32 v23, v23, s0
	v_mul_f32_e32 v20, v20, v24
	v_cvt_pk_bf16_f32 v20, v20, s0
	ds_write_b16 v22, v20
	v_add_u32_e32 v20, 0x10910, v34
	ds_read_u16 v22, v20
	v_exp_f32_e32 v19, v19
	ds_write_b16 v21, v23
	v_add_u32_e32 v21, 0x21110, v34
	ds_read_u16 v23, v21
	s_waitcnt lgkmcnt(2)
	v_lshlrev_b32_e32 v22, 16, v22
	v_mul_f32_e32 v22, 0x3d800000, v22
	v_mul_f32_e32 v22, v19, v22
	v_rcp_f32_e32 v19, v19
	s_waitcnt lgkmcnt(0)
	v_lshlrev_b32_e32 v23, 16, v23
	v_cvt_pk_bf16_f32 v22, v22, s0
	v_exp_f32_e32 v112, v18
	v_mul_f32_e32 v19, v19, v23
	v_cvt_pk_bf16_f32 v19, v19, s0
	ds_write_b16 v21, v19
	v_add_u32_e32 v19, 0x10700, v34
	ds_read_u16 v21, v19
	ds_write_b16 v20, v22
	v_add_u32_e32 v20, 0x20f00, v34
	ds_read_u16 v22, v20
	s_addk_i32 s52, 0xdf00
	s_waitcnt lgkmcnt(2)
	v_lshlrev_b32_e32 v21, 16, v21
	v_mul_f32_e32 v21, 0x3d800000, v21
	v_mul_f32_e32 v21, v112, v21
	v_cvt_pk_bf16_f32 v21, v21, s0
	ds_write_b16 v19, v21
	v_rcp_f32_e32 v19, v112
	s_waitcnt lgkmcnt(1)
	v_lshlrev_b32_e32 v22, 16, v22
	s_cmp_lg_u32 s52, 0xffff7c00
	v_mov_b32_e32 v33, v18
	v_mul_f32_e32 v19, v19, v22
	v_cvt_pk_bf16_f32 v19, v19, s0
	ds_write_b16 v20, v19
	s_cbranch_scc1 .LBB0_356

; template <int DIR>
; DI float prep_gate_loop(const float* r_s, bf16_t* qt, bf16_t* kt, const float (&w)[16], float bias, int kk) {
;     ...
;         for (int i = 0; i < 16; ++i) {
;             const int tt = blk * 16 + i; const int t = DIR ? 63 - tt : tt;
;             const f32x4* rr = (const f32x4*)(r_s + t * 32 + DIR * 16);
;             const f32x4 r0 = rr[0], r1 = rr[1], r2 = rr[2], r3 = rr[3];
;             float s0 = __builtin_fmaf(r0[0], w[0], bias), s1 = r0[1] * w[1], s2 = r0[2] * w[2], s3 = r0[3] * w[3];
;             s0 = __builtin_fmaf(r1[0], w[4], s0); s1 = __builtin_fmaf(r1[1], w[5], s1); s2 = __builtin_fmaf(r1[2], w[6], s2); s3 = __builtin_fmaf(r1[3], w[7], s3);
;             s0 = __builtin_fmaf(r2[0], w[8], s0); s1 = __builtin_fmaf(r2[1], w[9], s1); s2 = __builtin_fmaf(r2[2], w[10], s2); s3 = __builtin_fmaf(r2[3], w[11], s3);
;             s0 = __builtin_fmaf(r3[0], w[12], s0); s1 = __builtin_fmaf(r3[1], w[13], s1); s2 = __builtin_fmaf(r3[2], w[14], s2); s3 = __builtin_fmaf(r3[3], w[15], s3);
;             const float pre = (s0 + s1) + (s2 + s3);
;             const float ex = __builtin_amdgcn_exp2f(-fabsf(pre) * LOG2E);
;             la[i] = (fminf(pre, 0.f) * LOG2E - __builtin_amdgcn_logf(1.f + ex)) * 0.0625f;
;         }
.LBB0_360:
	v_mov_b32_e32 v32, s55
	ds_read_b128 v[18:21], v32
	ds_read_b128 v[22:25], v32 offset:16
	ds_read_b128 v[26:29], v32 offset:32
	ds_read_b128 v[34:37], v32 offset:48
	s_addk_i32 s55, 0x800
	s_waitcnt lgkmcnt(3)
	v_fma_f32 v18, v18, v85, v123
	v_mul_f32_e32 v19, v76, v19
	v_mul_f32_e32 v20, v83, v20
	v_mul_f32_e32 v21, v77, v21
	s_waitcnt lgkmcnt(2)
	v_fmac_f32_e32 v18, v22, v74
	v_fmac_f32_e32 v19, v23, v78
	v_fmac_f32_e32 v20, v24, v75
	v_fmac_f32_e32 v21, v25, v79
	s_waitcnt lgkmcnt(1)
	v_fmac_f32_e32 v18, v26, v80
	v_fmac_f32_e32 v19, v27, v90
	v_fmac_f32_e32 v20, v28, v81
	v_fmac_f32_e32 v21, v29, v91
	s_waitcnt lgkmcnt(0)
	v_fmac_f32_e32 v18, v34, v88
	v_fmac_f32_e32 v19, v35, v92
	v_fmac_f32_e32 v20, v36, v89
	v_fmac_f32_e32 v21, v37, v93
	v_add_f32_e32 v18, v18, v19
	v_add_f32_e32 v19, v20, v21
	v_add_f32_e32 v18, v18, v19
	v_mul_f32_e64 v19, |v18|, s79
	v_exp_f32_e32 v19, v19
	v_min_f32_e32 v18, 0, v18
	v_add_f32_e32 v19, 1.0, v19
	v_log_f32_e32 v19, v19
	s_nop 0
	v_fma_f32 v38, v18, s80, -v19
	ds_read_b128 v[18:21], v32 offset:128
	ds_read_b128 v[22:25], v32 offset:144
	ds_read_b128 v[26:29], v32 offset:160
	ds_read_b128 v[34:37], v32 offset:176
	v_fmac_f32_e32 v33, 0x3d800000, v38
	s_waitcnt lgkmcnt(3)
	v_fma_f32 v18, v18, v85, v123
	v_mul_f32_e32 v19, v76, v19
	v_mul_f32_e32 v20, v83, v20
	v_mul_f32_e32 v21, v77, v21
	s_waitcnt lgkmcnt(2)
	v_fmac_f32_e32 v18, v22, v74
	v_fmac_f32_e32 v19, v23, v78
	v_fmac_f32_e32 v20, v24, v75
	v_fmac_f32_e32 v21, v25, v79
	s_waitcnt lgkmcnt(1)
	v_fmac_f32_e32 v18, v26, v80
	v_fmac_f32_e32 v19, v27, v90
	v_fmac_f32_e32 v20, v28, v81
	v_fmac_f32_e32 v21, v29, v91
	s_waitcnt lgkmcnt(0)
	v_fmac_f32_e32 v18, v34, v88
	v_fmac_f32_e32 v19, v35, v92
	v_fmac_f32_e32 v20, v36, v89
	v_fmac_f32_e32 v21, v37, v93
	v_add_f32_e32 v18, v18, v19
	v_add_f32_e32 v19, v20, v21
	v_add_f32_e32 v18, v18, v19
	v_mul_f32_e64 v19, |v18|, s79
	v_exp_f32_e32 v19, v19
	v_min_f32_e32 v18, 0, v18
	v_add_f32_e32 v19, 1.0, v19
	v_log_f32_e32 v19, v19
	s_nop 0
	v_fma_f32 v39, v18, s80, -v19
	ds_read_b128 v[18:21], v32 offset:256
	ds_read_b128 v[22:25], v32 offset:272
	ds_read_b128 v[26:29], v32 offset:288
	ds_read_b128 v[34:37], v32 offset:304
	s_waitcnt lgkmcnt(3)
	v_fma_f32 v18, v18, v85, v123
	v_mul_f32_e32 v19, v76, v19
	v_mul_f32_e32 v20, v83, v20
	v_mul_f32_e32 v21, v77, v21
	s_waitcnt lgkmcnt(2)
	v_fmac_f32_e32 v18, v22, v74
	v_fmac_f32_e32 v19, v23, v78
	v_fmac_f32_e32 v20, v24, v75
	v_fmac_f32_e32 v21, v25, v79
	s_waitcnt lgkmcnt(1)
	v_fmac_f32_e32 v18, v26, v80
	v_fmac_f32_e32 v19, v27, v90
	v_fmac_f32_e32 v20, v28, v81
	v_fmac_f32_e32 v21, v29, v91
	s_waitcnt lgkmcnt(0)
	v_fmac_f32_e32 v18, v34, v88
	v_fmac_f32_e32 v19, v35, v92
	v_fmac_f32_e32 v20, v36, v89
	v_fmac_f32_e32 v21, v37, v93
	v_add_f32_e32 v18, v18, v19
	v_add_f32_e32 v19, v20, v21
	v_add_f32_e32 v18, v18, v19
	v_mul_f32_e64 v19, |v18|, s79
	v_exp_f32_e32 v19, v19
	v_min_f32_e32 v18, 0, v18
	v_add_f32_e32 v19, 1.0, v19
	v_log_f32_e32 v19, v19
	s_nop 0
	v_fma_f32 v40, v18, s80, -v19
	ds_read_b128 v[18:21], v32 offset:384
	ds_read_b128 v[22:25], v32 offset:400
	ds_read_b128 v[26:29], v32 offset:416
	ds_read_b128 v[34:37], v32 offset:432
	s_waitcnt lgkmcnt(3)
	v_fma_f32 v18, v18, v85, v123
	v_mul_f32_e32 v19, v76, v19
	v_mul_f32_e32 v20, v83, v20
	v_mul_f32_e32 v21, v77, v21
	s_waitcnt lgkmcnt(2)
	v_fmac_f32_e32 v18, v22, v74
	v_fmac_f32_e32 v19, v23, v78
	v_fmac_f32_e32 v20, v24, v75
	v_fmac_f32_e32 v21, v25, v79
	s_waitcnt lgkmcnt(1)
	v_fmac_f32_e32 v18, v26, v80
	v_fmac_f32_e32 v19, v27, v90
	v_fmac_f32_e32 v20, v28, v81
	v_fmac_f32_e32 v21, v29, v91
	s_waitcnt lgkmcnt(0)
	v_fmac_f32_e32 v18, v34, v88
	v_fmac_f32_e32 v19, v35, v92
	v_fmac_f32_e32 v20, v36, v89
	v_fmac_f32_e32 v21, v37, v93
	v_add_f32_e32 v18, v18, v19
	v_add_f32_e32 v19, v20, v21
	v_add_f32_e32 v18, v18, v19
	v_mul_f32_e64 v19, |v18|, s79
	v_exp_f32_e32 v19, v19
	v_min_f32_e32 v18, 0, v18
	v_add_f32_e32 v19, 1.0, v19
	v_log_f32_e32 v19, v19
	s_nop 0
	v_fma_f32 v41, v18, s80, -v19
	ds_read_b128 v[18:21], v32 offset:512
	ds_read_b128 v[22:25], v32 offset:528
	ds_read_b128 v[26:29], v32 offset:544
	ds_read_b128 v[34:37], v32 offset:560
	s_waitcnt lgkmcnt(3)
	v_fma_f32 v18, v18, v85, v123
	v_mul_f32_e32 v19, v76, v19
	v_mul_f32_e32 v20, v83, v20
	v_mul_f32_e32 v21, v77, v21
	s_waitcnt lgkmcnt(2)
	v_fmac_f32_e32 v18, v22, v74
	v_fmac_f32_e32 v19, v23, v78
	v_fmac_f32_e32 v20, v24, v75
	v_fmac_f32_e32 v21, v25, v79
	s_waitcnt lgkmcnt(1)
	v_fmac_f32_e32 v18, v26, v80
	v_fmac_f32_e32 v19, v27, v90
	v_fmac_f32_e32 v20, v28, v81
	v_fmac_f32_e32 v21, v29, v91
	s_waitcnt lgkmcnt(0)
	v_fmac_f32_e32 v18, v34, v88
	v_fmac_f32_e32 v19, v35, v92
	v_fmac_f32_e32 v20, v36, v89
	v_fmac_f32_e32 v21, v37, v93
	v_add_f32_e32 v18, v18, v19
	v_add_f32_e32 v19, v20, v21
	v_add_f32_e32 v18, v18, v19
	v_mul_f32_e64 v19, |v18|, s79
	v_exp_f32_e32 v19, v19
	v_min_f32_e32 v18, 0, v18
	v_add_f32_e32 v19, 1.0, v19
	v_log_f32_e32 v19, v19
	s_nop 0
	v_fma_f32 v42, v18, s80, -v19
	ds_read_b128 v[18:21], v32 offset:640
	ds_read_b128 v[22:25], v32 offset:656
	ds_read_b128 v[26:29], v32 offset:672
	ds_read_b128 v[34:37], v32 offset:688
	s_waitcnt lgkmcnt(3)
	v_fma_f32 v18, v18, v85, v123
	v_mul_f32_e32 v19, v76, v19
	v_mul_f32_e32 v20, v83, v20
	v_mul_f32_e32 v21, v77, v21
	s_waitcnt lgkmcnt(2)
	v_fmac_f32_e32 v18, v22, v74
	v_fmac_f32_e32 v19, v23, v78
	v_fmac_f32_e32 v20, v24, v75
	v_fmac_f32_e32 v21, v25, v79
	s_waitcnt lgkmcnt(1)
	v_fmac_f32_e32 v18, v26, v80
	v_fmac_f32_e32 v19, v27, v90
	v_fmac_f32_e32 v20, v28, v81
	v_fmac_f32_e32 v21, v29, v91
	s_waitcnt lgkmcnt(0)
; template <int DIR>
; DI float prep_gate_loop(const float* r_s, bf16_t* qt, bf16_t* kt, const float (&w)[16], float bias, int kk) {
;     ...
;         for (int i = 0; i < 16; ++i) {
;             const int tt = blk * 16 + i; const int t = DIR ? 63 - tt : tt;
;             const f32x4* rr = (const f32x4*)(r_s + t * 32 + DIR * 16);
;             const f32x4 r0 = rr[0], r1 = rr[1], r2 = rr[2], r3 = rr[3];
;             float s0 = __builtin_fmaf(r0[0], w[0], bias), s1 = r0[1] * w[1], s2 = r0[2] * w[2], s3 = r0[3] * w[3];
;             s0 = __builtin_fmaf(r1[0], w[4], s0); s1 = __builtin_fmaf(r1[1], w[5], s1); s2 = __builtin_fmaf(r1[2], w[6], s2); s3 = __builtin_fmaf(r1[3], w[7], s3);
;             s0 = __builtin_fmaf(r2[0], w[8], s0); s1 = __builtin_fmaf(r2[1], w[9], s1); s2 = __builtin_fmaf(r2[2], w[10], s2); s3 = __builtin_fmaf(r2[3], w[11], s3);
;             s0 = __builtin_fmaf(r3[0], w[12], s0); s1 = __builtin_fmaf(r3[1], w[13], s1); s2 = __builtin_fmaf(r3[2], w[14], s2); s3 = __builtin_fmaf(r3[3], w[15], s3);
;             const float pre = (s0 + s1) + (s2 + s3);
;             const float ex = __builtin_amdgcn_exp2f(-fabsf(pre) * LOG2E);
;             la[i] = (fminf(pre, 0.f) * LOG2E - __builtin_amdgcn_logf(1.f + ex)) * 0.0625f;
;         }
	v_fmac_f32_e32 v18, v34, v88
	v_fmac_f32_e32 v19, v35, v92
	v_fmac_f32_e32 v20, v36, v89
	v_fmac_f32_e32 v21, v37, v93
	v_add_f32_e32 v18, v18, v19
	v_add_f32_e32 v19, v20, v21
	v_add_f32_e32 v18, v18, v19
	v_mul_f32_e64 v19, |v18|, s79
	v_exp_f32_e32 v19, v19
	v_min_f32_e32 v18, 0, v18
	v_add_f32_e32 v19, 1.0, v19
	v_log_f32_e32 v19, v19
	s_nop 0
	v_fma_f32 v43, v18, s80, -v19
	ds_read_b128 v[18:21], v32 offset:768
	ds_read_b128 v[22:25], v32 offset:784
	ds_read_b128 v[26:29], v32 offset:800
	ds_read_b128 v[34:37], v32 offset:816
	s_waitcnt lgkmcnt(3)
	v_fma_f32 v18, v18, v85, v123
	v_mul_f32_e32 v19, v76, v19
	v_mul_f32_e32 v20, v83, v20
	v_mul_f32_e32 v21, v77, v21
	s_waitcnt lgkmcnt(2)
	v_fmac_f32_e32 v18, v22, v74
	v_fmac_f32_e32 v19, v23, v78
	v_fmac_f32_e32 v20, v24, v75
	v_fmac_f32_e32 v21, v25, v79
	s_waitcnt lgkmcnt(1)
	v_fmac_f32_e32 v18, v26, v80
	v_fmac_f32_e32 v19, v27, v90
	v_fmac_f32_e32 v20, v28, v81
	v_fmac_f32_e32 v21, v29, v91
	s_waitcnt lgkmcnt(0)
	v_fmac_f32_e32 v18, v34, v88
	v_fmac_f32_e32 v19, v35, v92
	v_fmac_f32_e32 v20, v36, v89
	v_fmac_f32_e32 v21, v37, v93
	v_add_f32_e32 v18, v18, v19
	v_add_f32_e32 v19, v20, v21
	v_add_f32_e32 v18, v18, v19
	v_mul_f32_e64 v19, |v18|, s79
	v_exp_f32_e32 v19, v19
	v_min_f32_e32 v18, 0, v18
	v_add_f32_e32 v19, 1.0, v19
	v_log_f32_e32 v19, v19
	s_nop 0
	v_fma_f32 v44, v18, s80, -v19
	ds_read_b128 v[18:21], v32 offset:896
	ds_read_b128 v[22:25], v32 offset:912
	ds_read_b128 v[26:29], v32 offset:928
	ds_read_b128 v[34:37], v32 offset:944
	s_waitcnt lgkmcnt(3)
	v_fma_f32 v18, v18, v85, v123
	v_mul_f32_e32 v19, v76, v19
	v_mul_f32_e32 v20, v83, v20
	v_mul_f32_e32 v21, v77, v21
	s_waitcnt lgkmcnt(2)
	v_fmac_f32_e32 v18, v22, v74
	v_fmac_f32_e32 v19, v23, v78
	v_fmac_f32_e32 v20, v24, v75
	v_fmac_f32_e32 v21, v25, v79
	s_waitcnt lgkmcnt(1)
	v_fmac_f32_e32 v18, v26, v80
	v_fmac_f32_e32 v19, v27, v90
	v_fmac_f32_e32 v20, v28, v81
	v_fmac_f32_e32 v21, v29, v91
	s_waitcnt lgkmcnt(0)
	v_fmac_f32_e32 v18, v34, v88
	v_fmac_f32_e32 v19, v35, v92
	v_fmac_f32_e32 v20, v36, v89
	v_fmac_f32_e32 v21, v37, v93
	v_add_f32_e32 v18, v18, v19
	v_add_f32_e32 v19, v20, v21
	v_add_f32_e32 v18, v18, v19
	v_mul_f32_e64 v19, |v18|, s79
	v_exp_f32_e32 v19, v19
	v_min_f32_e32 v18, 0, v18
	v_add_f32_e32 v19, 1.0, v19
	v_log_f32_e32 v19, v19
	s_nop 0
	v_fma_f32 v45, v18, s80, -v19
	ds_read_b128 v[18:21], v32 offset:1024
	ds_read_b128 v[22:25], v32 offset:1040
	ds_read_b128 v[26:29], v32 offset:1056
	ds_read_b128 v[34:37], v32 offset:1072
	s_waitcnt lgkmcnt(3)
	v_fma_f32 v18, v18, v85, v123
	v_mul_f32_e32 v19, v76, v19
	v_mul_f32_e32 v20, v83, v20
	v_mul_f32_e32 v21, v77, v21
	s_waitcnt lgkmcnt(2)
	v_fmac_f32_e32 v18, v22, v74
	v_fmac_f32_e32 v19, v23, v78
	v_fmac_f32_e32 v20, v24, v75
	v_fmac_f32_e32 v21, v25, v79
	s_waitcnt lgkmcnt(1)
	v_fmac_f32_e32 v18, v26, v80
	v_fmac_f32_e32 v19, v27, v90
	v_fmac_f32_e32 v20, v28, v81
	v_fmac_f32_e32 v21, v29, v91
	s_waitcnt lgkmcnt(0)
	v_fmac_f32_e32 v18, v34, v88
	v_fmac_f32_e32 v19, v35, v92
	v_fmac_f32_e32 v20, v36, v89
	v_fmac_f32_e32 v21, v37, v93
	v_add_f32_e32 v18, v18, v19
	v_add_f32_e32 v19, v20, v21
	v_add_f32_e32 v18, v18, v19
	v_mul_f32_e64 v19, |v18|, s79
	v_exp_f32_e32 v19, v19
	v_min_f32_e32 v18, 0, v18
	v_add_f32_e32 v19, 1.0, v19
	v_log_f32_e32 v19, v19
	s_nop 0
	v_fma_f32 v46, v18, s80, -v19
	ds_read_b128 v[18:21], v32 offset:1152
	ds_read_b128 v[22:25], v32 offset:1168
	ds_read_b128 v[26:29], v32 offset:1184
	ds_read_b128 v[34:37], v32 offset:1200
	s_waitcnt lgkmcnt(3)
	v_mul_f32_e32 v31, v83, v20
	v_mov_b32_e32 v20, v19
	v_fma_f32 v30, v18, v85, v123
	v_mul_f32_e64 v18, v76, v20
	v_mul_f32_e64 v19, v77, v21
	s_waitcnt lgkmcnt(2)
	v_mov_b32_e32 v20, v22
	v_mov_b32_e32 v21, v24
	v_mov_b32_e32 v24, v23
	v_fma_f32 v20, v20, v74, v30
	v_fma_f32 v21, v21, v75, v31
	v_fma_f32 v18, v24, v78, v18
	v_fma_f32 v19, v25, v79, v19
	s_waitcnt lgkmcnt(1)
	v_mov_b32_e32 v22, v26
	v_mov_b32_e32 v23, v28
	v_mov_b32_e32 v28, v27
	v_fma_f32 v20, v22, v80, v20
	v_fma_f32 v21, v23, v81, v21
	v_fma_f32 v18, v28, v90, v18
	v_fma_f32 v19, v29, v91, v19
	s_waitcnt lgkmcnt(0)
	v_mov_b32_e32 v22, v34
	v_mov_b32_e32 v23, v36
	v_mov_b32_e32 v36, v35
	v_fma_f32 v20, v22, v88, v20
	v_fma_f32 v21, v23, v89, v21
	v_fma_f32 v18, v36, v92, v18
	v_fma_f32 v19, v37, v93, v19
	s_nop 0
	v_add_f32_e64 v18, v20, v18
	v_add_f32_e64 v19, v21, v19
	s_nop 0
	v_add_f32_e32 v18, v18, v19
	v_mul_f32_e64 v19, |v18|, s79
	v_exp_f32_e32 v19, v19
	v_min_f32_e32 v18, 0, v18
	v_add_f32_e32 v19, 1.0, v19
	v_log_f32_e32 v19, v19
	s_nop 0
	v_fma_f32 v47, v18, s80, -v19
	ds_read_b128 v[18:21], v32 offset:1280
	ds_read_b128 v[22:25], v32 offset:1296
	ds_read_b128 v[26:29], v32 offset:1312
	ds_read_b128 v[34:37], v32 offset:1328
	s_waitcnt lgkmcnt(3)
	v_mul_f32_e32 v31, v83, v20
	v_mov_b32_e32 v20, v19
	v_fma_f32 v30, v18, v85, v123
	v_mul_f32_e64 v18, v76, v20
	v_mul_f32_e64 v19, v77, v21
	s_waitcnt lgkmcnt(2)
	v_mov_b32_e32 v20, v22
	v_mov_b32_e32 v21, v24
	v_mov_b32_e32 v24, v23
	v_fma_f32 v20, v20, v74, v30
	v_fma_f32 v21, v21, v75, v31
	v_fma_f32 v18, v24, v78, v18
	v_fma_f32 v19, v25, v79, v19
	s_waitcnt lgkmcnt(1)
	v_mov_b32_e32 v22, v26
	v_mov_b32_e32 v23, v28
	v_mov_b32_e32 v28, v27
	v_fma_f32 v20, v22, v80, v20
	v_fma_f32 v21, v23, v81, v21
	v_fma_f32 v18, v28, v90, v18
	v_fma_f32 v19, v29, v91, v19
	s_waitcnt lgkmcnt(0)
; template <int DIR>
; DI float prep_gate_loop(const float* r_s, bf16_t* qt, bf16_t* kt, const float (&w)[16], float bias, int kk) {
;     ...
;         for (int i = 0; i < 16; ++i) {
;             const int tt = blk * 16 + i; const int t = DIR ? 63 - tt : tt;
;             const f32x4* rr = (const f32x4*)(r_s + t * 32 + DIR * 16);
;             const f32x4 r0 = rr[0], r1 = rr[1], r2 = rr[2], r3 = rr[3];
;             float s0 = __builtin_fmaf(r0[0], w[0], bias), s1 = r0[1] * w[1], s2 = r0[2] * w[2], s3 = r0[3] * w[3];
;             s0 = __builtin_fmaf(r1[0], w[4], s0); s1 = __builtin_fmaf(r1[1], w[5], s1); s2 = __builtin_fmaf(r1[2], w[6], s2); s3 = __builtin_fmaf(r1[3], w[7], s3);
;             s0 = __builtin_fmaf(r2[0], w[8], s0); s1 = __builtin_fmaf(r2[1], w[9], s1); s2 = __builtin_fmaf(r2[2], w[10], s2); s3 = __builtin_fmaf(r2[3], w[11], s3);
;             s0 = __builtin_fmaf(r3[0], w[12], s0); s1 = __builtin_fmaf(r3[1], w[13], s1); s2 = __builtin_fmaf(r3[2], w[14], s2); s3 = __builtin_fmaf(r3[3], w[15], s3);
;             const float pre = (s0 + s1) + (s2 + s3);
;             const float ex = __builtin_amdgcn_exp2f(-fabsf(pre) * LOG2E);
;             la[i] = (fminf(pre, 0.f) * LOG2E - __builtin_amdgcn_logf(1.f + ex)) * 0.0625f;
;         }
	v_mov_b32_e32 v22, v34
	v_mov_b32_e32 v23, v36
	v_mov_b32_e32 v36, v35
	v_fma_f32 v20, v22, v88, v20
	v_fma_f32 v21, v23, v89, v21
	v_fma_f32 v18, v36, v92, v18
	v_fma_f32 v19, v37, v93, v19
	s_nop 0
	v_add_f32_e64 v18, v20, v18
	v_add_f32_e64 v19, v21, v19
	s_nop 0
	v_add_f32_e32 v18, v18, v19
	v_mul_f32_e64 v19, |v18|, s79
	v_exp_f32_e32 v19, v19
	v_min_f32_e32 v18, 0, v18
	v_add_f32_e32 v19, 1.0, v19
	v_log_f32_e32 v19, v19
	s_nop 0
	v_fma_f32 v48, v18, s80, -v19
	ds_read_b128 v[18:21], v32 offset:1408
	ds_read_b128 v[22:25], v32 offset:1424
	ds_read_b128 v[26:29], v32 offset:1440
	ds_read_b128 v[34:37], v32 offset:1456
	s_waitcnt lgkmcnt(3)
	v_mul_f32_e32 v31, v83, v20
	v_mov_b32_e32 v20, v19
	v_fma_f32 v30, v18, v85, v123
	v_mul_f32_e64 v18, v76, v20
	v_mul_f32_e64 v19, v77, v21
	s_waitcnt lgkmcnt(2)
	v_mov_b32_e32 v20, v22
	v_mov_b32_e32 v21, v24
	v_mov_b32_e32 v24, v23
	v_fma_f32 v20, v20, v74, v30
	v_fma_f32 v21, v21, v75, v31
	v_fma_f32 v18, v24, v78, v18
	v_fma_f32 v19, v25, v79, v19
	s_waitcnt lgkmcnt(1)
	v_mov_b32_e32 v22, v26
	v_mov_b32_e32 v23, v28
	v_mov_b32_e32 v28, v27
	v_fma_f32 v20, v22, v80, v20
	v_fma_f32 v21, v23, v81, v21
	v_fma_f32 v18, v28, v90, v18
	v_fma_f32 v19, v29, v91, v19
	s_waitcnt lgkmcnt(0)
	v_mov_b32_e32 v22, v34
	v_mov_b32_e32 v23, v36
	v_mov_b32_e32 v36, v35
	v_fma_f32 v20, v22, v88, v20
	v_fma_f32 v21, v23, v89, v21
	v_fma_f32 v18, v36, v92, v18
	v_fma_f32 v19, v37, v93, v19
	s_nop 0
	v_add_f32_e64 v18, v20, v18
	v_add_f32_e64 v19, v21, v19
	s_nop 0
	v_add_f32_e32 v18, v18, v19
	v_mul_f32_e64 v19, |v18|, s79
	v_exp_f32_e32 v19, v19
	v_min_f32_e32 v18, 0, v18
	v_add_f32_e32 v19, 1.0, v19
	v_log_f32_e32 v19, v19
	s_nop 0
	v_fma_f32 v49, v18, s80, -v19
	ds_read_b128 v[18:21], v32 offset:1536
	ds_read_b128 v[22:25], v32 offset:1552
	ds_read_b128 v[26:29], v32 offset:1568
	ds_read_b128 v[34:37], v32 offset:1584
	s_waitcnt lgkmcnt(3)
	v_mul_f32_e32 v31, v83, v20
	v_mov_b32_e32 v20, v19
	v_fma_f32 v30, v18, v85, v123
	v_mul_f32_e64 v18, v76, v20
	v_mul_f32_e64 v19, v77, v21
	s_waitcnt lgkmcnt(2)
	v_mov_b32_e32 v20, v22
	v_mov_b32_e32 v21, v24
	v_mov_b32_e32 v24, v23
	v_fma_f32 v20, v20, v74, v30
	v_fma_f32 v21, v21, v75, v31
	v_fma_f32 v18, v24, v78, v18
	v_fma_f32 v19, v25, v79, v19
	s_waitcnt lgkmcnt(1)
	v_mov_b32_e32 v22, v26
	v_mov_b32_e32 v23, v28
	v_mov_b32_e32 v28, v27
	v_fma_f32 v20, v22, v80, v20
	v_fma_f32 v21, v23, v81, v21
	v_fma_f32 v18, v28, v90, v18
	v_fma_f32 v19, v29, v91, v19
	s_waitcnt lgkmcnt(0)
	v_mov_b32_e32 v22, v34
	v_mov_b32_e32 v23, v36
	v_mov_b32_e32 v36, v35
	v_fma_f32 v20, v22, v88, v20
	v_fma_f32 v21, v23, v89, v21
	v_fma_f32 v18, v36, v92, v18
	v_fma_f32 v19, v37, v93, v19
	s_nop 0
	v_add_f32_e64 v18, v20, v18
	v_add_f32_e64 v19, v21, v19
	s_nop 0
	v_add_f32_e32 v18, v18, v19
	v_mul_f32_e64 v19, |v18|, s79
	v_exp_f32_e32 v19, v19
	v_min_f32_e32 v18, 0, v18
	v_add_f32_e32 v19, 1.0, v19
	v_log_f32_e32 v19, v19
	s_nop 0
	v_fma_f32 v50, v18, s80, -v19
	ds_read_b128 v[18:21], v32 offset:1664
	ds_read_b128 v[22:25], v32 offset:1680
	ds_read_b128 v[26:29], v32 offset:1696
	ds_read_b128 v[34:37], v32 offset:1712
	s_waitcnt lgkmcnt(3)
	v_mul_f32_e32 v31, v83, v20
	v_mov_b32_e32 v20, v19
	v_fma_f32 v30, v18, v85, v123
	v_mul_f32_e64 v18, v76, v20
	v_mul_f32_e64 v19, v77, v21
	s_waitcnt lgkmcnt(2)
	v_mov_b32_e32 v20, v22
	v_mov_b32_e32 v21, v24
	v_mov_b32_e32 v24, v23
	v_fma_f32 v20, v20, v74, v30
	v_fma_f32 v21, v21, v75, v31
	v_fma_f32 v18, v24, v78, v18
	v_fma_f32 v19, v25, v79, v19
	s_waitcnt lgkmcnt(1)
	v_mov_b32_e32 v22, v26
	v_mov_b32_e32 v23, v28
	v_mov_b32_e32 v28, v27
	v_fma_f32 v20, v22, v80, v20
	v_fma_f32 v21, v23, v81, v21
	v_fma_f32 v18, v28, v90, v18
	v_fma_f32 v19, v29, v91, v19
	s_waitcnt lgkmcnt(0)
	v_mov_b32_e32 v22, v34
	v_mov_b32_e32 v23, v36
	v_mov_b32_e32 v36, v35
	v_fma_f32 v20, v22, v88, v20
	v_fma_f32 v21, v23, v89, v21
	v_fma_f32 v18, v36, v92, v18
	v_fma_f32 v19, v37, v93, v19
	s_nop 0
	v_add_f32_e64 v18, v20, v18
	v_add_f32_e64 v19, v21, v19
	s_nop 0
	v_add_f32_e32 v18, v18, v19
	v_mul_f32_e64 v19, |v18|, s79
	v_exp_f32_e32 v19, v19
	v_min_f32_e32 v18, 0, v18
	v_add_f32_e32 v19, 1.0, v19
	v_log_f32_e32 v19, v19
	s_nop 0
	v_fma_f32 v51, v18, s80, -v19
	ds_read_b128 v[18:21], v32 offset:1792
	ds_read_b128 v[22:25], v32 offset:1808
	ds_read_b128 v[26:29], v32 offset:1824
	ds_read_b128 v[34:37], v32 offset:1840
	s_waitcnt lgkmcnt(3)
	v_mul_f32_e32 v31, v83, v20
	v_mov_b32_e32 v20, v19
	v_fma_f32 v30, v18, v85, v123
	v_mul_f32_e64 v18, v76, v20
	v_mul_f32_e64 v19, v77, v21
	s_waitcnt lgkmcnt(2)
	v_mov_b32_e32 v20, v22
	v_mov_b32_e32 v21, v24
	v_mov_b32_e32 v24, v23
	v_fma_f32 v20, v20, v74, v30
	v_fma_f32 v21, v21, v75, v31
	v_fma_f32 v18, v24, v78, v18
	v_fma_f32 v19, v25, v79, v19
	s_waitcnt lgkmcnt(1)
	v_mov_b32_e32 v22, v26
	v_mov_b32_e32 v23, v28
	v_mov_b32_e32 v28, v27
	v_fma_f32 v20, v22, v80, v20
	v_fma_f32 v21, v23, v81, v21
	v_fma_f32 v18, v28, v90, v18
	v_fma_f32 v19, v29, v91, v19
	s_waitcnt lgkmcnt(0)
	v_mov_b32_e32 v22, v34
	v_mov_b32_e32 v23, v36
	v_mov_b32_e32 v36, v35
	v_fma_f32 v20, v22, v88, v20
	v_fma_f32 v21, v23, v89, v21
	v_fma_f32 v18, v36, v92, v18
	v_fma_f32 v19, v37, v93, v19
	s_nop 0
	v_add_f32_e64 v18, v20, v18
	v_add_f32_e64 v19, v21, v19
	s_nop 0
	v_add_f32_e32 v18, v18, v19
	v_mul_f32_e64 v19, |v18|, s79
	v_exp_f32_e32 v19, v19
	v_min_f32_e32 v18, 0, v18
	v_add_f32_e32 v19, 1.0, v19
	v_log_f32_e32 v19, v19
	s_nop 0
	v_fma_f32 v52, v18, s80, -v19
	ds_read_b128 v[18:21], v32 offset:1920
	ds_read_b128 v[22:25], v32 offset:1936
	ds_read_b128 v[26:29], v32 offset:1952
	ds_read_b128 v[34:37], v32 offset:1968
	v_fmamk_f32 v32, v39, 0x3d800000, v33
	s_waitcnt lgkmcnt(3)
; DI float bf2f(bf16_t b) { return __uint_as_float(((unsigned)b) << 16); }
; DI bf16_t f2bf(float f) { return (bf16_t)(pk2(f, 0.f) & 0xffffu); }
; template <int DIR>
; DI float prep_gate_loop(const float* r_s, bf16_t* qt, bf16_t* kt, const float (&w)[16], float bias, int kk) {
;     ...
;             const int tt = blk * 16 + i; const int t = DIR ? 63 - tt : tt;
;             const f32x4* rr = (const f32x4*)(r_s + t * 32 + DIR * 16);
;             const f32x4 r0 = rr[0], r1 = rr[1], r2 = rr[2], r3 = rr[3];
;             float s0 = __builtin_fmaf(r0[0], w[0], bias), s1 = r0[1] * w[1], s2 = r0[2] * w[2], s3 = r0[3] * w[3];
;             s0 = __builtin_fmaf(r1[0], w[4], s0); s1 = __builtin_fmaf(r1[1], w[5], s1); s2 = __builtin_fmaf(r1[2], w[6], s2); s3 = __builtin_fmaf(r1[3], w[7], s3);
;             s0 = __builtin_fmaf(r2[0], w[8], s0); s1 = __builtin_fmaf(r2[1], w[9], s1); s2 = __builtin_fmaf(r2[2], w[10], s2); s3 = __builtin_fmaf(r2[3], w[11], s3);
;             s0 = __builtin_fmaf(r3[0], w[12], s0); s1 = __builtin_fmaf(r3[1], w[13], s1); s2 = __builtin_fmaf(r3[2], w[14], s2); s3 = __builtin_fmaf(r3[3], w[15], s3);
;             const float pre = (s0 + s1) + (s2 + s3);
;             const float ex = __builtin_amdgcn_exp2f(-fabsf(pre) * LOG2E);
;             la[i] = (fminf(pre, 0.f) * LOG2E - __builtin_amdgcn_logf(1.f + ex)) * 0.0625f;
;         }
; #pragma unroll
;         for (int i = 0; i < 16; ++i) { g += la[i]; la[i] = g; }
; #pragma unroll
;         for (int i = 0; i < 16; ++i) {
;             const int tt = blk * 16 + i; const int t = DIR ? 63 - tt : tt;
;             const float e = __builtin_amdgcn_exp2f(la[i]);
;             bf16_t* qp = qt + (DIR * 64 + t) * 264 + kk; bf16_t* kp = kt + (DIR * 64 + t) * 264 + kk;
;             const float qv = bf2f(*qp), kv = bf2f(*kp);
;             *qp = f2bf(qv * 0.0625f * e);
;             *kp = f2bf(kv * __builtin_amdgcn_rcpf(e));
;         }
	v_mul_f32_e32 v31, v83, v20
	v_mov_b32_e32 v20, v19
	v_fma_f32 v30, v18, v85, v123
	v_mul_f32_e64 v18, v76, v20
	v_mul_f32_e64 v19, v77, v21
	s_waitcnt lgkmcnt(2)
	v_mov_b32_e32 v20, v22
	v_mov_b32_e32 v21, v24
	v_mov_b32_e32 v24, v23
	v_fma_f32 v20, v20, v74, v30
	v_fma_f32 v21, v21, v75, v31
	v_fma_f32 v18, v24, v78, v18
	v_fma_f32 v19, v25, v79, v19
	s_waitcnt lgkmcnt(1)
	v_mov_b32_e32 v22, v26
	v_mov_b32_e32 v23, v28
	v_mov_b32_e32 v28, v27
	v_fma_f32 v20, v22, v80, v20
	v_fma_f32 v21, v23, v81, v21
	v_fma_f32 v18, v28, v90, v18
	v_fma_f32 v19, v29, v91, v19
	s_waitcnt lgkmcnt(0)
	v_mov_b32_e32 v22, v34
	v_mov_b32_e32 v23, v36
	v_mov_b32_e32 v36, v35
	v_add_u32_e32 v34, s52, v120
	v_fma_f32 v18, v36, v92, v18
	v_fma_f32 v19, v37, v93, v19
	ds_read_u16 v36, v34 offset:8192
	v_exp_f32_e32 v33, v33
	v_add_u32_e32 v35, 0x12800, v34
	ds_read_u16 v37, v35
	v_fmamk_f32 v31, v40, 0x3d800000, v32
	s_waitcnt lgkmcnt(1)
	v_lshlrev_b32_e32 v36, 16, v36
	v_mul_f32_e32 v36, 0x3d800000, v36
	v_mul_f32_e32 v36, v33, v36
	v_rcp_f32_e32 v33, v33
	s_waitcnt lgkmcnt(0)
	v_lshlrev_b32_e32 v37, 16, v37
	v_exp_f32_e32 v32, v32
	v_cvt_pk_bf16_f32 v36, v36, s0
	v_mul_f32_e32 v33, v33, v37
	v_cvt_pk_bf16_f32 v33, v33, s0
	ds_write_b16 v35, v33
	ds_read_u16 v35, v34 offset:8720
	v_add_u32_e32 v33, 0x12a10, v34
	ds_write_b16 v34, v36 offset:8192
	ds_read_u16 v36, v33
	v_fmamk_f32 v30, v41, 0x3d800000, v31
	s_waitcnt lgkmcnt(2)
	v_lshlrev_b32_e32 v35, 16, v35
	v_mul_f32_e32 v35, 0x3d800000, v35
	v_mul_f32_e32 v35, v32, v35
	v_rcp_f32_e32 v32, v32
	s_waitcnt lgkmcnt(0)
	v_lshlrev_b32_e32 v36, 16, v36
	v_exp_f32_e32 v31, v31
	v_cvt_pk_bf16_f32 v35, v35, s0
	v_mul_f32_e32 v32, v32, v36
	v_cvt_pk_bf16_f32 v32, v32, s0
	ds_write_b16 v33, v32
	ds_read_u16 v33, v34 offset:9248
	v_add_u32_e32 v32, 0x12c20, v34
	ds_write_b16 v34, v35 offset:8720
	ds_read_u16 v35, v32
	v_fmamk_f32 v29, v42, 0x3d800000, v30
	s_waitcnt lgkmcnt(2)
	v_lshlrev_b32_e32 v33, 16, v33
	v_mul_f32_e32 v33, 0x3d800000, v33
	v_mul_f32_e32 v33, v31, v33
	v_rcp_f32_e32 v31, v31
	s_waitcnt lgkmcnt(0)
	v_lshlrev_b32_e32 v35, 16, v35
	v_exp_f32_e32 v30, v30
	v_cvt_pk_bf16_f32 v33, v33, s0
	v_mul_f32_e32 v31, v31, v35
	v_cvt_pk_bf16_f32 v31, v31, s0
	ds_write_b16 v32, v31
	ds_read_u16 v32, v34 offset:9776
	v_add_u32_e32 v31, 0x12e30, v34
	ds_write_b16 v34, v33 offset:9248
	ds_read_u16 v33, v31
	v_fmamk_f32 v28, v43, 0x3d800000, v29
	s_waitcnt lgkmcnt(2)
	v_lshlrev_b32_e32 v32, 16, v32
	v_mul_f32_e32 v32, 0x3d800000, v32
	v_mul_f32_e32 v32, v30, v32
	v_rcp_f32_e32 v30, v30
	s_waitcnt lgkmcnt(0)
	v_lshlrev_b32_e32 v33, 16, v33
	v_exp_f32_e32 v29, v29
	v_cvt_pk_bf16_f32 v32, v32, s0
	v_mul_f32_e32 v30, v30, v33
	v_cvt_pk_bf16_f32 v30, v30, s0
	ds_write_b16 v31, v30
	ds_read_u16 v31, v34 offset:10304
	v_add_u32_e32 v30, 0x13040, v34
	ds_write_b16 v34, v32 offset:9776
	ds_read_u16 v32, v30
	v_fmamk_f32 v27, v44, 0x3d800000, v28
	s_waitcnt lgkmcnt(2)
	v_lshlrev_b32_e32 v31, 16, v31
	v_mul_f32_e32 v31, 0x3d800000, v31
	v_mul_f32_e32 v31, v29, v31
	v_rcp_f32_e32 v29, v29
	s_waitcnt lgkmcnt(0)
	v_lshlrev_b32_e32 v32, 16, v32
	v_exp_f32_e32 v28, v28
	v_cvt_pk_bf16_f32 v31, v31, s0
	v_mul_f32_e32 v29, v29, v32
	v_cvt_pk_bf16_f32 v29, v29, s0
	ds_write_b16 v30, v29
	ds_read_u16 v30, v34 offset:10832
	v_add_u32_e32 v29, 0x13250, v34
	ds_write_b16 v34, v31 offset:10304
	ds_read_u16 v31, v29
	v_fmamk_f32 v26, v45, 0x3d800000, v27
	s_waitcnt lgkmcnt(2)
	v_lshlrev_b32_e32 v30, 16, v30
	v_mul_f32_e32 v30, 0x3d800000, v30
	v_mul_f32_e32 v30, v28, v30
	v_rcp_f32_e32 v28, v28
	s_waitcnt lgkmcnt(0)
	v_lshlrev_b32_e32 v31, 16, v31
	v_exp_f32_e32 v27, v27
	v_cvt_pk_bf16_f32 v30, v30, s0
	v_mul_f32_e32 v28, v28, v31
	v_cvt_pk_bf16_f32 v28, v28, s0
	ds_write_b16 v29, v28
	ds_read_u16 v29, v34 offset:11360
	v_add_u32_e32 v28, 0x13460, v34
	ds_write_b16 v34, v30 offset:10832
	ds_read_u16 v30, v28
	v_fmamk_f32 v25, v46, 0x3d800000, v26
	s_waitcnt lgkmcnt(2)
	v_lshlrev_b32_e32 v29, 16, v29
	v_mul_f32_e32 v29, 0x3d800000, v29
	v_mul_f32_e32 v29, v27, v29
	v_rcp_f32_e32 v27, v27
	s_waitcnt lgkmcnt(0)
	v_lshlrev_b32_e32 v30, 16, v30
	v_exp_f32_e32 v26, v26
	v_cvt_pk_bf16_f32 v29, v29, s0
	v_mul_f32_e32 v27, v27, v30
	v_cvt_pk_bf16_f32 v27, v27, s0
	ds_write_b16 v28, v27
	ds_read_u16 v28, v34 offset:11888
	v_add_u32_e32 v27, 0x13670, v34
	ds_write_b16 v34, v29 offset:11360
	ds_read_u16 v29, v27
	v_fmamk_f32 v24, v47, 0x3d800000, v25
	s_waitcnt lgkmcnt(2)
	v_lshlrev_b32_e32 v28, 16, v28
	v_mul_f32_e32 v28, 0x3d800000, v28
	v_mul_f32_e32 v28, v26, v28
	v_rcp_f32_e32 v26, v26
	s_waitcnt lgkmcnt(0)
; DI float bf2f(bf16_t b) { return __uint_as_float(((unsigned)b) << 16); }
; DI bf16_t f2bf(float f) { return (bf16_t)(pk2(f, 0.f) & 0xffffu); }
; template <int DIR>
; DI float prep_gate_loop(const float* r_s, bf16_t* qt, bf16_t* kt, const float (&w)[16], float bias, int kk) {
;     ...
;             float s0 = __builtin_fmaf(r0[0], w[0], bias), s1 = r0[1] * w[1], s2 = r0[2] * w[2], s3 = r0[3] * w[3];
;             s0 = __builtin_fmaf(r1[0], w[4], s0); s1 = __builtin_fmaf(r1[1], w[5], s1); s2 = __builtin_fmaf(r1[2], w[6], s2); s3 = __builtin_fmaf(r1[3], w[7], s3);
;             s0 = __builtin_fmaf(r2[0], w[8], s0); s1 = __builtin_fmaf(r2[1], w[9], s1); s2 = __builtin_fmaf(r2[2], w[10], s2); s3 = __builtin_fmaf(r2[3], w[11], s3);
;             s0 = __builtin_fmaf(r3[0], w[12], s0); s1 = __builtin_fmaf(r3[1], w[13], s1); s2 = __builtin_fmaf(r3[2], w[14], s2); s3 = __builtin_fmaf(r3[3], w[15], s3);
;             const float pre = (s0 + s1) + (s2 + s3);
;             const float ex = __builtin_amdgcn_exp2f(-fabsf(pre) * LOG2E);
;             la[i] = (fminf(pre, 0.f) * LOG2E - __builtin_amdgcn_logf(1.f + ex)) * 0.0625f;
;         }
; #pragma unroll
;         for (int i = 0; i < 16; ++i) { g += la[i]; la[i] = g; }
; #pragma unroll
;         for (int i = 0; i < 16; ++i) {
;             const int tt = blk * 16 + i; const int t = DIR ? 63 - tt : tt;
;             const float e = __builtin_amdgcn_exp2f(la[i]);
;             bf16_t* qp = qt + (DIR * 64 + t) * 264 + kk; bf16_t* kp = kt + (DIR * 64 + t) * 264 + kk;
;             const float qv = bf2f(*qp), kv = bf2f(*kp);
;             *qp = f2bf(qv * 0.0625f * e);
;             *kp = f2bf(kv * __builtin_amdgcn_rcpf(e));
	v_lshlrev_b32_e32 v29, 16, v29
	v_exp_f32_e32 v25, v25
	v_cvt_pk_bf16_f32 v28, v28, s0
	v_mul_f32_e32 v26, v26, v29
	v_cvt_pk_bf16_f32 v26, v26, s0
	ds_write_b16 v27, v26
	ds_read_u16 v27, v34 offset:12416
	v_add_u32_e32 v26, 0x13880, v34
	ds_write_b16 v34, v28 offset:11888
	ds_read_u16 v28, v26
	v_fma_f32 v20, v22, v88, v20
	v_fma_f32 v21, v23, v89, v21
	s_waitcnt lgkmcnt(2)
	v_lshlrev_b32_e32 v27, 16, v27
	v_mul_f32_e32 v27, 0x3d800000, v27
	v_mul_f32_e32 v27, v25, v27
	v_rcp_f32_e32 v25, v25
	s_waitcnt lgkmcnt(0)
	v_lshlrev_b32_e32 v28, 16, v28
	v_fmamk_f32 v23, v48, 0x3d800000, v24
	v_exp_f32_e32 v24, v24
	v_mul_f32_e32 v25, v25, v28
	v_cvt_pk_bf16_f32 v25, v25, s0
	ds_write_b16 v26, v25
	ds_read_u16 v26, v34 offset:12944
	v_cvt_pk_bf16_f32 v27, v27, s0
	v_add_u32_e32 v25, 0x13a90, v34
	ds_write_b16 v34, v27 offset:12416
	ds_read_u16 v27, v25
	s_waitcnt lgkmcnt(2)
	v_lshlrev_b32_e32 v26, 16, v26
	v_mul_f32_e32 v26, 0x3d800000, v26
	v_mul_f32_e32 v26, v24, v26
	v_rcp_f32_e32 v24, v24
	s_waitcnt lgkmcnt(0)
	v_lshlrev_b32_e32 v27, 16, v27
	v_fmamk_f32 v22, v49, 0x3d800000, v23
	v_exp_f32_e32 v23, v23
	v_mul_f32_e32 v24, v24, v27
	v_cvt_pk_bf16_f32 v24, v24, s0
	ds_write_b16 v25, v24
	ds_read_u16 v25, v34 offset:13472
	v_cvt_pk_bf16_f32 v26, v26, s0
	v_add_u32_e32 v24, 0x13ca0, v34
	ds_write_b16 v34, v26 offset:12944
	ds_read_u16 v26, v24
	s_waitcnt lgkmcnt(2)
	v_lshlrev_b32_e32 v25, 16, v25
	v_mul_f32_e32 v25, 0x3d800000, v25
	v_mul_f32_e32 v25, v23, v25
	v_rcp_f32_e32 v23, v23
	s_waitcnt lgkmcnt(0)
	v_lshlrev_b32_e32 v26, 16, v26
	v_add_f32_e64 v18, v20, v18
	v_add_f32_e64 v19, v21, v19
	v_fmamk_f32 v21, v50, 0x3d800000, v22
	v_mul_f32_e32 v23, v23, v26
	v_cvt_pk_bf16_f32 v23, v23, s0
	ds_write_b16 v24, v23
	ds_read_u16 v24, v34 offset:14000
	v_exp_f32_e32 v22, v22
	v_cvt_pk_bf16_f32 v25, v25, s0
	v_add_u32_e32 v23, 0x13eb0, v34
	ds_write_b16 v34, v25 offset:13472
	ds_read_u16 v25, v23
	s_waitcnt lgkmcnt(2)
	v_lshlrev_b32_e32 v24, 16, v24
	v_mul_f32_e32 v24, 0x3d800000, v24
	v_mul_f32_e32 v24, v22, v24
	v_rcp_f32_e32 v22, v22
	s_waitcnt lgkmcnt(0)
	v_lshlrev_b32_e32 v25, 16, v25
	v_fmamk_f32 v20, v51, 0x3d800000, v21
	v_exp_f32_e32 v21, v21
	v_mul_f32_e32 v22, v22, v25
	v_cvt_pk_bf16_f32 v22, v22, s0
	ds_write_b16 v23, v22
	ds_read_u16 v23, v34 offset:14528
	v_cvt_pk_bf16_f32 v24, v24, s0
	v_add_u32_e32 v22, 0x140c0, v34
	v_add_f32_e32 v18, v18, v19
	ds_write_b16 v34, v24 offset:14000
	ds_read_u16 v24, v22
	s_waitcnt lgkmcnt(2)
	v_lshlrev_b32_e32 v23, 16, v23
	v_mul_f32_e64 v19, |v18|, s79
	v_mul_f32_e32 v23, 0x3d800000, v23
	v_exp_f32_e32 v19, v19
	v_mul_f32_e32 v23, v21, v23
	v_rcp_f32_e32 v21, v21
	s_waitcnt lgkmcnt(0)
	v_lshlrev_b32_e32 v24, 16, v24
	v_add_f32_e32 v19, 1.0, v19
	v_log_f32_e32 v19, v19
	v_mul_f32_e32 v21, v21, v24
	v_cvt_pk_bf16_f32 v21, v21, s0
	ds_write_b16 v22, v21
	ds_read_u16 v22, v34 offset:15056
	v_min_f32_e32 v18, 0, v18
	v_fma_f32 v18, v18, s80, -v19
	v_fmamk_f32 v19, v52, 0x3d800000, v20
	v_exp_f32_e32 v20, v20
	v_cvt_pk_bf16_f32 v23, v23, s0
	v_add_u32_e32 v21, 0x142d0, v34
	ds_write_b16 v34, v23 offset:14528
	ds_read_u16 v23, v21
	s_waitcnt lgkmcnt(2)
	v_lshlrev_b32_e32 v22, 16, v22
	v_mul_f32_e32 v22, 0x3d800000, v22
	v_mul_f32_e32 v22, v20, v22
	v_rcp_f32_e32 v20, v20
	s_waitcnt lgkmcnt(0)
	v_lshlrev_b32_e32 v23, 16, v23
	v_fmamk_f32 v18, v18, 0x3d800000, v19
	v_exp_f32_e32 v19, v19
	v_mul_f32_e32 v20, v20, v23
	v_cvt_pk_bf16_f32 v20, v20, s0
	ds_write_b16 v21, v20
	ds_read_u16 v21, v34 offset:15584
	v_cvt_pk_bf16_f32 v22, v22, s0
	v_add_u32_e32 v20, 0x144e0, v34
	ds_write_b16 v34, v22 offset:15056
	ds_read_u16 v22, v20
	s_waitcnt lgkmcnt(2)
	v_lshlrev_b32_e32 v21, 16, v21
	v_mul_f32_e32 v21, 0x3d800000, v21
	v_mul_f32_e32 v21, v19, v21
	v_rcp_f32_e32 v19, v19
	s_waitcnt lgkmcnt(0)
	v_lshlrev_b32_e32 v22, 16, v22
	v_exp_f32_e32 v112, v18
	v_cvt_pk_bf16_f32 v21, v21, s0
	v_mul_f32_e32 v19, v19, v22
	v_cvt_pk_bf16_f32 v19, v19, s0
	ds_write_b16 v20, v19
	ds_read_u16 v20, v34 offset:16112
	v_add_u32_e32 v19, 0x146f0, v34
	ds_write_b16 v34, v21 offset:15584
	ds_read_u16 v21, v19
	s_addk_i32 s52, 0x2100
	s_waitcnt lgkmcnt(2)
	v_lshlrev_b32_e32 v20, 16, v20
	v_mul_f32_e32 v20, 0x3d800000, v20
	v_mul_f32_e32 v20, v112, v20
	v_cvt_pk_bf16_f32 v20, v20, s0
	ds_write_b16 v34, v20 offset:16112
	v_rcp_f32_e32 v20, v112
	s_waitcnt lgkmcnt(1)
	v_lshlrev_b32_e32 v21, 16, v21
	s_cmpk_eq_u32 s52, 0x8400
	v_mov_b32_e32 v33, v18
	v_mul_f32_e32 v20, v20, v21
	v_cvt_pk_bf16_f32 v20, v20, s0
	ds_write_b16 v19, v20
	s_cbranch_scc0 .LBB0_360
	s_branch .LBB0_353

; DI float bf2f(bf16_t b) { return __uint_as_float(((unsigned)b) << 16); }
; DI unsigned pk2(float lo, float hi) { f32x2 v = {lo, hi}; bfv2 b = __builtin_convertvector(v, bfv2); return __builtin_bit_cast(unsigned, b); }
; DI void prep_load(PrepIn& I, const Params& p, int j, int item, int tid) {
;     ...
;     { const int t = tid >> 3, sg = tid & 7; I.rr = *(const u32x2*)(H + (row0 + t) * HE + 8192 + sg * 4); }
;     const float* wgf = p.in[9]; const float* wgb = p.in[11]; const float* bgf = p.in[10]; const float* bgb = p.in[12];
;     const float* wg = (dir ? wgb : wgf) + (size_t)j * 16 * 1024 + h * 256 + kk;
; #pragma unroll
;     for (int i = 0; i < 16; ++i) I.w[i] = wg[i * 1024];
;     I.bias = (dir ? bgb : bgf)[j * 1024 + h * 256 + kk];
; #pragma unroll
;     for (int it = 0; it < 4; ++it) { const int idx = it * 512 + tid; const int t = idx >> 5, seg = idx & 31;
;         I.q[it] = *(const u32x4*)(H + (row0 + t) * HE + 2048 + h * 256 + seg * 8);
;         I.k[it] = *(const u32x4*)(H + (row0 + t) * HE + h * 256 + seg * 8);
;         I.v[it] = *(const u32x4*)(H + (row0 + t) * HE + 1024 + h * 256 + seg * 8); }
; DI void phase_prep(const Params& p, int j, unsigned char* lds) {
;     ...
;         ((float*)(p.ws + WS_DD))[(size_t)(item * 2 + dir) * 256 + kk] = dlast;
;         { const int nitem = item + (int)gridDim.x; prep_load(I, p, j, nitem < NCH * 4 ? nitem : item, tid); }
;         {
;             bf16_t* KHp = (bf16_t*)(p.ws + WS_KH) + (size_t)(item * 2 + dir) * 16384;
;             const int w8 = kk >> 5, r = kk & 31;
; #pragma unroll
;             for (int tg = 0; tg < 8; ++tg) {
;                 float val[8];
; #pragma unroll
;                 for (int i = 0; i < 8; ++i) val[i] = bf2f(kt[(dir * 64 + 8 * tg + i) * 264 + kk]) * dlast;
;                 u32x4 pk; pk.x = pk2(val[0], val[1]); pk.y = pk2(val[2], val[3]); pk.z = pk2(val[4], val[5]); pk.w = pk2(val[6], val[7]);
;                 const int s = tg >> 1, hh = tg & 1;
;                 *(u32x4*)(KHp + ((w8 * 4 + s) * 64 + hh * 32 + r) * 8) = pk;
.LBB0_1532:
	s_or_b64 exec, exec, s[56:57]
	s_lshl_b32 s58, s54, 1
	s_add_i32 s81, s54, s71
	s_cmpk_lt_i32 s81, 0x820
	s_cselect_b64 s[56:57], -1, 0
	s_and_b64 s[60:61], s[56:57], exec
	v_add_u32_e32 v116, s58, v1
	s_cselect_b32 s52, s81, s54
	v_ashrrev_i32_e32 v117, 31, v116
	s_ashr_i32 s60, s52, 2
	v_lshlrev_b64 v[18:19], 10, v[116:117]
	s_ashr_i32 s61, s60, 31
	v_lshl_add_u64 v[18:19], v[94:95], 0, v[18:19]
	s_lshl_b64 s[60:61], s[60:61], 6
	global_store_dword v[18:19], v112, off
	v_lshl_add_u64 v[18:19], s[60:61], 0, v[66:67]
	v_mov_b64_e32 v[38:39], s[50:51]
	v_mad_u64_u32 v[20:21], s[82:83], v18, s33, v[38:39]
	v_mad_i32_i24 v21, v19, s33, v21
	v_lshl_add_u64 v[18:19], v[20:21], 0, v[68:69]
	s_lshl_b32 s52, s52, 8
	v_add_co_u32_e32 v18, vcc, s62, v18
	s_and_b32 s55, s52, 0x300
	s_nop 0
	v_addc_co_u32_e32 v19, vcc, 0, v19, vcc
	s_lshl_b32 s52, s55, 2
	global_load_dwordx2 v[114:115], v[18:19], off
	v_lshl_add_u64 v[18:19], v[96:97], 0, s[52:53]
	v_add_co_u32_e32 v20, vcc, s64, v18
	s_lshl_b32 s52, s55, 1
	s_nop 0
	v_addc_co_u32_e32 v21, vcc, 0, v19, vcc
	v_add_co_u32_e32 v22, vcc, s62, v18
	v_mov_b32_e32 v101, v69
	s_nop 0
	v_addc_co_u32_e32 v23, vcc, 0, v19, vcc
	v_add_co_u32_e32 v24, vcc, s65, v18
	v_lshlrev_b64 v[116:117], 15, v[116:117]
	s_nop 0
	v_addc_co_u32_e32 v25, vcc, 0, v19, vcc
	v_add_co_u32_e32 v26, vcc, s66, v18
	s_ashr_i32 s59, s58, 31
	s_nop 0
	v_addc_co_u32_e32 v27, vcc, 0, v19, vcc
	global_load_dword v76, v[20:21], off offset:-4096
	global_load_dword v73, v[20:21], off
	global_load_dword v77, v[22:23], off offset:-4096
	global_load_dword v74, v[22:23], off
	global_load_dword v78, v[24:25], off offset:-4096
	global_load_dword v75, v[24:25], off
	global_load_dword v79, v[26:27], off offset:-4096
	global_load_dword v80, v[26:27], off
	v_add_co_u32_e32 v20, vcc, s67, v18
	s_nop 1
	v_addc_co_u32_e32 v21, vcc, 0, v19, vcc
	v_add_co_u32_e32 v22, vcc, s68, v18
	s_nop 1
	v_addc_co_u32_e32 v23, vcc, 0, v19, vcc
	v_add_co_u32_e32 v24, vcc, s69, v18
	s_nop 1
	v_addc_co_u32_e32 v25, vcc, 0, v19, vcc
	global_load_dword v88, v[20:21], off offset:-4096
	global_load_dword v81, v[20:21], off
	global_load_dword v89, v[22:23], off offset:-4096
	global_load_dword v86, v[22:23], off
	global_load_dword v92, v[24:25], off offset:-4096
	global_load_dword v87, v[24:25], off
	v_add_co_u32_e32 v20, vcc, s70, v18
	s_nop 1
	v_addc_co_u32_e32 v21, vcc, 0, v19, vcc
	global_load_dword v85, v[18:19], off
	global_load_dword v93, v[20:21], off
	v_or_b32_sdwa v18, v254, s55 dst_sel:DWORD dst_unused:UNUSED_PAD src0_sel:BYTE_0 src1_sel:DWORD
	v_lshlrev_b32_e32 v18, 2, v18
	v_mov_b32_e32 v19, v69
	v_lshl_add_u64 v[18:19], v[70:71], 0, v[18:19]
	v_add_co_u32_e32 v18, vcc, s63, v18
	s_nop 1
	v_addc_co_u32_e32 v19, vcc, 0, v19, vcc
	global_load_dword v123, v[18:19], off
	v_or_b32_e32 v18, s60, v72
	v_mad_u64_u32 v[18:19], s[82:83], v18, s33, v[38:39]
	v_mad_i32_i24 v19, s61, v83, v19
	v_lshl_add_u64 v[18:19], v[18:19], 0, s[52:53]
	v_lshl_add_u64 v[22:23], v[18:19], 0, v[100:101]
	v_add_co_u32_e32 v24, vcc, s63, v22
	global_load_dwordx4 v[18:21], v[22:23], off
	global_load_dwordx4 v[50:53], v[22:23], off offset:2048
	v_or_b32_e32 v22, s60, v82
	v_addc_co_u32_e32 v25, vcc, 0, v23, vcc
	v_mad_u64_u32 v[22:23], s[82:83], v22, s33, v[38:39]
	v_mad_i32_i24 v23, s61, v83, v23
	v_lshl_add_u64 v[22:23], v[22:23], 0, s[52:53]
	v_lshl_add_u64 v[34:35], v[22:23], 0, v[100:101]
	v_add_co_u32_e32 v30, vcc, s63, v34
	s_nop 1
	v_addc_co_u32_e32 v31, vcc, 0, v35, vcc
	global_load_dwordx4 v[22:25], v[24:25], off
	s_nop 0
	global_load_dwordx4 v[26:29], v[34:35], off
	s_nop 0
	global_load_dwordx4 v[30:33], v[30:31], off
	s_nop 0
	global_load_dwordx4 v[54:57], v[34:35], off offset:2048
	v_or_b32_e32 v34, s60, v84
	v_mad_u64_u32 v[34:35], s[82:83], v34, s33, v[38:39]
	v_mad_i32_i24 v35, s61, v83, v35
	v_lshl_add_u64 v[34:35], v[34:35], 0, s[52:53]
	v_lshl_add_u64 v[40:41], v[34:35], 0, v[100:101]
	v_add_co_u32_e32 v42, vcc, s63, v40
	global_load_dwordx4 v[34:37], v[40:41], off
	global_load_dwordx4 v[58:61], v[40:41], off offset:2048
	v_addc_co_u32_e32 v43, vcc, 0, v41, vcc
	v_lshl_add_u64 v[40:41], s[60:61], 0, v[90:91]
	v_mad_u64_u32 v[38:39], s[60:61], v40, s33, v[38:39]
	v_mad_i32_i24 v39, v41, s33, v39
	v_lshl_add_u64 v[38:39], v[38:39], 0, s[52:53]
	v_lshl_add_u64 v[62:63], v[38:39], 0, v[100:101]
	v_add_co_u32_e32 v46, vcc, s63, v62
	s_lshl_b64 s[60:61], s[58:59], 15
	s_nop 0
	v_addc_co_u32_e32 v47, vcc, 0, v63, vcc
	global_load_dwordx4 v[38:41], v[42:43], off
	s_nop 0
	global_load_dwordx4 v[42:45], v[62:63], off
	s_nop 0
	global_load_dwordx4 v[46:49], v[46:47], off
	s_nop 0
	global_load_dwordx4 v[62:65], v[62:63], off offset:2048
	ds_read_u16 v101, v134
	ds_read_u16 v103, v134 offset:528
	ds_read_u16 v105, v134 offset:1056
	ds_read_u16 v107, v134 offset:1584
	ds_read_u16 v109, v134 offset:2112
	ds_read_u16 v111, v134 offset:2640
	ds_read_u16 v162, v134 offset:3168
	s_waitcnt lgkmcnt(4)
	v_lshlrev_b32_e32 v156, 16, v105
	s_waitcnt lgkmcnt(3)
	v_lshlrev_b32_e32 v157, 16, v107
	v_lshlrev_b32_e32 v119, 16, v103
	ds_read_u16 v103, v134 offset:33264
	v_lshlrev_b32_e32 v118, 16, v101
	v_mul_f32_e64 v158, v112, v156
	v_mul_f32_e64 v159, v112, v157
	s_waitcnt lgkmcnt(2)
	v_lshlrev_b32_e32 v157, 16, v111
	v_lshlrev_b32_e32 v156, 16, v109
	ds_read_u16 v101, v134 offset:3696
	ds_read_u16 v105, v134 offset:4224
	ds_read_u16 v107, v134 offset:4752
	ds_read_u16 v109, v134 offset:5280
	ds_read_u16 v111, v134 offset:5808
	ds_read_u16 v164, v134 offset:6336
	ds_read_u16 v165, v134 offset:6864
	ds_read_u16 v166, v134 offset:7392
	v_mul_f32_e64 v160, v112, v156
	v_mul_f32_e64 v161, v112, v157
	s_waitcnt lgkmcnt(7)
; DI float bf2f(bf16_t b) { return __uint_as_float(((unsigned)b) << 16); }
; DI unsigned pk2(float lo, float hi) { f32x2 v = {lo, hi}; bfv2 b = __builtin_convertvector(v, bfv2); return __builtin_bit_cast(unsigned, b); }
; DI void phase_prep(const Params& p, int j, unsigned char* lds) {
;     ...
;             for (int tg = 0; tg < 8; ++tg) {
;                 float val[8];
; #pragma unroll
;                 for (int i = 0; i < 8; ++i) val[i] = bf2f(kt[(dir * 64 + 8 * tg + i) * 264 + kk]) * dlast;
;                 u32x4 pk; pk.x = pk2(val[0], val[1]); pk.y = pk2(val[2], val[3]); pk.z = pk2(val[4], val[5]); pk.w = pk2(val[6], val[7]);
;                 const int s = tg >> 1, hh = tg & 1;
;                 *(u32x4*)(KHp + ((w8 * 4 + s) * 64 + hh * 32 + r) * 8) = pk;
	v_lshlrev_b32_e32 v157, 16, v101
	v_lshlrev_b32_e32 v156, 16, v162
	v_mul_f32_e64 v118, v112, v118
	v_mul_f32_e64 v119, v112, v119
	v_mul_f32_e64 v162, v112, v156
	v_mul_f32_e64 v163, v112, v157
	v_cvt_pk_bf16_f32 v156, v118, v119
	v_cvt_pk_bf16_f32 v157, v158, v159
	v_cvt_pk_bf16_f32 v158, v160, v161
	v_cvt_pk_bf16_f32 v159, v162, v163
	v_lshl_add_u64 v[160:161], v[98:99], 0, v[116:117]
	global_store_dwordx4 v[160:161], v[156:159], off
	s_waitcnt lgkmcnt(5)
	v_lshlrev_b32_e32 v117, 16, v107
	v_lshlrev_b32_e32 v116, 16, v105
	s_waitcnt lgkmcnt(3)
	v_lshlrev_b32_e32 v119, 16, v111
	v_lshlrev_b32_e32 v118, 16, v109
	s_waitcnt lgkmcnt(1)
	v_lshlrev_b32_e32 v157, 16, v165
	v_lshlrev_b32_e32 v156, 16, v164
	ds_read_u16 v101, v134 offset:7920
	ds_read_u16 v105, v134 offset:8448
	ds_read_u16 v107, v134 offset:8976
	ds_read_u16 v109, v134 offset:9504
	ds_read_u16 v111, v134 offset:10032
	ds_read_u16 v162, v134 offset:10560
	ds_read_u16 v163, v134 offset:11088
	ds_read_u16 v164, v134 offset:11616
	s_waitcnt lgkmcnt(7)
	v_lshlrev_b32_e32 v159, 16, v101
	v_lshlrev_b32_e32 v158, 16, v166
	v_mul_f32_e64 v116, v112, v116
	v_mul_f32_e64 v117, v112, v117
	v_mul_f32_e64 v118, v112, v118
	v_mul_f32_e64 v119, v112, v119
	v_mul_f32_e64 v156, v112, v156
	v_mul_f32_e64 v157, v112, v157
	v_mul_f32_e64 v158, v112, v158
	v_mul_f32_e64 v159, v112, v159
	v_cvt_pk_bf16_f32 v116, v116, v117
	v_cvt_pk_bf16_f32 v117, v118, v119
	v_cvt_pk_bf16_f32 v118, v156, v157
	v_cvt_pk_bf16_f32 v119, v158, v159
	global_store_dwordx4 v[160:161], v[116:119], off offset:512
	s_waitcnt lgkmcnt(1)
	v_lshlrev_b32_e32 v157, 16, v163
	v_lshlrev_b32_e32 v156, 16, v162
	v_lshlrev_b32_e32 v117, 16, v107
	v_lshlrev_b32_e32 v116, 16, v105
	v_lshlrev_b32_e32 v119, 16, v111
	v_lshlrev_b32_e32 v118, 16, v109
	ds_read_u16 v101, v134 offset:12144
	ds_read_u16 v105, v134 offset:12672
	ds_read_u16 v107, v134 offset:13200
	ds_read_u16 v109, v134 offset:13728
	ds_read_u16 v111, v134 offset:14256
	ds_read_u16 v162, v134 offset:14784
	ds_read_u16 v163, v134 offset:15312
	ds_read_u16 v165, v134 offset:15840
	s_waitcnt lgkmcnt(7)
	v_lshlrev_b32_e32 v159, 16, v101
	v_lshlrev_b32_e32 v158, 16, v164
	v_mul_f32_e64 v116, v112, v116
	v_mul_f32_e64 v117, v112, v117
	v_mul_f32_e64 v118, v112, v118
	v_mul_f32_e64 v119, v112, v119
	v_mul_f32_e64 v156, v112, v156
	v_mul_f32_e64 v157, v112, v157
	v_mul_f32_e64 v158, v112, v158
	v_mul_f32_e64 v159, v112, v159
	v_cvt_pk_bf16_f32 v116, v116, v117
	v_cvt_pk_bf16_f32 v117, v118, v119
	v_cvt_pk_bf16_f32 v118, v156, v157
	v_cvt_pk_bf16_f32 v119, v158, v159
	global_store_dwordx4 v[160:161], v[116:119], off offset:1024
	s_waitcnt lgkmcnt(1)
	v_lshlrev_b32_e32 v157, 16, v163
	v_lshlrev_b32_e32 v156, 16, v162
	v_lshlrev_b32_e32 v117, 16, v107
	v_lshlrev_b32_e32 v116, 16, v105
	v_lshlrev_b32_e32 v119, 16, v111
	v_lshlrev_b32_e32 v118, 16, v109
	ds_read_u16 v101, v134 offset:16368
	ds_read_u16 v105, v134 offset:16896
	ds_read_u16 v107, v134 offset:17424
	ds_read_u16 v109, v134 offset:17952
	ds_read_u16 v111, v134 offset:18480
	ds_read_u16 v162, v134 offset:19008
	ds_read_u16 v163, v134 offset:19536
	ds_read_u16 v164, v134 offset:20064
	s_waitcnt lgkmcnt(7)
	v_lshlrev_b32_e32 v159, 16, v101
	v_lshlrev_b32_e32 v158, 16, v165
	v_mul_f32_e64 v116, v112, v116
	v_mul_f32_e64 v117, v112, v117
	v_mul_f32_e64 v118, v112, v118
	v_mul_f32_e64 v119, v112, v119
	v_mul_f32_e64 v156, v112, v156
	v_mul_f32_e64 v157, v112, v157
	v_mul_f32_e64 v158, v112, v158
	v_mul_f32_e64 v159, v112, v159
	v_cvt_pk_bf16_f32 v116, v116, v117
	v_cvt_pk_bf16_f32 v117, v118, v119
	v_cvt_pk_bf16_f32 v118, v156, v157
	v_cvt_pk_bf16_f32 v119, v158, v159
	global_store_dwordx4 v[160:161], v[116:119], off offset:1536
	s_waitcnt lgkmcnt(1)
	v_lshlrev_b32_e32 v157, 16, v163
	v_lshlrev_b32_e32 v156, 16, v162
	v_lshlrev_b32_e32 v117, 16, v107
	v_lshlrev_b32_e32 v116, 16, v105
	v_lshlrev_b32_e32 v119, 16, v111
	v_lshlrev_b32_e32 v118, 16, v109
	ds_read_u16 v101, v134 offset:20592
	ds_read_u16 v105, v134 offset:21120
	ds_read_u16 v107, v134 offset:21648
	ds_read_u16 v109, v134 offset:22176
	ds_read_u16 v111, v134 offset:22704
	ds_read_u16 v162, v134 offset:23232
	ds_read_u16 v163, v134 offset:23760
	ds_read_u16 v165, v134 offset:24288
	s_waitcnt lgkmcnt(7)
	v_lshlrev_b32_e32 v159, 16, v101
	v_lshlrev_b32_e32 v158, 16, v164
	v_mul_f32_e64 v116, v112, v116
	v_mul_f32_e64 v117, v112, v117
	v_mul_f32_e64 v118, v112, v118
	v_mul_f32_e64 v119, v112, v119
	v_mul_f32_e64 v156, v112, v156
	v_mul_f32_e64 v157, v112, v157
	v_mul_f32_e64 v158, v112, v158
	v_mul_f32_e64 v159, v112, v159
	v_cvt_pk_bf16_f32 v116, v116, v117
	v_cvt_pk_bf16_f32 v117, v118, v119
	v_cvt_pk_bf16_f32 v118, v156, v157
	v_cvt_pk_bf16_f32 v119, v158, v159
	global_store_dwordx4 v[160:161], v[116:119], off offset:2048
	s_waitcnt lgkmcnt(1)
	v_lshlrev_b32_e32 v157, 16, v163
	v_lshlrev_b32_e32 v156, 16, v162
	v_lshlrev_b32_e32 v117, 16, v107
	v_lshlrev_b32_e32 v116, 16, v105
	v_lshlrev_b32_e32 v119, 16, v111
	v_lshlrev_b32_e32 v118, 16, v109
	ds_read_u16 v101, v134 offset:24816
	ds_read_u16 v105, v134 offset:25344
	ds_read_u16 v107, v134 offset:25872
	ds_read_u16 v109, v134 offset:26400
	ds_read_u16 v111, v134 offset:26928
	ds_read_u16 v162, v134 offset:27456
	ds_read_u16 v163, v134 offset:27984
	ds_read_u16 v164, v134 offset:28512
	s_waitcnt lgkmcnt(7)
	v_lshlrev_b32_e32 v159, 16, v101
	v_lshlrev_b32_e32 v158, 16, v165
	v_mul_f32_e64 v116, v112, v116
	v_mul_f32_e64 v117, v112, v117
	v_mul_f32_e64 v118, v112, v118
	v_mul_f32_e64 v119, v112, v119
	v_mul_f32_e64 v156, v112, v156
	v_mul_f32_e64 v157, v112, v157
	v_mul_f32_e64 v158, v112, v158
	v_mul_f32_e64 v159, v112, v159
	v_cvt_pk_bf16_f32 v116, v116, v117
	v_cvt_pk_bf16_f32 v117, v118, v119
	v_cvt_pk_bf16_f32 v118, v156, v157
	v_cvt_pk_bf16_f32 v119, v158, v159
	global_store_dwordx4 v[160:161], v[116:119], off offset:2560
	s_waitcnt lgkmcnt(1)
; DI float bf2f(bf16_t b) { return __uint_as_float(((unsigned)b) << 16); }
; DI unsigned pk2(float lo, float hi) { f32x2 v = {lo, hi}; bfv2 b = __builtin_convertvector(v, bfv2); return __builtin_bit_cast(unsigned, b); }
; DI void phase_prep(const Params& p, int j, unsigned char* lds) {
;     ...
;             for (int tg = 0; tg < 8; ++tg) {
;                 float val[8];
; #pragma unroll
;                 for (int i = 0; i < 8; ++i) val[i] = bf2f(kt[(dir * 64 + 8 * tg + i) * 264 + kk]) * dlast;
;                 u32x4 pk; pk.x = pk2(val[0], val[1]); pk.y = pk2(val[2], val[3]); pk.z = pk2(val[4], val[5]); pk.w = pk2(val[6], val[7]);
;                 const int s = tg >> 1, hh = tg & 1;
;                 *(u32x4*)(KHp + ((w8 * 4 + s) * 64 + hh * 32 + r) * 8) = pk;
;             }
;         }
;         __syncthreads();
;         {
;             bf16_t* QTp = (bf16_t*)(p.ws + WS_U) + (size_t)(item * 2) * 16384;
; #pragma unroll
;             for (int it = 0; it < 8; ++it) {
;                 const int idx = it * 512 + tid; const int d2 = idx >> 11, f = (idx >> 6) & 31, ln = idx & 63;
;                 const int w8 = f >> 2, mb = (f >> 1) & 1, s = f & 1, rr = ln & 31, hh = ln >> 5;
;                 const bf16_t* sp = qt + (d2 * 64 + 32 * mb + rr) * 264 + 32 * w8 + 16 * s + 4 * hh;
;                 const u32x2 lo = *(const u32x2*)sp, hi = *(const u32x2*)(sp + 8);
;                 u32x4 o; o.x = lo.x; o.y = lo.y; o.z = hi.x; o.w = hi.y;
;                 *(u32x4*)(QTp + (size_t)d2 * 16384 + (f * 64 + ln) * 8) = o;
;             }
;         }
;         float amask[4][4];
;         {
;             const int d2 = wave >> 2, wd = wave & 3, fr = lane & 15, fq = lane >> 4;
;             f32x4 acc[4];
; #pragma unroll
;             for (int nb = 0; nb < 4; ++nb) acc[nb] = (f32x4){0.f, 0.f, 0.f, 0.f};
;             const bf16_t* qb = qt + (d2 * 64 + 16 * wd + fr) * 264 + 8 * fq;
;             const bf16_t* kb = kt + (d2 * 64 + fr) * 264 + 8 * fq;
; #pragma unroll
;             for (int ks = 0; ks < 8; ++ks) {
;                 const bf16x8 a = *(const bf16x8*)(qb + 32 * ks);
; #pragma unroll
;                 for (int nb = 0; nb < 4; ++nb) { const bf16x8 b = *(const bf16x8*)(kb + nb * 16 * 264 + 32 * ks); acc[nb] = __builtin_amdgcn_mfma_f32_16x16x32_bf16(a, b, acc[nb], 0, 0, 0); }
	v_lshlrev_b32_e32 v157, 16, v163
	v_lshlrev_b32_e32 v156, 16, v162
	v_lshlrev_b32_e32 v117, 16, v107
	v_lshlrev_b32_e32 v116, 16, v105
	v_lshlrev_b32_e32 v119, 16, v111
	v_lshlrev_b32_e32 v118, 16, v109
	ds_read_u16 v101, v134 offset:29040
	ds_read_u16 v105, v134 offset:29568
	ds_read_u16 v107, v134 offset:30096
	ds_read_u16 v109, v134 offset:30624
	ds_read_u16 v111, v134 offset:31152
	ds_read_u16 v162, v134 offset:31680
	ds_read_u16 v163, v134 offset:32208
	ds_read_u16 v165, v134 offset:32736
	s_waitcnt lgkmcnt(7)
	v_lshlrev_b32_e32 v159, 16, v101
	v_lshlrev_b32_e32 v158, 16, v164
	v_mul_f32_e64 v116, v112, v116
	v_mul_f32_e64 v117, v112, v117
	v_mul_f32_e64 v118, v112, v118
	v_mul_f32_e64 v119, v112, v119
	v_mul_f32_e64 v156, v112, v156
	v_mul_f32_e64 v157, v112, v157
	v_mul_f32_e64 v158, v112, v158
	v_mul_f32_e64 v159, v112, v159
	v_cvt_pk_bf16_f32 v116, v116, v117
	v_cvt_pk_bf16_f32 v117, v118, v119
	v_cvt_pk_bf16_f32 v118, v156, v157
	v_cvt_pk_bf16_f32 v119, v158, v159
	global_store_dwordx4 v[160:161], v[116:119], off offset:3072
	s_waitcnt lgkmcnt(1)
	v_lshlrev_b32_e32 v157, 16, v163
	v_lshlrev_b32_e32 v156, 16, v162
	v_lshlrev_b32_e32 v117, 16, v107
	v_lshlrev_b32_e32 v116, 16, v105
	v_lshlrev_b32_e32 v119, 16, v111
	v_lshlrev_b32_e32 v118, 16, v109
	v_lshlrev_b32_e32 v159, 16, v103
	s_waitcnt lgkmcnt(0)
	v_lshlrev_b32_e32 v158, 16, v165
	v_mul_f32_e64 v116, v112, v116
	v_mul_f32_e64 v117, v112, v117
	v_mul_f32_e64 v118, v112, v118
	v_mul_f32_e64 v119, v112, v119
	v_mul_f32_e64 v156, v112, v156
	v_mul_f32_e64 v157, v112, v157
	v_mul_f32_e64 v158, v112, v158
	v_mul_f32_e64 v159, v112, v159
	v_cvt_pk_bf16_f32 v116, v116, v117
	v_cvt_pk_bf16_f32 v117, v118, v119
	v_cvt_pk_bf16_f32 v118, v156, v157
	v_cvt_pk_bf16_f32 v119, v158, v159
	global_store_dwordx4 v[160:161], v[116:119], off offset:3584
	s_barrier
	ds_read_b128 v[116:119], v121 offset:8192
	ds_read_b128 v[156:159], v122
	ds_read_b128 v[160:163], v121 offset:8256
	ds_read_b128 v[164:167], v122 offset:64
	ds_read_b128 v[168:171], v122 offset:8448
	ds_read_b128 v[172:175], v122 offset:8512
	s_waitcnt lgkmcnt(4)
	v_mfma_f32_16x16x32_bf16 v[156:159], v[116:119], v[156:159], 0
	ds_read_b128 v[176:179], v122 offset:16896
	ds_read_b128 v[180:183], v122 offset:16960
	ds_read_b128 v[184:187], v122 offset:25344
	ds_read_b128 v[188:191], v122 offset:25408
	v_add_u32_e32 v101, 0x2000, v135
	s_waitcnt lgkmcnt(5)
	v_mfma_f32_16x16x32_bf16 v[168:171], v[116:119], v[168:171], 0
	s_add_u32 s60, s72, s60
	s_addc_u32 s61, s73, s61
	v_mov_b32_e32 v105, v69
	v_mfma_f32_16x16x32_bf16 v[156:159], v[160:163], v[164:167], v[156:159]
	v_mov_b32_e32 v107, v69
	s_add_u32 s82, s60, 0x8000
	s_addc_u32 s83, s61, 0
	s_waitcnt lgkmcnt(4)
	v_mfma_f32_16x16x32_bf16 v[164:167], v[160:163], v[172:175], v[168:171]
	ds_read_b128 v[172:175], v121 offset:8320
	v_mov_b32_e32 v109, v69
	v_mov_b32_e32 v111, v69
	s_waitcnt lgkmcnt(4)
	v_mfma_f32_16x16x32_bf16 v[176:179], v[116:119], v[176:179], 0
	s_lshl_b64 s[58:59], s[58:59], 13
	s_add_u32 s58, s74, s58
	v_mov_b32_e32 v103, v69
	s_waitcnt lgkmcnt(2)
	v_mfma_f32_16x16x32_bf16 v[116:119], v[116:119], v[184:187], 0
	s_addc_u32 s59, s75, s59
	s_ashr_i32 s55, s54, 31
	s_lshl_b64 s[54:55], s[54:55], 15
	v_mfma_f32_16x16x32_bf16 v[168:171], v[160:163], v[180:183], v[176:179]
	s_add_u32 s54, s76, s54
	s_addc_u32 s55, s77, s55
	s_waitcnt lgkmcnt(1)
	v_mfma_f32_16x16x32_bf16 v[116:119], v[160:163], v[188:191], v[116:119]
	ds_read_b128 v[160:163], v122 offset:128
	ds_read_b128 v[176:179], v121 offset:8384
	ds_read_b128 v[180:183], v122 offset:192
	s_waitcnt lgkmcnt(2)
	v_mfma_f32_16x16x32_bf16 v[156:159], v[172:175], v[160:163], v[156:159]
	ds_read_b128 v[160:163], v122 offset:8576
	ds_read_b128 v[184:187], v122 offset:8640
	s_waitcnt lgkmcnt(1)
	v_mfma_f32_16x16x32_bf16 v[160:163], v[172:175], v[160:163], v[164:167]
	s_nop 2
	ds_read_b128 v[164:167], v122 offset:17024
	ds_read_b128 v[188:191], v122 offset:17088
	s_waitcnt lgkmcnt(1)
	v_mfma_f32_16x16x32_bf16 v[164:167], v[172:175], v[164:167], v[168:171]
	s_nop 2
	ds_read_b128 v[168:171], v122 offset:25472
	ds_read_b128 v[192:195], v122 offset:25536
	s_waitcnt lgkmcnt(1)
	v_mfma_f32_16x16x32_bf16 v[116:119], v[172:175], v[168:171], v[116:119]
	ds_read_b128 v[168:171], v121 offset:8448
	ds_read_b128 v[172:175], v122 offset:256
	v_mfma_f32_16x16x32_bf16 v[156:159], v[176:179], v[180:183], v[156:159]
	v_mfma_f32_16x16x32_bf16 v[160:163], v[176:179], v[184:187], v[160:163]
	v_mfma_f32_16x16x32_bf16 v[164:167], v[176:179], v[188:191], v[164:167]
	s_waitcnt lgkmcnt(2)
	v_mfma_f32_16x16x32_bf16 v[116:119], v[176:179], v[192:195], v[116:119]
	ds_read_b128 v[176:179], v122 offset:8704
	ds_read_b128 v[180:183], v121 offset:8512
	ds_read_b128 v[184:187], v122 offset:320
	s_waitcnt lgkmcnt(3)
	v_mfma_f32_16x16x32_bf16 v[156:159], v[168:171], v[172:175], v[156:159]
	ds_read_b128 v[172:175], v122 offset:17152
	ds_read_b128 v[188:191], v122 offset:8768
	s_waitcnt lgkmcnt(4)
	v_mfma_f32_16x16x32_bf16 v[160:163], v[168:171], v[176:179], v[160:163]
	ds_read_b128 v[176:179], v122 offset:25600
	ds_read_b128 v[192:195], v122 offset:17216
	s_waitcnt lgkmcnt(3)
	v_mfma_f32_16x16x32_bf16 v[164:167], v[168:171], v[172:175], v[164:167]
	ds_read2_b64 v[172:175], v101 offset1:2
	ds_read2_b64 v[196:199], v150 offset1:2
	ds_read_b128 v[200:203], v122 offset:25664
	v_add_u32_e32 v101, 0xa000, v135
	s_waitcnt lgkmcnt(2)
	global_store_dwordx4 v102, v[172:175], s[60:61]
	v_mfma_f32_16x16x32_bf16 v[116:119], v[168:171], v[176:179], v[116:119]
	ds_read2_b64 v[168:171], v151 offset1:2
	s_waitcnt lgkmcnt(2)
	global_store_dwordx4 v140, v[196:199], s[60:61]
	s_waitcnt lgkmcnt(0)
; DI void phase_prep(const Params& p, int j, unsigned char* lds) {
;     ...
;             bf16_t* QTp = (bf16_t*)(p.ws + WS_U) + (size_t)(item * 2) * 16384;
; #pragma unroll
;             for (int it = 0; it < 8; ++it) {
;                 const int idx = it * 512 + tid; const int d2 = idx >> 11, f = (idx >> 6) & 31, ln = idx & 63;
;                 const int w8 = f >> 2, mb = (f >> 1) & 1, s = f & 1, rr = ln & 31, hh = ln >> 5;
;                 const bf16_t* sp = qt + (d2 * 64 + 32 * mb + rr) * 264 + 32 * w8 + 16 * s + 4 * hh;
;                 const u32x2 lo = *(const u32x2*)sp, hi = *(const u32x2*)(sp + 8);
;                 u32x4 o; o.x = lo.x; o.y = lo.y; o.z = hi.x; o.w = hi.y;
;                 *(u32x4*)(QTp + (size_t)d2 * 16384 + (f * 64 + ln) * 8) = o;
;             }
;         }
;         float amask[4][4];
;         {
;             const int d2 = wave >> 2, wd = wave & 3, fr = lane & 15, fq = lane >> 4;
;             f32x4 acc[4];
; #pragma unroll
;             for (int nb = 0; nb < 4; ++nb) acc[nb] = (f32x4){0.f, 0.f, 0.f, 0.f};
;             const bf16_t* qb = qt + (d2 * 64 + 16 * wd + fr) * 264 + 8 * fq;
;             const bf16_t* kb = kt + (d2 * 64 + fr) * 264 + 8 * fq;
; #pragma unroll
;             for (int ks = 0; ks < 8; ++ks) {
;                 const bf16x8 a = *(const bf16x8*)(qb + 32 * ks);
; #pragma unroll
;                 for (int nb = 0; nb < 4; ++nb) { const bf16x8 b = *(const bf16x8*)(kb + nb * 16 * 264 + 32 * ks); acc[nb] = __builtin_amdgcn_mfma_f32_16x16x32_bf16(a, b, acc[nb], 0, 0, 0); }
;             }
; #pragma unroll
;             for (int nb = 0; nb < 4; ++nb)
; #pragma unroll
;                 for (int jx = 0; jx < 4; ++jx) {
;                     const int i = 16 * wd + 4 * fq + jx, jt = 16 * nb + fr;
;                     const bool keep = d2 ? (jt >= i) : (jt <= i);
;                     amask[nb][jx] = keep ? acc[nb][jx] : 0.f;
	global_store_dwordx4 v141, v[168:171], s[60:61]
	ds_read_b128 v[172:175], v121 offset:8576
	ds_read2_b64 v[168:171], v152 offset1:2
	v_lshl_add_u64 v[176:177], s[60:61], 0, v[104:105]
	v_mfma_f32_16x16x32_bf16 v[164:167], v[180:183], v[192:195], v[164:167]
	v_lshl_add_u64 v[192:193], v[176:177], 0, v[106:107]
	ds_read_b128 v[176:179], v122 offset:384
	v_mfma_f32_16x16x32_bf16 v[156:159], v[180:183], v[184:187], v[156:159]
	v_mfma_f32_16x16x32_bf16 v[160:163], v[180:183], v[188:191], v[160:163]
	v_mfma_f32_16x16x32_bf16 v[116:119], v[180:183], v[200:203], v[116:119]
	ds_read_b128 v[180:183], v122 offset:8832
	ds_read_b128 v[184:187], v121 offset:8640
	ds_read_b128 v[188:191], v122 offset:448
	s_waitcnt lgkmcnt(4)
	global_store_dwordx4 v[192:193], v[168:171], off
	s_waitcnt lgkmcnt(3)
	v_mfma_f32_16x16x32_bf16 v[156:159], v[172:175], v[176:179], v[156:159]
	ds_read_b128 v[168:171], v122 offset:17280
	ds_read_b128 v[176:179], v122 offset:8896
	s_waitcnt lgkmcnt(4)
	v_mfma_f32_16x16x32_bf16 v[160:163], v[172:175], v[180:183], v[160:163]
	ds_read_b128 v[180:183], v122 offset:25728
	ds_read_b128 v[192:195], v122 offset:17344
	ds_read_b128 v[196:199], v122 offset:25792
	s_waitcnt lgkmcnt(4)
	v_mfma_f32_16x16x32_bf16 v[164:167], v[172:175], v[168:171], v[164:167]
	ds_read2_b64 v[168:171], v101 offset0:128 offset1:130
	s_waitcnt lgkmcnt(3)
	v_mfma_f32_16x16x32_bf16 v[116:119], v[172:175], v[180:183], v[116:119]
	ds_read2_b64 v[172:175], v153 offset0:128 offset1:130
	ds_read2_b64 v[180:183], v154 offset0:128 offset1:130
	s_waitcnt lgkmcnt(2)
	global_store_dwordx4 v102, v[168:171], s[82:83]
	s_waitcnt lgkmcnt(1)
	global_store_dwordx4 v142, v[172:175], s[82:83]
	s_waitcnt lgkmcnt(0)
	global_store_dwordx4 v143, v[180:183], s[82:83]
	v_mfma_f32_16x16x32_bf16 v[156:159], v[184:187], v[188:191], v[156:159]
	ds_read2_b64 v[168:171], v155 offset1:2
	v_lshl_add_u64 v[172:173], s[60:61], 0, v[108:109]
	v_lshl_add_u64 v[172:173], v[172:173], 0, v[110:111]
	v_mfma_f32_16x16x32_bf16 v[160:163], v[184:187], v[176:179], v[160:163]
	s_waitcnt lgkmcnt(0)
	global_store_dwordx4 v[172:173], v[168:171], off
	s_nop 1
	v_cvt_pk_bf16_f32 v101, v156, s0
	v_mfma_f32_16x16x32_bf16 v[164:167], v[184:187], v[192:195], v[164:167]
	v_cvt_pk_bf16_f32 v105, v157, s0
	v_cvt_pk_bf16_f32 v107, v158, s0
	v_cvt_pk_bf16_f32 v109, v159, s0
	v_mfma_f32_16x16x32_bf16 v[116:119], v[184:187], v[196:199], v[116:119]
	v_cvt_pk_bf16_f32 v111, v160, s0
	v_cvt_pk_bf16_f32 v112, v161, s0
	v_cvt_pk_bf16_f32 v156, v162, s0
	v_cvt_pk_bf16_f32 v157, v163, s0
	v_cvt_pk_bf16_f32 v158, v164, s0
	v_cvt_pk_bf16_f32 v159, v165, s0
	v_cvt_pk_bf16_f32 v160, v166, s0
	v_cvt_pk_bf16_f32 v161, v167, s0
	v_cvt_pk_bf16_f32 v116, v116, s0
	v_cvt_pk_bf16_f32 v117, v117, s0
	v_cvt_pk_bf16_f32 v118, v118, s0
	v_cvt_pk_bf16_f32 v119, v119, s0
	v_cndmask_b32_e64 v101, 0, v101, s[6:7]
	v_cndmask_b32_e64 v105, 0, v105, s[8:9]
	v_cndmask_b32_e64 v107, 0, v107, s[10:11]
	v_cndmask_b32_e64 v109, 0, v109, s[12:13]
	v_cndmask_b32_e64 v111, 0, v111, s[14:15]
	v_cndmask_b32_e64 v112, 0, v112, s[16:17]
	v_cndmask_b32_e64 v156, 0, v156, s[18:19]
	v_cndmask_b32_e64 v157, 0, v157, s[20:21]
	v_cndmask_b32_e64 v158, 0, v158, s[22:23]
	v_cndmask_b32_e64 v159, 0, v159, s[24:25]
	v_cndmask_b32_e64 v160, 0, v160, s[26:27]
	v_cndmask_b32_e64 v161, 0, v161, s[28:29]
	v_cndmask_b32_e64 v116, 0, v116, s[30:31]
	v_cndmask_b32_e64 v117, 0, v117, s[34:35]
	v_cndmask_b32_e64 v118, 0, v118, s[36:37]
	v_cndmask_b32_e64 v119, 0, v119, s[38:39]
	s_barrier
; DI bf16_t f2bf(float f) { return (bf16_t)(pk2(f, 0.f) & 0xffffu); }
; DI void phase_prep(const Params& p, int j, unsigned char* lds) {
;     ...
;         __syncthreads();
;         {
; #pragma unroll
;             for (int it = 0; it < 4; ++it) { const int idx = it * 512 + tid; const int t = idx >> 5, seg = idx & 31; *(u32x4*)(qt + t * 264 + seg * 8) = vcur[it]; }
;         }
;         {
;             const int d2 = wave >> 2, wd = wave & 3, fr = lane & 15, fq = lane >> 4;
; #pragma unroll
;             for (int nb = 0; nb < 4; ++nb)
; #pragma unroll
;                 for (int jx = 0; jx < 4; ++jx) {
;                     const int i = 16 * wd + 4 * fq + jx, jt = 16 * nb + fr;
;                     const int mb = i >> 5, r = i & 31, hh = (jt >> 3) & 1, jj = jt & 7;
;                     kt[d2 * 4096 + ((nb * 2 + mb) * 64 + hh * 32 + r) * 8 + jj] = f2bf(amask[nb][jx]);
;                 }
;         }
;         __syncthreads();
;         {
;             bf16_t* AMp = (bf16_t*)(p.ws + WS_AM) + (size_t)(item * 2) * 4096;
;             *(u32x4*)(AMp + tid * 8) = *(const u32x4*)(kt + tid * 8);
;             *(u32x4*)(AMp + 4096 + tid * 8) = *(const u32x4*)(kt + 4096 + tid * 8);
;         }
;         {
;             bf16_t* VTp = (bf16_t*)(p.ws + WS_VT) + (size_t)item * 16384;
; #pragma unroll
;             for (int it = 0; it < 4; ++it) {
;                 const int idx = it * 512 + tid; const int f = idx >> 6, ln = idx & 63; const int sl = f >> 2, s = f & 3, rr = ln & 31, hh = ln >> 5;
;                 const bf16_t* sp = qt + (16 * s + 8 * hh) * 264 + 32 * sl + rr;
;                 unsigned e[8];
; #pragma unroll
;                 for (int jj = 0; jj < 8; ++jj) e[jj] = sp[jj * 264];
;                 u32x4 o; o.x = e[0] | (e[1] << 16); o.y = e[2] | (e[3] << 16); o.z = e[4] | (e[5] << 16); o.w = e[6] | (e[7] << 16);
;                 *(u32x4*)(VTp + (f * 64 + ln) * 8) = o;
;             }
;         }
	ds_write_b128 v144, v[2:5] offset:8192
	ds_write_b128 v145, v[6:9] offset:8192
	ds_write_b128 v146, v[10:13] offset:8192
	s_waitcnt vmcnt(47)
	ds_write_b128 v147, v[14:17] offset:8192
	ds_write_b16 v148, v101
	ds_write_b16 v148, v105 offset:16
	ds_write_b16 v148, v107 offset:32
	ds_write_b16 v148, v109 offset:48
	ds_write_b16 v148, v111 offset:2048
	ds_write_b16 v148, v112 offset:2064
	ds_write_b16 v148, v156 offset:2080
	ds_write_b16 v148, v157 offset:2096
	ds_write_b16 v148, v158 offset:4096
	ds_write_b16 v148, v159 offset:4112
	ds_write_b16 v148, v160 offset:4128
	ds_write_b16 v148, v161 offset:4144
	ds_write_b16 v148, v116 offset:6144
	ds_write_b16 v148, v117 offset:6160
	ds_write_b16 v148, v118 offset:6176
	ds_write_b16 v148, v119 offset:6192
	s_waitcnt lgkmcnt(0)
	s_barrier
	ds_read_b128 v[2:5], v124
	ds_read_b128 v[6:9], v125
	v_lshl_add_u64 v[10:11], s[58:59], 0, v[102:103]
	s_waitcnt vmcnt(16)
	v_mov_b64_e32 v[14:15], v[62:63]
	v_mov_b64_e32 v[16:17], v[64:65]
	s_waitcnt lgkmcnt(1)
	global_store_dwordx4 v102, v[2:5], s[58:59]
	s_nop 1
	v_add_co_u32_e32 v2, vcc, s64, v10
	s_nop 1
	v_addc_co_u32_e32 v3, vcc, 0, v11, vcc
	s_waitcnt lgkmcnt(0)
	global_store_dwordx4 v[2:3], v[6:9], off
	ds_read_u16 v2, v136 offset:8192
	ds_read_u16 v3, v136 offset:8720
	ds_read_u16 v4, v136 offset:9248
	ds_read_u16 v5, v136 offset:9776
	ds_read_u16 v6, v136 offset:10304
	ds_read_u16 v7, v136 offset:10832
	ds_read_u16 v8, v136 offset:11360
	ds_read_u16 v9, v136 offset:11888
	s_waitcnt lgkmcnt(6)
	v_lshl_or_b32 v2, v3, 16, v2
	s_waitcnt lgkmcnt(4)
	v_lshl_or_b32 v3, v5, 16, v4
	s_waitcnt lgkmcnt(2)
	v_lshl_or_b32 v4, v7, 16, v6
	s_and_b64 vcc, s[56:57], exec
	s_waitcnt lgkmcnt(0)
	v_lshl_or_b32 v5, v9, 16, v8
	ds_read_u16 v6, v137 offset:8192
	ds_read_u16 v7, v137 offset:8720
	ds_read_u16 v8, v137 offset:9248
	ds_read_u16 v9, v137 offset:9776
	ds_read_u16 v10, v137 offset:10304
	ds_read_u16 v11, v137 offset:10832
	ds_read_u16 v12, v137 offset:11360
	ds_read_u16 v13, v137 offset:11888
	global_store_dwordx4 v102, v[2:5], s[54:55]
	s_waitcnt lgkmcnt(6)
	s_nop 0
	v_lshl_or_b32 v2, v7, 16, v6
	s_waitcnt lgkmcnt(4)
	v_lshl_or_b32 v3, v9, 16, v8
	s_waitcnt lgkmcnt(2)
	v_lshl_or_b32 v4, v11, 16, v10
	s_waitcnt lgkmcnt(0)
	v_lshl_or_b32 v5, v13, 16, v12
	ds_read_u16 v6, v138 offset:8192
	ds_read_u16 v7, v138 offset:8720
	ds_read_u16 v8, v138 offset:9248
	ds_read_u16 v9, v138 offset:9776
	ds_read_u16 v10, v138 offset:10304
	ds_read_u16 v11, v138 offset:10832
	ds_read_u16 v12, v138 offset:11360
	ds_read_u16 v13, v138 offset:11888
	global_store_dwordx4 v140, v[2:5], s[54:55]
	s_waitcnt lgkmcnt(6)
	s_nop 0
	v_lshl_or_b32 v2, v7, 16, v6
	s_waitcnt lgkmcnt(4)
	v_lshl_or_b32 v3, v9, 16, v8
	s_waitcnt lgkmcnt(2)
	v_lshl_or_b32 v4, v11, 16, v10
	s_waitcnt lgkmcnt(0)
	v_lshl_or_b32 v5, v13, 16, v12
	ds_read_u16 v6, v139 offset:8192
	ds_read_u16 v7, v139 offset:8720
	ds_read_u16 v8, v139 offset:9248
	ds_read_u16 v9, v139 offset:9776
	ds_read_u16 v10, v139 offset:10304
	ds_read_u16 v11, v139 offset:10832
	ds_read_u16 v12, v139 offset:11360
	ds_read_u16 v13, v139 offset:11888
	global_store_dwordx4 v141, v[2:5], s[54:55]
	s_waitcnt lgkmcnt(6)
	s_nop 0
	v_lshl_or_b32 v2, v7, 16, v6
	s_waitcnt lgkmcnt(4)
	v_lshl_or_b32 v3, v9, 16, v8
	s_waitcnt lgkmcnt(2)
	v_lshl_or_b32 v4, v11, 16, v10
	s_waitcnt lgkmcnt(0)
	v_lshl_or_b32 v5, v13, 16, v12
	global_store_dwordx4 v149, v[2:5], s[54:55]
	v_mov_b64_e32 v[6:7], v[54:55]
	v_mov_b64_e32 v[10:11], v[58:59]
	v_mov_b64_e32 v[2:3], v[50:51]
	v_mov_b64_e32 v[4:5], v[52:53]
	v_mov_b64_e32 v[8:9], v[56:57]
	v_mov_b64_e32 v[12:13], v[60:61]
	s_mov_b32 s54, s81
	s_barrier
	s_cbranch_vccz .LBB0_1540

; template <int DIR>
; DI float prep_gate_loop(const float* r_s, bf16_t* qt, bf16_t* kt, const float (&w)[16], float bias, int kk) {
;     ...
;         for (int i = 0; i < 16; ++i) {
;             const int tt = blk * 16 + i; const int t = DIR ? 63 - tt : tt;
;             const f32x4* rr = (const f32x4*)(r_s + t * 32 + DIR * 16);
;             const f32x4 r0 = rr[0], r1 = rr[1], r2 = rr[2], r3 = rr[3];
;             float s0 = __builtin_fmaf(r0[0], w[0], bias), s1 = r0[1] * w[1], s2 = r0[2] * w[2], s3 = r0[3] * w[3];
;             s0 = __builtin_fmaf(r1[0], w[4], s0); s1 = __builtin_fmaf(r1[1], w[5], s1); s2 = __builtin_fmaf(r1[2], w[6], s2); s3 = __builtin_fmaf(r1[3], w[7], s3);
;             s0 = __builtin_fmaf(r2[0], w[8], s0); s1 = __builtin_fmaf(r2[1], w[9], s1); s2 = __builtin_fmaf(r2[2], w[10], s2); s3 = __builtin_fmaf(r2[3], w[11], s3);
;             s0 = __builtin_fmaf(r3[0], w[12], s0); s1 = __builtin_fmaf(r3[1], w[13], s1); s2 = __builtin_fmaf(r3[2], w[14], s2); s3 = __builtin_fmaf(r3[3], w[15], s3);
;             const float pre = (s0 + s1) + (s2 + s3);
;             const float ex = __builtin_amdgcn_exp2f(-fabsf(pre) * LOG2E);
;             la[i] = (fminf(pre, 0.f) * LOG2E - __builtin_amdgcn_logf(1.f + ex)) * 0.0625f;
.LBB0_1535:
	v_mov_b32_e32 v32, s55
	ds_read_b128 v[18:21], v32 offset:1920
	ds_read_b128 v[22:25], v32 offset:1936
	ds_read_b128 v[26:29], v32 offset:1952
	ds_read_b128 v[34:37], v32 offset:1968
	s_addk_i32 s55, 0xf800
	s_waitcnt lgkmcnt(3)
	v_fma_f32 v18, v18, v85, v123
	v_mul_f32_e32 v19, v76, v19
	v_mul_f32_e32 v20, v73, v20
	v_mul_f32_e32 v21, v77, v21
	s_waitcnt lgkmcnt(2)
	v_fmac_f32_e32 v18, v22, v74
	v_fmac_f32_e32 v19, v23, v78
	v_fmac_f32_e32 v20, v24, v75
	v_fmac_f32_e32 v21, v25, v79
	s_waitcnt lgkmcnt(1)
	v_fmac_f32_e32 v18, v26, v80
	v_fmac_f32_e32 v19, v27, v88
	v_fmac_f32_e32 v20, v28, v81
	v_fmac_f32_e32 v21, v29, v89
	s_waitcnt lgkmcnt(0)
	v_fmac_f32_e32 v18, v34, v86
	v_fmac_f32_e32 v19, v35, v92
	v_fmac_f32_e32 v20, v36, v87
	v_fmac_f32_e32 v21, v37, v93
	v_add_f32_e32 v18, v18, v19
	v_add_f32_e32 v19, v20, v21
	v_add_f32_e32 v18, v18, v19
	v_mul_f32_e64 v19, |v18|, s79
	v_exp_f32_e32 v19, v19
	v_min_f32_e32 v18, 0, v18
	v_add_f32_e32 v19, 1.0, v19
	v_log_f32_e32 v19, v19
	s_nop 0
	v_fma_f32 v38, v18, s80, -v19
	ds_read_b128 v[18:21], v32 offset:1792
	ds_read_b128 v[22:25], v32 offset:1808
	ds_read_b128 v[26:29], v32 offset:1824
	ds_read_b128 v[34:37], v32 offset:1840
	v_fmac_f32_e32 v33, 0x3d800000, v38
	s_waitcnt lgkmcnt(3)
	v_fma_f32 v18, v18, v85, v123
	v_mul_f32_e32 v19, v76, v19
	v_mul_f32_e32 v20, v73, v20
	v_mul_f32_e32 v21, v77, v21
	s_waitcnt lgkmcnt(2)
	v_fmac_f32_e32 v18, v22, v74
	v_fmac_f32_e32 v19, v23, v78
	v_fmac_f32_e32 v20, v24, v75
	v_fmac_f32_e32 v21, v25, v79
	s_waitcnt lgkmcnt(1)
	v_fmac_f32_e32 v18, v26, v80
	v_fmac_f32_e32 v19, v27, v88
	v_fmac_f32_e32 v20, v28, v81
	v_fmac_f32_e32 v21, v29, v89
	s_waitcnt lgkmcnt(0)
	v_fmac_f32_e32 v18, v34, v86
	v_fmac_f32_e32 v19, v35, v92
	v_fmac_f32_e32 v20, v36, v87
	v_fmac_f32_e32 v21, v37, v93
	v_add_f32_e32 v18, v18, v19
	v_add_f32_e32 v19, v20, v21
	v_add_f32_e32 v18, v18, v19
	v_mul_f32_e64 v19, |v18|, s79
	v_exp_f32_e32 v19, v19
	v_min_f32_e32 v18, 0, v18
	v_add_f32_e32 v19, 1.0, v19
	v_log_f32_e32 v19, v19
	s_nop 0
	v_fma_f32 v39, v18, s80, -v19
	ds_read_b128 v[18:21], v32 offset:1664
	ds_read_b128 v[22:25], v32 offset:1680
	ds_read_b128 v[26:29], v32 offset:1696
	ds_read_b128 v[34:37], v32 offset:1712
	s_waitcnt lgkmcnt(3)
	v_fma_f32 v18, v18, v85, v123
	v_mul_f32_e32 v19, v76, v19
	v_mul_f32_e32 v20, v73, v20
	v_mul_f32_e32 v21, v77, v21
	s_waitcnt lgkmcnt(2)
	v_fmac_f32_e32 v18, v22, v74
	v_fmac_f32_e32 v19, v23, v78
	v_fmac_f32_e32 v20, v24, v75
	v_fmac_f32_e32 v21, v25, v79
	s_waitcnt lgkmcnt(1)
	v_fmac_f32_e32 v18, v26, v80
	v_fmac_f32_e32 v19, v27, v88
	v_fmac_f32_e32 v20, v28, v81
	v_fmac_f32_e32 v21, v29, v89
	s_waitcnt lgkmcnt(0)
	v_fmac_f32_e32 v18, v34, v86
	v_fmac_f32_e32 v19, v35, v92
	v_fmac_f32_e32 v20, v36, v87
	v_fmac_f32_e32 v21, v37, v93
	v_add_f32_e32 v18, v18, v19
	v_add_f32_e32 v19, v20, v21
	v_add_f32_e32 v18, v18, v19
	v_mul_f32_e64 v19, |v18|, s79
	v_exp_f32_e32 v19, v19
	v_min_f32_e32 v18, 0, v18
	v_add_f32_e32 v19, 1.0, v19
	v_log_f32_e32 v19, v19
	s_nop 0
	v_fma_f32 v40, v18, s80, -v19
	ds_read_b128 v[18:21], v32 offset:1536
	ds_read_b128 v[22:25], v32 offset:1552
	ds_read_b128 v[26:29], v32 offset:1568
	ds_read_b128 v[34:37], v32 offset:1584
	s_waitcnt lgkmcnt(3)
	v_fma_f32 v18, v18, v85, v123
	v_mul_f32_e32 v19, v76, v19
	v_mul_f32_e32 v20, v73, v20
	v_mul_f32_e32 v21, v77, v21
	s_waitcnt lgkmcnt(2)
	v_fmac_f32_e32 v18, v22, v74
	v_fmac_f32_e32 v19, v23, v78
	v_fmac_f32_e32 v20, v24, v75
	v_fmac_f32_e32 v21, v25, v79
	s_waitcnt lgkmcnt(1)
	v_fmac_f32_e32 v18, v26, v80
	v_fmac_f32_e32 v19, v27, v88
	v_fmac_f32_e32 v20, v28, v81
	v_fmac_f32_e32 v21, v29, v89
	s_waitcnt lgkmcnt(0)
	v_fmac_f32_e32 v18, v34, v86
	v_fmac_f32_e32 v19, v35, v92
	v_fmac_f32_e32 v20, v36, v87
	v_fmac_f32_e32 v21, v37, v93
	v_add_f32_e32 v18, v18, v19
	v_add_f32_e32 v19, v20, v21
	v_add_f32_e32 v18, v18, v19
	v_mul_f32_e64 v19, |v18|, s79
	v_exp_f32_e32 v19, v19
	v_min_f32_e32 v18, 0, v18
	v_add_f32_e32 v19, 1.0, v19
	v_log_f32_e32 v19, v19
	s_nop 0
	v_fma_f32 v41, v18, s80, -v19
	ds_read_b128 v[18:21], v32 offset:1408
	ds_read_b128 v[22:25], v32 offset:1424
	ds_read_b128 v[26:29], v32 offset:1440
	ds_read_b128 v[34:37], v32 offset:1456
	s_waitcnt lgkmcnt(3)
	v_fma_f32 v18, v18, v85, v123
	v_mul_f32_e32 v19, v76, v19
	v_mul_f32_e32 v20, v73, v20
	v_mul_f32_e32 v21, v77, v21
	s_waitcnt lgkmcnt(2)
	v_fmac_f32_e32 v18, v22, v74
	v_fmac_f32_e32 v19, v23, v78
	v_fmac_f32_e32 v20, v24, v75
	v_fmac_f32_e32 v21, v25, v79
	s_waitcnt lgkmcnt(1)
	v_fmac_f32_e32 v18, v26, v80
	v_fmac_f32_e32 v19, v27, v88
	v_fmac_f32_e32 v20, v28, v81
	v_fmac_f32_e32 v21, v29, v89
	s_waitcnt lgkmcnt(0)
	v_fmac_f32_e32 v18, v34, v86
	v_fmac_f32_e32 v19, v35, v92
	v_fmac_f32_e32 v20, v36, v87
	v_fmac_f32_e32 v21, v37, v93
	v_add_f32_e32 v18, v18, v19
	v_add_f32_e32 v19, v20, v21
	v_add_f32_e32 v18, v18, v19
	v_mul_f32_e64 v19, |v18|, s79
	v_exp_f32_e32 v19, v19
	v_min_f32_e32 v18, 0, v18
	v_add_f32_e32 v19, 1.0, v19
	v_log_f32_e32 v19, v19
	s_nop 0
	v_fma_f32 v42, v18, s80, -v19
	ds_read_b128 v[18:21], v32 offset:1280
	ds_read_b128 v[22:25], v32 offset:1296
	ds_read_b128 v[26:29], v32 offset:1312
	ds_read_b128 v[34:37], v32 offset:1328
	s_waitcnt lgkmcnt(3)
	v_fma_f32 v18, v18, v85, v123
	v_mul_f32_e32 v19, v76, v19
	v_mul_f32_e32 v20, v73, v20
	v_mul_f32_e32 v21, v77, v21
	s_waitcnt lgkmcnt(2)
	v_fmac_f32_e32 v18, v22, v74
	v_fmac_f32_e32 v19, v23, v78
	v_fmac_f32_e32 v20, v24, v75
	v_fmac_f32_e32 v21, v25, v79
	s_waitcnt lgkmcnt(1)
	v_fmac_f32_e32 v18, v26, v80
	v_fmac_f32_e32 v19, v27, v88
	v_fmac_f32_e32 v20, v28, v81
	v_fmac_f32_e32 v21, v29, v89
	s_waitcnt lgkmcnt(0)
; template <int DIR>
; DI float prep_gate_loop(const float* r_s, bf16_t* qt, bf16_t* kt, const float (&w)[16], float bias, int kk) {
;     ...
;         for (int i = 0; i < 16; ++i) {
;             const int tt = blk * 16 + i; const int t = DIR ? 63 - tt : tt;
;             const f32x4* rr = (const f32x4*)(r_s + t * 32 + DIR * 16);
;             const f32x4 r0 = rr[0], r1 = rr[1], r2 = rr[2], r3 = rr[3];
;             float s0 = __builtin_fmaf(r0[0], w[0], bias), s1 = r0[1] * w[1], s2 = r0[2] * w[2], s3 = r0[3] * w[3];
;             s0 = __builtin_fmaf(r1[0], w[4], s0); s1 = __builtin_fmaf(r1[1], w[5], s1); s2 = __builtin_fmaf(r1[2], w[6], s2); s3 = __builtin_fmaf(r1[3], w[7], s3);
;             s0 = __builtin_fmaf(r2[0], w[8], s0); s1 = __builtin_fmaf(r2[1], w[9], s1); s2 = __builtin_fmaf(r2[2], w[10], s2); s3 = __builtin_fmaf(r2[3], w[11], s3);
;             s0 = __builtin_fmaf(r3[0], w[12], s0); s1 = __builtin_fmaf(r3[1], w[13], s1); s2 = __builtin_fmaf(r3[2], w[14], s2); s3 = __builtin_fmaf(r3[3], w[15], s3);
;             const float pre = (s0 + s1) + (s2 + s3);
;             const float ex = __builtin_amdgcn_exp2f(-fabsf(pre) * LOG2E);
;             la[i] = (fminf(pre, 0.f) * LOG2E - __builtin_amdgcn_logf(1.f + ex)) * 0.0625f;
	v_fmac_f32_e32 v18, v34, v86
	v_fmac_f32_e32 v19, v35, v92
	v_fmac_f32_e32 v20, v36, v87
	v_fmac_f32_e32 v21, v37, v93
	v_add_f32_e32 v18, v18, v19
	v_add_f32_e32 v19, v20, v21
	v_add_f32_e32 v18, v18, v19
	v_mul_f32_e64 v19, |v18|, s79
	v_exp_f32_e32 v19, v19
	v_min_f32_e32 v18, 0, v18
	v_add_f32_e32 v19, 1.0, v19
	v_log_f32_e32 v19, v19
	s_nop 0
	v_fma_f32 v43, v18, s80, -v19
	ds_read_b128 v[18:21], v32 offset:1152
	ds_read_b128 v[22:25], v32 offset:1168
	ds_read_b128 v[26:29], v32 offset:1184
	ds_read_b128 v[34:37], v32 offset:1200
	s_waitcnt lgkmcnt(3)
	v_fma_f32 v18, v18, v85, v123
	v_mul_f32_e32 v19, v76, v19
	v_mul_f32_e32 v20, v73, v20
	v_mul_f32_e32 v21, v77, v21
	s_waitcnt lgkmcnt(2)
	v_fmac_f32_e32 v18, v22, v74
	v_fmac_f32_e32 v19, v23, v78
	v_fmac_f32_e32 v20, v24, v75
	v_fmac_f32_e32 v21, v25, v79
	s_waitcnt lgkmcnt(1)
	v_fmac_f32_e32 v18, v26, v80
	v_fmac_f32_e32 v19, v27, v88
	v_fmac_f32_e32 v20, v28, v81
	v_fmac_f32_e32 v21, v29, v89
	s_waitcnt lgkmcnt(0)
	v_fmac_f32_e32 v18, v34, v86
	v_fmac_f32_e32 v19, v35, v92
	v_fmac_f32_e32 v20, v36, v87
	v_fmac_f32_e32 v21, v37, v93
	v_add_f32_e32 v18, v18, v19
	v_add_f32_e32 v19, v20, v21
	v_add_f32_e32 v18, v18, v19
	v_mul_f32_e64 v19, |v18|, s79
	v_exp_f32_e32 v19, v19
	v_min_f32_e32 v18, 0, v18
	v_add_f32_e32 v19, 1.0, v19
	v_log_f32_e32 v19, v19
	s_nop 0
	v_fma_f32 v44, v18, s80, -v19
	ds_read_b128 v[18:21], v32 offset:1024
	ds_read_b128 v[22:25], v32 offset:1040
	ds_read_b128 v[26:29], v32 offset:1056
	ds_read_b128 v[34:37], v32 offset:1072
	s_waitcnt lgkmcnt(3)
	v_fma_f32 v18, v18, v85, v123
	v_mul_f32_e32 v19, v76, v19
	v_mul_f32_e32 v20, v73, v20
	v_mul_f32_e32 v21, v77, v21
	s_waitcnt lgkmcnt(2)
	v_fmac_f32_e32 v18, v22, v74
	v_fmac_f32_e32 v19, v23, v78
	v_fmac_f32_e32 v20, v24, v75
	v_fmac_f32_e32 v21, v25, v79
	s_waitcnt lgkmcnt(1)
	v_fmac_f32_e32 v18, v26, v80
	v_fmac_f32_e32 v19, v27, v88
	v_fmac_f32_e32 v20, v28, v81
	v_fmac_f32_e32 v21, v29, v89
	s_waitcnt lgkmcnt(0)
	v_fmac_f32_e32 v18, v34, v86
	v_fmac_f32_e32 v19, v35, v92
	v_fmac_f32_e32 v20, v36, v87
	v_fmac_f32_e32 v21, v37, v93
	v_add_f32_e32 v18, v18, v19
	v_add_f32_e32 v19, v20, v21
	v_add_f32_e32 v18, v18, v19
	v_mul_f32_e64 v19, |v18|, s79
	v_exp_f32_e32 v19, v19
	v_min_f32_e32 v18, 0, v18
	v_add_f32_e32 v19, 1.0, v19
	v_log_f32_e32 v19, v19
	s_nop 0
	v_fma_f32 v45, v18, s80, -v19
	ds_read_b128 v[18:21], v32 offset:896
	ds_read_b128 v[22:25], v32 offset:912
	ds_read_b128 v[26:29], v32 offset:928
	ds_read_b128 v[34:37], v32 offset:944
	s_waitcnt lgkmcnt(3)
	v_fma_f32 v18, v18, v85, v123
	v_mul_f32_e32 v19, v76, v19
	v_mul_f32_e32 v20, v73, v20
	v_mul_f32_e32 v21, v77, v21
	s_waitcnt lgkmcnt(2)
	v_fmac_f32_e32 v18, v22, v74
	v_fmac_f32_e32 v19, v23, v78
	v_fmac_f32_e32 v20, v24, v75
	v_fmac_f32_e32 v21, v25, v79
	s_waitcnt lgkmcnt(1)
	v_fmac_f32_e32 v18, v26, v80
	v_fmac_f32_e32 v19, v27, v88
	v_fmac_f32_e32 v20, v28, v81
	v_fmac_f32_e32 v21, v29, v89
	s_waitcnt lgkmcnt(0)
	v_fmac_f32_e32 v18, v34, v86
	v_fmac_f32_e32 v19, v35, v92
	v_fmac_f32_e32 v20, v36, v87
	v_fmac_f32_e32 v21, v37, v93
	v_add_f32_e32 v18, v18, v19
	v_add_f32_e32 v19, v20, v21
	v_add_f32_e32 v18, v18, v19
	v_mul_f32_e64 v19, |v18|, s79
	v_exp_f32_e32 v19, v19
	v_min_f32_e32 v18, 0, v18
	v_add_f32_e32 v19, 1.0, v19
	v_log_f32_e32 v19, v19
	s_nop 0
	v_fma_f32 v46, v18, s80, -v19
	ds_read_b128 v[18:21], v32 offset:768
	ds_read_b128 v[22:25], v32 offset:784
	ds_read_b128 v[26:29], v32 offset:800
	ds_read_b128 v[34:37], v32 offset:816
	s_waitcnt lgkmcnt(3)
	v_mul_f32_e32 v31, v73, v20
	v_mov_b32_e32 v20, v19
	v_fma_f32 v30, v18, v85, v123
	v_mul_f32_e64 v18, v76, v20
	v_mul_f32_e64 v19, v77, v21
	s_waitcnt lgkmcnt(2)
	v_mov_b32_e32 v20, v22
	v_mov_b32_e32 v21, v24
	v_mov_b32_e32 v24, v23
	v_fma_f32 v20, v20, v74, v30
	v_fma_f32 v21, v21, v75, v31
	v_fma_f32 v18, v24, v78, v18
	v_fma_f32 v19, v25, v79, v19
	s_waitcnt lgkmcnt(1)
	v_mov_b32_e32 v22, v26
	v_mov_b32_e32 v23, v28
	v_mov_b32_e32 v28, v27
	v_fma_f32 v20, v22, v80, v20
	v_fma_f32 v21, v23, v81, v21
	v_fma_f32 v18, v28, v88, v18
	v_fma_f32 v19, v29, v89, v19
	s_waitcnt lgkmcnt(0)
	v_mov_b32_e32 v22, v34
	v_mov_b32_e32 v23, v36
	v_mov_b32_e32 v36, v35
	v_fma_f32 v20, v22, v86, v20
	v_fma_f32 v21, v23, v87, v21
	v_fma_f32 v18, v36, v92, v18
	v_fma_f32 v19, v37, v93, v19
	s_nop 0
	v_add_f32_e64 v18, v20, v18
	v_add_f32_e64 v19, v21, v19
	s_nop 0
	v_add_f32_e32 v18, v18, v19
	v_mul_f32_e64 v19, |v18|, s79
	v_exp_f32_e32 v19, v19
	v_min_f32_e32 v18, 0, v18
	v_add_f32_e32 v19, 1.0, v19
	v_log_f32_e32 v19, v19
	s_nop 0
	v_fma_f32 v47, v18, s80, -v19
	ds_read_b128 v[18:21], v32 offset:640
	ds_read_b128 v[22:25], v32 offset:656
	ds_read_b128 v[26:29], v32 offset:672
	ds_read_b128 v[34:37], v32 offset:688
	s_waitcnt lgkmcnt(3)
	v_mul_f32_e32 v31, v73, v20
	v_mov_b32_e32 v20, v19
	v_fma_f32 v30, v18, v85, v123
	v_mul_f32_e64 v18, v76, v20
	v_mul_f32_e64 v19, v77, v21
	s_waitcnt lgkmcnt(2)
	v_mov_b32_e32 v20, v22
	v_mov_b32_e32 v21, v24
	v_mov_b32_e32 v24, v23
	v_fma_f32 v20, v20, v74, v30
	v_fma_f32 v21, v21, v75, v31
	v_fma_f32 v18, v24, v78, v18
	v_fma_f32 v19, v25, v79, v19
	s_waitcnt lgkmcnt(1)
	v_mov_b32_e32 v22, v26
	v_mov_b32_e32 v23, v28
	v_mov_b32_e32 v28, v27
	v_fma_f32 v20, v22, v80, v20
	v_fma_f32 v21, v23, v81, v21
	v_fma_f32 v18, v28, v88, v18
	v_fma_f32 v19, v29, v89, v19
	s_waitcnt lgkmcnt(0)
; template <int DIR>
; DI float prep_gate_loop(const float* r_s, bf16_t* qt, bf16_t* kt, const float (&w)[16], float bias, int kk) {
;     ...
;         for (int i = 0; i < 16; ++i) {
;             const int tt = blk * 16 + i; const int t = DIR ? 63 - tt : tt;
;             const f32x4* rr = (const f32x4*)(r_s + t * 32 + DIR * 16);
;             const f32x4 r0 = rr[0], r1 = rr[1], r2 = rr[2], r3 = rr[3];
;             float s0 = __builtin_fmaf(r0[0], w[0], bias), s1 = r0[1] * w[1], s2 = r0[2] * w[2], s3 = r0[3] * w[3];
;             s0 = __builtin_fmaf(r1[0], w[4], s0); s1 = __builtin_fmaf(r1[1], w[5], s1); s2 = __builtin_fmaf(r1[2], w[6], s2); s3 = __builtin_fmaf(r1[3], w[7], s3);
;             s0 = __builtin_fmaf(r2[0], w[8], s0); s1 = __builtin_fmaf(r2[1], w[9], s1); s2 = __builtin_fmaf(r2[2], w[10], s2); s3 = __builtin_fmaf(r2[3], w[11], s3);
;             s0 = __builtin_fmaf(r3[0], w[12], s0); s1 = __builtin_fmaf(r3[1], w[13], s1); s2 = __builtin_fmaf(r3[2], w[14], s2); s3 = __builtin_fmaf(r3[3], w[15], s3);
;             const float pre = (s0 + s1) + (s2 + s3);
;             const float ex = __builtin_amdgcn_exp2f(-fabsf(pre) * LOG2E);
;             la[i] = (fminf(pre, 0.f) * LOG2E - __builtin_amdgcn_logf(1.f + ex)) * 0.0625f;
;         }
; #pragma unroll
;         for (int i = 0; i < 16; ++i) { g += la[i]; la[i] = g; }
	v_mov_b32_e32 v22, v34
	v_mov_b32_e32 v23, v36
	v_mov_b32_e32 v36, v35
	v_fma_f32 v20, v22, v86, v20
	v_fma_f32 v21, v23, v87, v21
	v_fma_f32 v18, v36, v92, v18
	v_fma_f32 v19, v37, v93, v19
	s_nop 0
	v_add_f32_e64 v18, v20, v18
	v_add_f32_e64 v19, v21, v19
	s_nop 0
	v_add_f32_e32 v18, v18, v19
	v_mul_f32_e64 v19, |v18|, s79
	v_exp_f32_e32 v19, v19
	v_min_f32_e32 v18, 0, v18
	v_add_f32_e32 v19, 1.0, v19
	v_log_f32_e32 v19, v19
	s_nop 0
	v_fma_f32 v48, v18, s80, -v19
	ds_read_b128 v[18:21], v32 offset:512
	ds_read_b128 v[22:25], v32 offset:528
	ds_read_b128 v[26:29], v32 offset:544
	ds_read_b128 v[34:37], v32 offset:560
	s_waitcnt lgkmcnt(3)
	v_mul_f32_e32 v31, v73, v20
	v_mov_b32_e32 v20, v19
	v_fma_f32 v30, v18, v85, v123
	v_mul_f32_e64 v18, v76, v20
	v_mul_f32_e64 v19, v77, v21
	s_waitcnt lgkmcnt(2)
	v_mov_b32_e32 v20, v22
	v_mov_b32_e32 v21, v24
	v_mov_b32_e32 v24, v23
	v_fma_f32 v20, v20, v74, v30
	v_fma_f32 v21, v21, v75, v31
	v_fma_f32 v18, v24, v78, v18
	v_fma_f32 v19, v25, v79, v19
	s_waitcnt lgkmcnt(1)
	v_mov_b32_e32 v22, v26
	v_mov_b32_e32 v23, v28
	v_mov_b32_e32 v28, v27
	v_fma_f32 v20, v22, v80, v20
	v_fma_f32 v21, v23, v81, v21
	v_fma_f32 v18, v28, v88, v18
	v_fma_f32 v19, v29, v89, v19
	s_waitcnt lgkmcnt(0)
	v_mov_b32_e32 v22, v34
	v_mov_b32_e32 v23, v36
	v_mov_b32_e32 v36, v35
	v_fma_f32 v20, v22, v86, v20
	v_fma_f32 v21, v23, v87, v21
	v_fma_f32 v18, v36, v92, v18
	v_fma_f32 v19, v37, v93, v19
	s_nop 0
	v_add_f32_e64 v18, v20, v18
	v_add_f32_e64 v19, v21, v19
	s_nop 0
	v_add_f32_e32 v18, v18, v19
	v_mul_f32_e64 v19, |v18|, s79
	v_exp_f32_e32 v19, v19
	v_min_f32_e32 v18, 0, v18
	v_add_f32_e32 v19, 1.0, v19
	v_log_f32_e32 v19, v19
	s_nop 0
	v_fma_f32 v49, v18, s80, -v19
	ds_read_b128 v[18:21], v32 offset:384
	ds_read_b128 v[22:25], v32 offset:400
	ds_read_b128 v[26:29], v32 offset:416
	ds_read_b128 v[34:37], v32 offset:432
	s_waitcnt lgkmcnt(3)
	v_mul_f32_e32 v31, v73, v20
	v_mov_b32_e32 v20, v19
	v_fma_f32 v30, v18, v85, v123
	v_mul_f32_e64 v18, v76, v20
	v_mul_f32_e64 v19, v77, v21
	s_waitcnt lgkmcnt(2)
	v_mov_b32_e32 v20, v22
	v_mov_b32_e32 v21, v24
	v_mov_b32_e32 v24, v23
	v_fma_f32 v20, v20, v74, v30
	v_fma_f32 v21, v21, v75, v31
	v_fma_f32 v18, v24, v78, v18
	v_fma_f32 v19, v25, v79, v19
	s_waitcnt lgkmcnt(1)
	v_mov_b32_e32 v22, v26
	v_mov_b32_e32 v23, v28
	v_mov_b32_e32 v28, v27
	v_fma_f32 v20, v22, v80, v20
	v_fma_f32 v21, v23, v81, v21
	v_fma_f32 v18, v28, v88, v18
	v_fma_f32 v19, v29, v89, v19
	s_waitcnt lgkmcnt(0)
	v_mov_b32_e32 v22, v34
	v_mov_b32_e32 v23, v36
	v_mov_b32_e32 v36, v35
	v_fma_f32 v20, v22, v86, v20
	v_fma_f32 v21, v23, v87, v21
	v_fma_f32 v18, v36, v92, v18
	v_fma_f32 v19, v37, v93, v19
	s_nop 0
	v_add_f32_e64 v18, v20, v18
	v_add_f32_e64 v19, v21, v19
	s_nop 0
	v_add_f32_e32 v18, v18, v19
	v_mul_f32_e64 v19, |v18|, s79
	v_exp_f32_e32 v19, v19
	v_min_f32_e32 v18, 0, v18
	v_add_f32_e32 v19, 1.0, v19
	v_log_f32_e32 v19, v19
	s_nop 0
	v_fma_f32 v50, v18, s80, -v19
	ds_read_b128 v[18:21], v32 offset:256
	ds_read_b128 v[22:25], v32 offset:272
	ds_read_b128 v[26:29], v32 offset:288
	ds_read_b128 v[34:37], v32 offset:304
	s_waitcnt lgkmcnt(3)
	v_mul_f32_e32 v31, v73, v20
	v_mov_b32_e32 v20, v19
	v_fma_f32 v30, v18, v85, v123
	v_mul_f32_e64 v18, v76, v20
	v_mul_f32_e64 v19, v77, v21
	s_waitcnt lgkmcnt(2)
	v_mov_b32_e32 v20, v22
	v_mov_b32_e32 v21, v24
	v_mov_b32_e32 v24, v23
	v_fma_f32 v20, v20, v74, v30
	v_fma_f32 v21, v21, v75, v31
	v_fma_f32 v18, v24, v78, v18
	v_fma_f32 v19, v25, v79, v19
	s_waitcnt lgkmcnt(1)
	v_mov_b32_e32 v22, v26
	v_mov_b32_e32 v23, v28
	v_mov_b32_e32 v28, v27
	v_fma_f32 v20, v22, v80, v20
	v_fma_f32 v21, v23, v81, v21
	v_fma_f32 v18, v28, v88, v18
	v_fma_f32 v19, v29, v89, v19
	s_waitcnt lgkmcnt(0)
	v_mov_b32_e32 v22, v34
	v_mov_b32_e32 v23, v36
	v_mov_b32_e32 v36, v35
	v_fma_f32 v20, v22, v86, v20
	v_fma_f32 v21, v23, v87, v21
	v_fma_f32 v18, v36, v92, v18
	v_fma_f32 v19, v37, v93, v19
	s_nop 0
	v_add_f32_e64 v18, v20, v18
	v_add_f32_e64 v19, v21, v19
	s_nop 0
	v_add_f32_e32 v18, v18, v19
	v_mul_f32_e64 v19, |v18|, s79
	v_exp_f32_e32 v19, v19
	v_min_f32_e32 v18, 0, v18
	v_add_f32_e32 v19, 1.0, v19
	v_log_f32_e32 v19, v19
	s_nop 0
	v_fma_f32 v51, v18, s80, -v19
	ds_read_b128 v[18:21], v32 offset:128
	ds_read_b128 v[22:25], v32 offset:144
	ds_read_b128 v[26:29], v32 offset:160
	ds_read_b128 v[34:37], v32 offset:176
	s_waitcnt lgkmcnt(3)
	v_mul_f32_e32 v31, v73, v20
	v_mov_b32_e32 v20, v19
	v_fma_f32 v30, v18, v85, v123
	v_mul_f32_e64 v18, v76, v20
	v_mul_f32_e64 v19, v77, v21
	s_waitcnt lgkmcnt(2)
	v_mov_b32_e32 v20, v22
	v_mov_b32_e32 v21, v24
	v_mov_b32_e32 v24, v23
	v_fma_f32 v20, v20, v74, v30
	v_fma_f32 v21, v21, v75, v31
	v_fma_f32 v18, v24, v78, v18
	v_fma_f32 v19, v25, v79, v19
	s_waitcnt lgkmcnt(1)
	v_mov_b32_e32 v22, v26
	v_mov_b32_e32 v23, v28
	v_mov_b32_e32 v28, v27
	v_fma_f32 v20, v22, v80, v20
	v_fma_f32 v21, v23, v81, v21
	v_fma_f32 v18, v28, v88, v18
	v_fma_f32 v19, v29, v89, v19
	s_waitcnt lgkmcnt(0)
	v_mov_b32_e32 v22, v34
	v_mov_b32_e32 v23, v36
	v_mov_b32_e32 v36, v35
	v_fma_f32 v20, v22, v86, v20
	v_fma_f32 v21, v23, v87, v21
	v_fma_f32 v18, v36, v92, v18
	v_fma_f32 v19, v37, v93, v19
	s_nop 0
	v_add_f32_e64 v18, v20, v18
	v_add_f32_e64 v19, v21, v19
	s_nop 0
	v_add_f32_e32 v18, v18, v19
	v_mul_f32_e64 v19, |v18|, s79
	v_exp_f32_e32 v19, v19
	v_min_f32_e32 v18, 0, v18
	v_add_f32_e32 v19, 1.0, v19
	v_log_f32_e32 v19, v19
	s_nop 0
	v_fma_f32 v52, v18, s80, -v19
	ds_read_b128 v[18:21], v32
	ds_read_b128 v[22:25], v32 offset:16
	ds_read_b128 v[26:29], v32 offset:32
	ds_read_b128 v[34:37], v32 offset:48
	v_fmamk_f32 v32, v39, 0x3d800000, v33
	s_waitcnt lgkmcnt(3)
; DI float bf2f(bf16_t b) { return __uint_as_float(((unsigned)b) << 16); }
; DI bf16_t f2bf(float f) { return (bf16_t)(pk2(f, 0.f) & 0xffffu); }
; template <int DIR>
; DI float prep_gate_loop(const float* r_s, bf16_t* qt, bf16_t* kt, const float (&w)[16], float bias, int kk) {
;     ...
;         for (int i = 0; i < 16; ++i) {
;             const int tt = blk * 16 + i; const int t = DIR ? 63 - tt : tt;
;             const f32x4* rr = (const f32x4*)(r_s + t * 32 + DIR * 16);
;             const f32x4 r0 = rr[0], r1 = rr[1], r2 = rr[2], r3 = rr[3];
;             float s0 = __builtin_fmaf(r0[0], w[0], bias), s1 = r0[1] * w[1], s2 = r0[2] * w[2], s3 = r0[3] * w[3];
;             s0 = __builtin_fmaf(r1[0], w[4], s0); s1 = __builtin_fmaf(r1[1], w[5], s1); s2 = __builtin_fmaf(r1[2], w[6], s2); s3 = __builtin_fmaf(r1[3], w[7], s3);
;             s0 = __builtin_fmaf(r2[0], w[8], s0); s1 = __builtin_fmaf(r2[1], w[9], s1); s2 = __builtin_fmaf(r2[2], w[10], s2); s3 = __builtin_fmaf(r2[3], w[11], s3);
;             s0 = __builtin_fmaf(r3[0], w[12], s0); s1 = __builtin_fmaf(r3[1], w[13], s1); s2 = __builtin_fmaf(r3[2], w[14], s2); s3 = __builtin_fmaf(r3[3], w[15], s3);
;             const float pre = (s0 + s1) + (s2 + s3);
;             const float ex = __builtin_amdgcn_exp2f(-fabsf(pre) * LOG2E);
;             la[i] = (fminf(pre, 0.f) * LOG2E - __builtin_amdgcn_logf(1.f + ex)) * 0.0625f;
;         }
; #pragma unroll
;         for (int i = 0; i < 16; ++i) { g += la[i]; la[i] = g; }
; #pragma unroll
;         for (int i = 0; i < 16; ++i) {
;             const int tt = blk * 16 + i; const int t = DIR ? 63 - tt : tt;
;             const float e = __builtin_amdgcn_exp2f(la[i]);
;             bf16_t* qp = qt + (DIR * 64 + t) * 264 + kk; bf16_t* kp = kt + (DIR * 64 + t) * 264 + kk;
;             const float qv = bf2f(*qp), kv = bf2f(*kp);
;             *qp = f2bf(qv * 0.0625f * e);
;             *kp = f2bf(kv * __builtin_amdgcn_rcpf(e));
	v_mul_f32_e32 v31, v73, v20
	v_mov_b32_e32 v20, v19
	v_fma_f32 v30, v18, v85, v123
	v_mul_f32_e64 v18, v76, v20
	v_mul_f32_e64 v19, v77, v21
	s_waitcnt lgkmcnt(2)
	v_mov_b32_e32 v20, v22
	v_mov_b32_e32 v21, v24
	v_fma_f32 v20, v20, v74, v30
	v_fma_f32 v21, v21, v75, v31
	v_mov_b32_e32 v24, v23
	s_waitcnt lgkmcnt(1)
	v_mov_b32_e32 v22, v26
	v_mov_b32_e32 v23, v28
	v_fma_f32 v18, v24, v78, v18
	v_fma_f32 v19, v25, v79, v19
	v_fma_f32 v20, v22, v80, v20
	v_fma_f32 v21, v23, v81, v21
	v_mov_b32_e32 v28, v27
	s_waitcnt lgkmcnt(0)
	v_mov_b32_e32 v22, v34
	v_add_u32_e32 v34, s52, v120
	v_fma_f32 v18, v28, v88, v18
	v_fma_f32 v19, v29, v89, v19
	v_mov_b32_e32 v23, v36
	v_mov_b32_e32 v36, v35
	v_add_u32_e32 v35, 0x125f0, v34
	v_fma_f32 v18, v36, v92, v18
	v_fma_f32 v19, v37, v93, v19
	ds_read_u16 v37, v35
	v_exp_f32_e32 v33, v33
	v_add_u32_e32 v36, 0x22df0, v34
	ds_read_u16 v38, v36
	v_fmamk_f32 v31, v40, 0x3d800000, v32
	s_waitcnt lgkmcnt(1)
	v_lshlrev_b32_e32 v37, 16, v37
	v_mul_f32_e32 v37, 0x3d800000, v37
	v_mul_f32_e32 v37, v33, v37
	v_rcp_f32_e32 v33, v33
	s_waitcnt lgkmcnt(0)
	v_lshlrev_b32_e32 v38, 16, v38
	v_cvt_pk_bf16_f32 v37, v37, s0
	v_exp_f32_e32 v32, v32
	v_mul_f32_e32 v33, v33, v38
	v_cvt_pk_bf16_f32 v33, v33, s0
	ds_write_b16 v36, v33
	v_add_u32_e32 v33, 0x123e0, v34
	ds_read_u16 v36, v33
	ds_write_b16 v35, v37
	v_add_u32_e32 v35, 0x22be0, v34
	ds_read_u16 v37, v35
	v_fmamk_f32 v30, v41, 0x3d800000, v31
	s_waitcnt lgkmcnt(2)
	v_lshlrev_b32_e32 v36, 16, v36
	v_mul_f32_e32 v36, 0x3d800000, v36
	v_mul_f32_e32 v36, v32, v36
	v_rcp_f32_e32 v32, v32
	s_waitcnt lgkmcnt(0)
	v_lshlrev_b32_e32 v37, 16, v37
	v_cvt_pk_bf16_f32 v36, v36, s0
	v_exp_f32_e32 v31, v31
	v_mul_f32_e32 v32, v32, v37
	v_cvt_pk_bf16_f32 v32, v32, s0
	ds_write_b16 v35, v32
	v_add_u32_e32 v32, 0x121d0, v34
	ds_read_u16 v35, v32
	ds_write_b16 v33, v36
	v_add_u32_e32 v33, 0x229d0, v34
	ds_read_u16 v36, v33
	v_fmamk_f32 v29, v42, 0x3d800000, v30
	s_waitcnt lgkmcnt(2)
	v_lshlrev_b32_e32 v35, 16, v35
	v_mul_f32_e32 v35, 0x3d800000, v35
	v_mul_f32_e32 v35, v31, v35
	v_rcp_f32_e32 v31, v31
	s_waitcnt lgkmcnt(0)
	v_lshlrev_b32_e32 v36, 16, v36
	v_cvt_pk_bf16_f32 v35, v35, s0
	v_exp_f32_e32 v30, v30
	v_mul_f32_e32 v31, v31, v36
	v_cvt_pk_bf16_f32 v31, v31, s0
	ds_write_b16 v33, v31
	v_add_u32_e32 v31, 0x11fc0, v34
	ds_read_u16 v33, v31
	ds_write_b16 v32, v35
	v_add_u32_e32 v32, 0x227c0, v34
	ds_read_u16 v35, v32
	v_fmamk_f32 v28, v43, 0x3d800000, v29
	s_waitcnt lgkmcnt(2)
	v_lshlrev_b32_e32 v33, 16, v33
	v_mul_f32_e32 v33, 0x3d800000, v33
	v_mul_f32_e32 v33, v30, v33
	v_rcp_f32_e32 v30, v30
	s_waitcnt lgkmcnt(0)
	v_lshlrev_b32_e32 v35, 16, v35
	v_cvt_pk_bf16_f32 v33, v33, s0
	v_exp_f32_e32 v29, v29
	v_mul_f32_e32 v30, v30, v35
	v_cvt_pk_bf16_f32 v30, v30, s0
	ds_write_b16 v32, v30
	v_add_u32_e32 v30, 0x11db0, v34
	ds_read_u16 v32, v30
	ds_write_b16 v31, v33
	v_add_u32_e32 v31, 0x225b0, v34
	ds_read_u16 v33, v31
	v_fmamk_f32 v27, v44, 0x3d800000, v28
	s_waitcnt lgkmcnt(2)
	v_lshlrev_b32_e32 v32, 16, v32
	v_mul_f32_e32 v32, 0x3d800000, v32
	v_mul_f32_e32 v32, v29, v32
	v_rcp_f32_e32 v29, v29
	s_waitcnt lgkmcnt(0)
	v_lshlrev_b32_e32 v33, 16, v33
	v_cvt_pk_bf16_f32 v32, v32, s0
	v_exp_f32_e32 v28, v28
	v_mul_f32_e32 v29, v29, v33
	v_cvt_pk_bf16_f32 v29, v29, s0
	ds_write_b16 v31, v29
	v_add_u32_e32 v29, 0x11ba0, v34
	ds_read_u16 v31, v29
	ds_write_b16 v30, v32
	v_add_u32_e32 v30, 0x223a0, v34
	ds_read_u16 v32, v30
	v_fmamk_f32 v26, v45, 0x3d800000, v27
	s_waitcnt lgkmcnt(2)
	v_lshlrev_b32_e32 v31, 16, v31
	v_mul_f32_e32 v31, 0x3d800000, v31
	v_mul_f32_e32 v31, v28, v31
	v_rcp_f32_e32 v28, v28
	s_waitcnt lgkmcnt(0)
	v_lshlrev_b32_e32 v32, 16, v32
	v_cvt_pk_bf16_f32 v31, v31, s0
	v_exp_f32_e32 v27, v27
	v_mul_f32_e32 v28, v28, v32
	v_cvt_pk_bf16_f32 v28, v28, s0
	ds_write_b16 v30, v28
	v_add_u32_e32 v28, 0x11990, v34
	ds_read_u16 v30, v28
	ds_write_b16 v29, v31
	v_add_u32_e32 v29, 0x22190, v34
	ds_read_u16 v31, v29
	v_fmamk_f32 v25, v46, 0x3d800000, v26
	s_waitcnt lgkmcnt(2)
	v_lshlrev_b32_e32 v30, 16, v30
	v_mul_f32_e32 v30, 0x3d800000, v30
	v_mul_f32_e32 v30, v27, v30
	v_rcp_f32_e32 v27, v27
	s_waitcnt lgkmcnt(0)
	v_lshlrev_b32_e32 v31, 16, v31
	v_cvt_pk_bf16_f32 v30, v30, s0
	v_exp_f32_e32 v26, v26
	v_mul_f32_e32 v27, v27, v31
	v_cvt_pk_bf16_f32 v27, v27, s0
	ds_write_b16 v29, v27
	v_add_u32_e32 v27, 0x11780, v34
	ds_read_u16 v29, v27
	ds_write_b16 v28, v30
	v_add_u32_e32 v28, 0x21f80, v34
	ds_read_u16 v30, v28
	v_fmamk_f32 v24, v47, 0x3d800000, v25
	s_waitcnt lgkmcnt(2)
	v_lshlrev_b32_e32 v29, 16, v29
	v_mul_f32_e32 v29, 0x3d800000, v29
	v_mul_f32_e32 v29, v26, v29
	v_rcp_f32_e32 v26, v26
	s_waitcnt lgkmcnt(0)
; DI float bf2f(bf16_t b) { return __uint_as_float(((unsigned)b) << 16); }
; DI bf16_t f2bf(float f) { return (bf16_t)(pk2(f, 0.f) & 0xffffu); }
; template <int DIR>
; DI float prep_gate_loop(const float* r_s, bf16_t* qt, bf16_t* kt, const float (&w)[16], float bias, int kk) {
;     ...
;             float s0 = __builtin_fmaf(r0[0], w[0], bias), s1 = r0[1] * w[1], s2 = r0[2] * w[2], s3 = r0[3] * w[3];
;             s0 = __builtin_fmaf(r1[0], w[4], s0); s1 = __builtin_fmaf(r1[1], w[5], s1); s2 = __builtin_fmaf(r1[2], w[6], s2); s3 = __builtin_fmaf(r1[3], w[7], s3);
;             s0 = __builtin_fmaf(r2[0], w[8], s0); s1 = __builtin_fmaf(r2[1], w[9], s1); s2 = __builtin_fmaf(r2[2], w[10], s2); s3 = __builtin_fmaf(r2[3], w[11], s3);
;             s0 = __builtin_fmaf(r3[0], w[12], s0); s1 = __builtin_fmaf(r3[1], w[13], s1); s2 = __builtin_fmaf(r3[2], w[14], s2); s3 = __builtin_fmaf(r3[3], w[15], s3);
;             const float pre = (s0 + s1) + (s2 + s3);
;             const float ex = __builtin_amdgcn_exp2f(-fabsf(pre) * LOG2E);
;             la[i] = (fminf(pre, 0.f) * LOG2E - __builtin_amdgcn_logf(1.f + ex)) * 0.0625f;
;         }
; #pragma unroll
;         for (int i = 0; i < 16; ++i) { g += la[i]; la[i] = g; }
; #pragma unroll
;         for (int i = 0; i < 16; ++i) {
;             const int tt = blk * 16 + i; const int t = DIR ? 63 - tt : tt;
;             const float e = __builtin_amdgcn_exp2f(la[i]);
;             bf16_t* qp = qt + (DIR * 64 + t) * 264 + kk; bf16_t* kp = kt + (DIR * 64 + t) * 264 + kk;
;             const float qv = bf2f(*qp), kv = bf2f(*kp);
;             *qp = f2bf(qv * 0.0625f * e);
;             *kp = f2bf(kv * __builtin_amdgcn_rcpf(e));
	v_lshlrev_b32_e32 v30, 16, v30
	v_cvt_pk_bf16_f32 v29, v29, s0
	v_exp_f32_e32 v25, v25
	v_mul_f32_e32 v26, v26, v30
	v_cvt_pk_bf16_f32 v26, v26, s0
	ds_write_b16 v28, v26
	v_add_u32_e32 v26, 0x11570, v34
	ds_read_u16 v28, v26
	ds_write_b16 v27, v29
	v_add_u32_e32 v27, 0x21d70, v34
	ds_read_u16 v29, v27
	v_fma_f32 v20, v22, v86, v20
	v_fma_f32 v21, v23, v87, v21
	s_waitcnt lgkmcnt(2)
	v_lshlrev_b32_e32 v28, 16, v28
	v_mul_f32_e32 v28, 0x3d800000, v28
	v_mul_f32_e32 v28, v25, v28
	v_rcp_f32_e32 v25, v25
	s_waitcnt lgkmcnt(0)
	v_lshlrev_b32_e32 v29, 16, v29
	v_fmamk_f32 v23, v48, 0x3d800000, v24
	v_cvt_pk_bf16_f32 v28, v28, s0
	v_mul_f32_e32 v25, v25, v29
	v_cvt_pk_bf16_f32 v25, v25, s0
	ds_write_b16 v27, v25
	v_add_u32_e32 v25, 0x11360, v34
	ds_read_u16 v27, v25
	v_exp_f32_e32 v24, v24
	ds_write_b16 v26, v28
	v_add_u32_e32 v26, 0x21b60, v34
	ds_read_u16 v28, v26
	s_waitcnt lgkmcnt(2)
	v_lshlrev_b32_e32 v27, 16, v27
	v_mul_f32_e32 v27, 0x3d800000, v27
	v_mul_f32_e32 v27, v24, v27
	v_rcp_f32_e32 v24, v24
	s_waitcnt lgkmcnt(0)
	v_lshlrev_b32_e32 v28, 16, v28
	v_fmamk_f32 v22, v49, 0x3d800000, v23
	v_cvt_pk_bf16_f32 v27, v27, s0
	v_mul_f32_e32 v24, v24, v28
	v_cvt_pk_bf16_f32 v24, v24, s0
	ds_write_b16 v26, v24
	v_add_u32_e32 v24, 0x11150, v34
	ds_read_u16 v26, v24
	v_exp_f32_e32 v23, v23
	ds_write_b16 v25, v27
	v_add_u32_e32 v25, 0x21950, v34
	ds_read_u16 v27, v25
	s_waitcnt lgkmcnt(2)
	v_lshlrev_b32_e32 v26, 16, v26
	v_mul_f32_e32 v26, 0x3d800000, v26
	v_mul_f32_e32 v26, v23, v26
	v_rcp_f32_e32 v23, v23
	s_waitcnt lgkmcnt(0)
	v_lshlrev_b32_e32 v27, 16, v27
	v_add_f32_e64 v18, v20, v18
	v_add_f32_e64 v19, v21, v19
	v_fmamk_f32 v21, v50, 0x3d800000, v22
	v_mul_f32_e32 v23, v23, v27
	v_cvt_pk_bf16_f32 v23, v23, s0
	ds_write_b16 v25, v23
	v_add_u32_e32 v23, 0x10f40, v34
	ds_read_u16 v25, v23
	v_cvt_pk_bf16_f32 v26, v26, s0
	v_exp_f32_e32 v22, v22
	ds_write_b16 v24, v26
	v_add_u32_e32 v24, 0x21740, v34
	ds_read_u16 v26, v24
	s_waitcnt lgkmcnt(2)
	v_lshlrev_b32_e32 v25, 16, v25
	v_mul_f32_e32 v25, 0x3d800000, v25
	v_mul_f32_e32 v25, v22, v25
	v_rcp_f32_e32 v22, v22
	s_waitcnt lgkmcnt(0)
	v_lshlrev_b32_e32 v26, 16, v26
	v_fmamk_f32 v20, v51, 0x3d800000, v21
	v_cvt_pk_bf16_f32 v25, v25, s0
	v_mul_f32_e32 v22, v22, v26
	v_cvt_pk_bf16_f32 v22, v22, s0
	ds_write_b16 v24, v22
	v_add_u32_e32 v22, 0x10d30, v34
	ds_read_u16 v24, v22
	v_exp_f32_e32 v21, v21
	ds_write_b16 v23, v25
	v_add_u32_e32 v23, 0x21530, v34
	ds_read_u16 v25, v23
	s_waitcnt lgkmcnt(2)
	v_lshlrev_b32_e32 v24, 16, v24
	v_add_f32_e32 v18, v18, v19
	v_mul_f32_e32 v24, 0x3d800000, v24
	v_mul_f32_e64 v19, |v18|, s79
	v_mul_f32_e32 v24, v21, v24
	v_rcp_f32_e32 v21, v21
	v_exp_f32_e32 v19, v19
	s_waitcnt lgkmcnt(0)
	v_lshlrev_b32_e32 v25, 16, v25
	v_min_f32_e32 v18, 0, v18
	v_mul_f32_e32 v21, v21, v25
	v_add_f32_e32 v19, 1.0, v19
	v_cvt_pk_bf16_f32 v21, v21, s0
	v_log_f32_e32 v19, v19
	ds_write_b16 v23, v21
	v_add_u32_e32 v21, 0x10b20, v34
	ds_read_u16 v23, v21
	v_fma_f32 v18, v18, s80, -v19
	v_fmamk_f32 v19, v52, 0x3d800000, v20
	v_cvt_pk_bf16_f32 v24, v24, s0
	v_exp_f32_e32 v20, v20
	ds_write_b16 v22, v24
	v_add_u32_e32 v22, 0x21320, v34
	ds_read_u16 v24, v22
	s_waitcnt lgkmcnt(2)
	v_lshlrev_b32_e32 v23, 16, v23
	v_mul_f32_e32 v23, 0x3d800000, v23
	v_mul_f32_e32 v23, v20, v23
	v_rcp_f32_e32 v20, v20
	s_waitcnt lgkmcnt(0)
	v_lshlrev_b32_e32 v24, 16, v24
	v_fmamk_f32 v18, v18, 0x3d800000, v19
	v_cvt_pk_bf16_f32 v23, v23, s0
	v_mul_f32_e32 v20, v20, v24
	v_cvt_pk_bf16_f32 v20, v20, s0
	ds_write_b16 v22, v20
	v_add_u32_e32 v20, 0x10910, v34
	ds_read_u16 v22, v20
	v_exp_f32_e32 v19, v19
	ds_write_b16 v21, v23
	v_add_u32_e32 v21, 0x21110, v34
	ds_read_u16 v23, v21
	s_waitcnt lgkmcnt(2)
	v_lshlrev_b32_e32 v22, 16, v22
	v_mul_f32_e32 v22, 0x3d800000, v22
	v_mul_f32_e32 v22, v19, v22
	v_rcp_f32_e32 v19, v19
	s_waitcnt lgkmcnt(0)
	v_lshlrev_b32_e32 v23, 16, v23
	v_cvt_pk_bf16_f32 v22, v22, s0
	v_exp_f32_e32 v112, v18
	v_mul_f32_e32 v19, v19, v23
	v_cvt_pk_bf16_f32 v19, v19, s0
	ds_write_b16 v21, v19
	v_add_u32_e32 v19, 0x10700, v34
	ds_read_u16 v21, v19
	ds_write_b16 v20, v22
	v_add_u32_e32 v20, 0x20f00, v34
	ds_read_u16 v22, v20
	s_addk_i32 s52, 0xdf00
	s_waitcnt lgkmcnt(2)
	v_lshlrev_b32_e32 v21, 16, v21
	v_mul_f32_e32 v21, 0x3d800000, v21
	v_mul_f32_e32 v21, v112, v21
	v_cvt_pk_bf16_f32 v21, v21, s0
	ds_write_b16 v19, v21
	v_rcp_f32_e32 v19, v112
	s_waitcnt lgkmcnt(1)
	v_lshlrev_b32_e32 v22, 16, v22
	s_cmp_lg_u32 s52, 0xffff7c00
	v_mov_b32_e32 v33, v18
	v_mul_f32_e32 v19, v19, v22
	v_cvt_pk_bf16_f32 v19, v19, s0
	ds_write_b16 v20, v19
	s_cbranch_scc1 .LBB0_1535

; template <int DIR>
; DI float prep_gate_loop(const float* r_s, bf16_t* qt, bf16_t* kt, const float (&w)[16], float bias, int kk) {
;     ...
;         for (int i = 0; i < 16; ++i) {
;             const int tt = blk * 16 + i; const int t = DIR ? 63 - tt : tt;
;             const f32x4* rr = (const f32x4*)(r_s + t * 32 + DIR * 16);
;             const f32x4 r0 = rr[0], r1 = rr[1], r2 = rr[2], r3 = rr[3];
;             float s0 = __builtin_fmaf(r0[0], w[0], bias), s1 = r0[1] * w[1], s2 = r0[2] * w[2], s3 = r0[3] * w[3];
;             s0 = __builtin_fmaf(r1[0], w[4], s0); s1 = __builtin_fmaf(r1[1], w[5], s1); s2 = __builtin_fmaf(r1[2], w[6], s2); s3 = __builtin_fmaf(r1[3], w[7], s3);
;             s0 = __builtin_fmaf(r2[0], w[8], s0); s1 = __builtin_fmaf(r2[1], w[9], s1); s2 = __builtin_fmaf(r2[2], w[10], s2); s3 = __builtin_fmaf(r2[3], w[11], s3);
;             s0 = __builtin_fmaf(r3[0], w[12], s0); s1 = __builtin_fmaf(r3[1], w[13], s1); s2 = __builtin_fmaf(r3[2], w[14], s2); s3 = __builtin_fmaf(r3[3], w[15], s3);
;             const float pre = (s0 + s1) + (s2 + s3);
;             const float ex = __builtin_amdgcn_exp2f(-fabsf(pre) * LOG2E);
;             la[i] = (fminf(pre, 0.f) * LOG2E - __builtin_amdgcn_logf(1.f + ex)) * 0.0625f;
.LBB0_1539:
	v_mov_b32_e32 v32, s55
	ds_read_b128 v[18:21], v32
	ds_read_b128 v[22:25], v32 offset:16
	ds_read_b128 v[26:29], v32 offset:32
	ds_read_b128 v[34:37], v32 offset:48
	s_addk_i32 s55, 0x800
	s_waitcnt lgkmcnt(3)
	v_fma_f32 v18, v18, v85, v123
	v_mul_f32_e32 v19, v76, v19
	v_mul_f32_e32 v20, v73, v20
	v_mul_f32_e32 v21, v77, v21
	s_waitcnt lgkmcnt(2)
	v_fmac_f32_e32 v18, v22, v74
	v_fmac_f32_e32 v19, v23, v78
	v_fmac_f32_e32 v20, v24, v75
	v_fmac_f32_e32 v21, v25, v79
	s_waitcnt lgkmcnt(1)
	v_fmac_f32_e32 v18, v26, v80
	v_fmac_f32_e32 v19, v27, v88
	v_fmac_f32_e32 v20, v28, v81
	v_fmac_f32_e32 v21, v29, v89
	s_waitcnt lgkmcnt(0)
	v_fmac_f32_e32 v18, v34, v86
	v_fmac_f32_e32 v19, v35, v92
	v_fmac_f32_e32 v20, v36, v87
	v_fmac_f32_e32 v21, v37, v93
	v_add_f32_e32 v18, v18, v19
	v_add_f32_e32 v19, v20, v21
	v_add_f32_e32 v18, v18, v19
	v_mul_f32_e64 v19, |v18|, s79
	v_exp_f32_e32 v19, v19
	v_min_f32_e32 v18, 0, v18
	v_add_f32_e32 v19, 1.0, v19
	v_log_f32_e32 v19, v19
	s_nop 0
	v_fma_f32 v38, v18, s80, -v19
	ds_read_b128 v[18:21], v32 offset:128
	ds_read_b128 v[22:25], v32 offset:144
	ds_read_b128 v[26:29], v32 offset:160
	ds_read_b128 v[34:37], v32 offset:176
	v_fmac_f32_e32 v33, 0x3d800000, v38
	s_waitcnt lgkmcnt(3)
	v_fma_f32 v18, v18, v85, v123
	v_mul_f32_e32 v19, v76, v19
	v_mul_f32_e32 v20, v73, v20
	v_mul_f32_e32 v21, v77, v21
	s_waitcnt lgkmcnt(2)
	v_fmac_f32_e32 v18, v22, v74
	v_fmac_f32_e32 v19, v23, v78
	v_fmac_f32_e32 v20, v24, v75
	v_fmac_f32_e32 v21, v25, v79
	s_waitcnt lgkmcnt(1)
	v_fmac_f32_e32 v18, v26, v80
	v_fmac_f32_e32 v19, v27, v88
	v_fmac_f32_e32 v20, v28, v81
	v_fmac_f32_e32 v21, v29, v89
	s_waitcnt lgkmcnt(0)
	v_fmac_f32_e32 v18, v34, v86
	v_fmac_f32_e32 v19, v35, v92
	v_fmac_f32_e32 v20, v36, v87
	v_fmac_f32_e32 v21, v37, v93
	v_add_f32_e32 v18, v18, v19
	v_add_f32_e32 v19, v20, v21
	v_add_f32_e32 v18, v18, v19
	v_mul_f32_e64 v19, |v18|, s79
	v_exp_f32_e32 v19, v19
	v_min_f32_e32 v18, 0, v18
	v_add_f32_e32 v19, 1.0, v19
	v_log_f32_e32 v19, v19
	s_nop 0
	v_fma_f32 v39, v18, s80, -v19
	ds_read_b128 v[18:21], v32 offset:256
	ds_read_b128 v[22:25], v32 offset:272
	ds_read_b128 v[26:29], v32 offset:288
	ds_read_b128 v[34:37], v32 offset:304
	s_waitcnt lgkmcnt(3)
	v_fma_f32 v18, v18, v85, v123
	v_mul_f32_e32 v19, v76, v19
	v_mul_f32_e32 v20, v73, v20
	v_mul_f32_e32 v21, v77, v21
	s_waitcnt lgkmcnt(2)
	v_fmac_f32_e32 v18, v22, v74
	v_fmac_f32_e32 v19, v23, v78
	v_fmac_f32_e32 v20, v24, v75
	v_fmac_f32_e32 v21, v25, v79
	s_waitcnt lgkmcnt(1)
	v_fmac_f32_e32 v18, v26, v80
	v_fmac_f32_e32 v19, v27, v88
	v_fmac_f32_e32 v20, v28, v81
	v_fmac_f32_e32 v21, v29, v89
	s_waitcnt lgkmcnt(0)
	v_fmac_f32_e32 v18, v34, v86
	v_fmac_f32_e32 v19, v35, v92
	v_fmac_f32_e32 v20, v36, v87
	v_fmac_f32_e32 v21, v37, v93
	v_add_f32_e32 v18, v18, v19
	v_add_f32_e32 v19, v20, v21
	v_add_f32_e32 v18, v18, v19
	v_mul_f32_e64 v19, |v18|, s79
	v_exp_f32_e32 v19, v19
	v_min_f32_e32 v18, 0, v18
	v_add_f32_e32 v19, 1.0, v19
	v_log_f32_e32 v19, v19
	s_nop 0
	v_fma_f32 v40, v18, s80, -v19
	ds_read_b128 v[18:21], v32 offset:384
	ds_read_b128 v[22:25], v32 offset:400
	ds_read_b128 v[26:29], v32 offset:416
	ds_read_b128 v[34:37], v32 offset:432
	s_waitcnt lgkmcnt(3)
	v_fma_f32 v18, v18, v85, v123
	v_mul_f32_e32 v19, v76, v19
	v_mul_f32_e32 v20, v73, v20
	v_mul_f32_e32 v21, v77, v21
	s_waitcnt lgkmcnt(2)
	v_fmac_f32_e32 v18, v22, v74
	v_fmac_f32_e32 v19, v23, v78
	v_fmac_f32_e32 v20, v24, v75
	v_fmac_f32_e32 v21, v25, v79
	s_waitcnt lgkmcnt(1)
	v_fmac_f32_e32 v18, v26, v80
	v_fmac_f32_e32 v19, v27, v88
	v_fmac_f32_e32 v20, v28, v81
	v_fmac_f32_e32 v21, v29, v89
	s_waitcnt lgkmcnt(0)
	v_fmac_f32_e32 v18, v34, v86
	v_fmac_f32_e32 v19, v35, v92
	v_fmac_f32_e32 v20, v36, v87
	v_fmac_f32_e32 v21, v37, v93
	v_add_f32_e32 v18, v18, v19
	v_add_f32_e32 v19, v20, v21
	v_add_f32_e32 v18, v18, v19
	v_mul_f32_e64 v19, |v18|, s79
	v_exp_f32_e32 v19, v19
	v_min_f32_e32 v18, 0, v18
	v_add_f32_e32 v19, 1.0, v19
	v_log_f32_e32 v19, v19
	s_nop 0
	v_fma_f32 v41, v18, s80, -v19
	ds_read_b128 v[18:21], v32 offset:512
	ds_read_b128 v[22:25], v32 offset:528
	ds_read_b128 v[26:29], v32 offset:544
	ds_read_b128 v[34:37], v32 offset:560
	s_waitcnt lgkmcnt(3)
	v_fma_f32 v18, v18, v85, v123
	v_mul_f32_e32 v19, v76, v19
	v_mul_f32_e32 v20, v73, v20
	v_mul_f32_e32 v21, v77, v21
	s_waitcnt lgkmcnt(2)
	v_fmac_f32_e32 v18, v22, v74
	v_fmac_f32_e32 v19, v23, v78
	v_fmac_f32_e32 v20, v24, v75
	v_fmac_f32_e32 v21, v25, v79
	s_waitcnt lgkmcnt(1)
	v_fmac_f32_e32 v18, v26, v80
	v_fmac_f32_e32 v19, v27, v88
	v_fmac_f32_e32 v20, v28, v81
	v_fmac_f32_e32 v21, v29, v89
	s_waitcnt lgkmcnt(0)
	v_fmac_f32_e32 v18, v34, v86
	v_fmac_f32_e32 v19, v35, v92
	v_fmac_f32_e32 v20, v36, v87
	v_fmac_f32_e32 v21, v37, v93
	v_add_f32_e32 v18, v18, v19
	v_add_f32_e32 v19, v20, v21
	v_add_f32_e32 v18, v18, v19
	v_mul_f32_e64 v19, |v18|, s79
	v_exp_f32_e32 v19, v19
	v_min_f32_e32 v18, 0, v18
	v_add_f32_e32 v19, 1.0, v19
	v_log_f32_e32 v19, v19
	s_nop 0
	v_fma_f32 v42, v18, s80, -v19
	ds_read_b128 v[18:21], v32 offset:640
	ds_read_b128 v[22:25], v32 offset:656
	ds_read_b128 v[26:29], v32 offset:672
	ds_read_b128 v[34:37], v32 offset:688
	s_waitcnt lgkmcnt(3)
	v_fma_f32 v18, v18, v85, v123
	v_mul_f32_e32 v19, v76, v19
	v_mul_f32_e32 v20, v73, v20
	v_mul_f32_e32 v21, v77, v21
	s_waitcnt lgkmcnt(2)
	v_fmac_f32_e32 v18, v22, v74
	v_fmac_f32_e32 v19, v23, v78
	v_fmac_f32_e32 v20, v24, v75
	v_fmac_f32_e32 v21, v25, v79
	s_waitcnt lgkmcnt(1)
	v_fmac_f32_e32 v18, v26, v80
	v_fmac_f32_e32 v19, v27, v88
	v_fmac_f32_e32 v20, v28, v81
	v_fmac_f32_e32 v21, v29, v89
	s_waitcnt lgkmcnt(0)
; template <int DIR>
; DI float prep_gate_loop(const float* r_s, bf16_t* qt, bf16_t* kt, const float (&w)[16], float bias, int kk) {
;     ...
;         for (int i = 0; i < 16; ++i) {
;             const int tt = blk * 16 + i; const int t = DIR ? 63 - tt : tt;
;             const f32x4* rr = (const f32x4*)(r_s + t * 32 + DIR * 16);
;             const f32x4 r0 = rr[0], r1 = rr[1], r2 = rr[2], r3 = rr[3];
;             float s0 = __builtin_fmaf(r0[0], w[0], bias), s1 = r0[1] * w[1], s2 = r0[2] * w[2], s3 = r0[3] * w[3];
;             s0 = __builtin_fmaf(r1[0], w[4], s0); s1 = __builtin_fmaf(r1[1], w[5], s1); s2 = __builtin_fmaf(r1[2], w[6], s2); s3 = __builtin_fmaf(r1[3], w[7], s3);
;             s0 = __builtin_fmaf(r2[0], w[8], s0); s1 = __builtin_fmaf(r2[1], w[9], s1); s2 = __builtin_fmaf(r2[2], w[10], s2); s3 = __builtin_fmaf(r2[3], w[11], s3);
;             s0 = __builtin_fmaf(r3[0], w[12], s0); s1 = __builtin_fmaf(r3[1], w[13], s1); s2 = __builtin_fmaf(r3[2], w[14], s2); s3 = __builtin_fmaf(r3[3], w[15], s3);
;             const float pre = (s0 + s1) + (s2 + s3);
;             const float ex = __builtin_amdgcn_exp2f(-fabsf(pre) * LOG2E);
;             la[i] = (fminf(pre, 0.f) * LOG2E - __builtin_amdgcn_logf(1.f + ex)) * 0.0625f;
	v_fmac_f32_e32 v18, v34, v86
	v_fmac_f32_e32 v19, v35, v92
	v_fmac_f32_e32 v20, v36, v87
	v_fmac_f32_e32 v21, v37, v93
	v_add_f32_e32 v18, v18, v19
	v_add_f32_e32 v19, v20, v21
	v_add_f32_e32 v18, v18, v19
	v_mul_f32_e64 v19, |v18|, s79
	v_exp_f32_e32 v19, v19
	v_min_f32_e32 v18, 0, v18
	v_add_f32_e32 v19, 1.0, v19
	v_log_f32_e32 v19, v19
	s_nop 0
	v_fma_f32 v43, v18, s80, -v19
	ds_read_b128 v[18:21], v32 offset:768
	ds_read_b128 v[22:25], v32 offset:784
	ds_read_b128 v[26:29], v32 offset:800
	ds_read_b128 v[34:37], v32 offset:816
	s_waitcnt lgkmcnt(3)
	v_fma_f32 v18, v18, v85, v123
	v_mul_f32_e32 v19, v76, v19
	v_mul_f32_e32 v20, v73, v20
	v_mul_f32_e32 v21, v77, v21
	s_waitcnt lgkmcnt(2)
	v_fmac_f32_e32 v18, v22, v74
	v_fmac_f32_e32 v19, v23, v78
	v_fmac_f32_e32 v20, v24, v75
	v_fmac_f32_e32 v21, v25, v79
	s_waitcnt lgkmcnt(1)
	v_fmac_f32_e32 v18, v26, v80
	v_fmac_f32_e32 v19, v27, v88
	v_fmac_f32_e32 v20, v28, v81
	v_fmac_f32_e32 v21, v29, v89
	s_waitcnt lgkmcnt(0)
	v_fmac_f32_e32 v18, v34, v86
	v_fmac_f32_e32 v19, v35, v92
	v_fmac_f32_e32 v20, v36, v87
	v_fmac_f32_e32 v21, v37, v93
	v_add_f32_e32 v18, v18, v19
	v_add_f32_e32 v19, v20, v21
	v_add_f32_e32 v18, v18, v19
	v_mul_f32_e64 v19, |v18|, s79
	v_exp_f32_e32 v19, v19
	v_min_f32_e32 v18, 0, v18
	v_add_f32_e32 v19, 1.0, v19
	v_log_f32_e32 v19, v19
	s_nop 0
	v_fma_f32 v44, v18, s80, -v19
	ds_read_b128 v[18:21], v32 offset:896
	ds_read_b128 v[22:25], v32 offset:912
	ds_read_b128 v[26:29], v32 offset:928
	ds_read_b128 v[34:37], v32 offset:944
	s_waitcnt lgkmcnt(3)
	v_fma_f32 v18, v18, v85, v123
	v_mul_f32_e32 v19, v76, v19
	v_mul_f32_e32 v20, v73, v20
	v_mul_f32_e32 v21, v77, v21
	s_waitcnt lgkmcnt(2)
	v_fmac_f32_e32 v18, v22, v74
	v_fmac_f32_e32 v19, v23, v78
	v_fmac_f32_e32 v20, v24, v75
	v_fmac_f32_e32 v21, v25, v79
	s_waitcnt lgkmcnt(1)
	v_fmac_f32_e32 v18, v26, v80
	v_fmac_f32_e32 v19, v27, v88
	v_fmac_f32_e32 v20, v28, v81
	v_fmac_f32_e32 v21, v29, v89
	s_waitcnt lgkmcnt(0)
	v_fmac_f32_e32 v18, v34, v86
	v_fmac_f32_e32 v19, v35, v92
	v_fmac_f32_e32 v20, v36, v87
	v_fmac_f32_e32 v21, v37, v93
	v_add_f32_e32 v18, v18, v19
	v_add_f32_e32 v19, v20, v21
	v_add_f32_e32 v18, v18, v19
	v_mul_f32_e64 v19, |v18|, s79
	v_exp_f32_e32 v19, v19
	v_min_f32_e32 v18, 0, v18
	v_add_f32_e32 v19, 1.0, v19
	v_log_f32_e32 v19, v19
	s_nop 0
	v_fma_f32 v45, v18, s80, -v19
	ds_read_b128 v[18:21], v32 offset:1024
	ds_read_b128 v[22:25], v32 offset:1040
	ds_read_b128 v[26:29], v32 offset:1056
	ds_read_b128 v[34:37], v32 offset:1072
	s_waitcnt lgkmcnt(3)
	v_fma_f32 v18, v18, v85, v123
	v_mul_f32_e32 v19, v76, v19
	v_mul_f32_e32 v20, v73, v20
	v_mul_f32_e32 v21, v77, v21
	s_waitcnt lgkmcnt(2)
	v_fmac_f32_e32 v18, v22, v74
	v_fmac_f32_e32 v19, v23, v78
	v_fmac_f32_e32 v20, v24, v75
	v_fmac_f32_e32 v21, v25, v79
	s_waitcnt lgkmcnt(1)
	v_fmac_f32_e32 v18, v26, v80
	v_fmac_f32_e32 v19, v27, v88
	v_fmac_f32_e32 v20, v28, v81
	v_fmac_f32_e32 v21, v29, v89
	s_waitcnt lgkmcnt(0)
	v_fmac_f32_e32 v18, v34, v86
	v_fmac_f32_e32 v19, v35, v92
	v_fmac_f32_e32 v20, v36, v87
	v_fmac_f32_e32 v21, v37, v93
	v_add_f32_e32 v18, v18, v19
	v_add_f32_e32 v19, v20, v21
	v_add_f32_e32 v18, v18, v19
	v_mul_f32_e64 v19, |v18|, s79
	v_exp_f32_e32 v19, v19
	v_min_f32_e32 v18, 0, v18
	v_add_f32_e32 v19, 1.0, v19
	v_log_f32_e32 v19, v19
	s_nop 0
	v_fma_f32 v46, v18, s80, -v19
	ds_read_b128 v[18:21], v32 offset:1152
	ds_read_b128 v[22:25], v32 offset:1168
	ds_read_b128 v[26:29], v32 offset:1184
	ds_read_b128 v[34:37], v32 offset:1200
	s_waitcnt lgkmcnt(3)
	v_mul_f32_e32 v31, v73, v20
	v_mov_b32_e32 v20, v19
	v_fma_f32 v30, v18, v85, v123
	v_mul_f32_e64 v18, v76, v20
	v_mul_f32_e64 v19, v77, v21
	s_waitcnt lgkmcnt(2)
	v_mov_b32_e32 v20, v22
	v_mov_b32_e32 v21, v24
	v_mov_b32_e32 v24, v23
	v_fma_f32 v20, v20, v74, v30
	v_fma_f32 v21, v21, v75, v31
	v_fma_f32 v18, v24, v78, v18
	v_fma_f32 v19, v25, v79, v19
	s_waitcnt lgkmcnt(1)
	v_mov_b32_e32 v22, v26
	v_mov_b32_e32 v23, v28
	v_mov_b32_e32 v28, v27
	v_fma_f32 v20, v22, v80, v20
	v_fma_f32 v21, v23, v81, v21
	v_fma_f32 v18, v28, v88, v18
	v_fma_f32 v19, v29, v89, v19
	s_waitcnt lgkmcnt(0)
	v_mov_b32_e32 v22, v34
	v_mov_b32_e32 v23, v36
	v_mov_b32_e32 v36, v35
	v_fma_f32 v20, v22, v86, v20
	v_fma_f32 v21, v23, v87, v21
	v_fma_f32 v18, v36, v92, v18
	v_fma_f32 v19, v37, v93, v19
	s_nop 0
	v_add_f32_e64 v18, v20, v18
	v_add_f32_e64 v19, v21, v19
	s_nop 0
	v_add_f32_e32 v18, v18, v19
	v_mul_f32_e64 v19, |v18|, s79
	v_exp_f32_e32 v19, v19
	v_min_f32_e32 v18, 0, v18
	v_add_f32_e32 v19, 1.0, v19
	v_log_f32_e32 v19, v19
	s_nop 0
	v_fma_f32 v47, v18, s80, -v19
	ds_read_b128 v[18:21], v32 offset:1280
	ds_read_b128 v[22:25], v32 offset:1296
	ds_read_b128 v[26:29], v32 offset:1312
	ds_read_b128 v[34:37], v32 offset:1328
	s_waitcnt lgkmcnt(3)
	v_mul_f32_e32 v31, v73, v20
	v_mov_b32_e32 v20, v19
	v_fma_f32 v30, v18, v85, v123
	v_mul_f32_e64 v18, v76, v20
	v_mul_f32_e64 v19, v77, v21
	s_waitcnt lgkmcnt(2)
	v_mov_b32_e32 v20, v22
	v_mov_b32_e32 v21, v24
	v_mov_b32_e32 v24, v23
	v_fma_f32 v20, v20, v74, v30
	v_fma_f32 v21, v21, v75, v31
	v_fma_f32 v18, v24, v78, v18
	v_fma_f32 v19, v25, v79, v19
	s_waitcnt lgkmcnt(1)
	v_mov_b32_e32 v22, v26
	v_mov_b32_e32 v23, v28
	v_mov_b32_e32 v28, v27
	v_fma_f32 v20, v22, v80, v20
	v_fma_f32 v21, v23, v81, v21
	v_fma_f32 v18, v28, v88, v18
	v_fma_f32 v19, v29, v89, v19
	s_waitcnt lgkmcnt(0)
; template <int DIR>
; DI float prep_gate_loop(const float* r_s, bf16_t* qt, bf16_t* kt, const float (&w)[16], float bias, int kk) {
;     ...
;         for (int i = 0; i < 16; ++i) {
;             const int tt = blk * 16 + i; const int t = DIR ? 63 - tt : tt;
;             const f32x4* rr = (const f32x4*)(r_s + t * 32 + DIR * 16);
;             const f32x4 r0 = rr[0], r1 = rr[1], r2 = rr[2], r3 = rr[3];
;             float s0 = __builtin_fmaf(r0[0], w[0], bias), s1 = r0[1] * w[1], s2 = r0[2] * w[2], s3 = r0[3] * w[3];
;             s0 = __builtin_fmaf(r1[0], w[4], s0); s1 = __builtin_fmaf(r1[1], w[5], s1); s2 = __builtin_fmaf(r1[2], w[6], s2); s3 = __builtin_fmaf(r1[3], w[7], s3);
;             s0 = __builtin_fmaf(r2[0], w[8], s0); s1 = __builtin_fmaf(r2[1], w[9], s1); s2 = __builtin_fmaf(r2[2], w[10], s2); s3 = __builtin_fmaf(r2[3], w[11], s3);
;             s0 = __builtin_fmaf(r3[0], w[12], s0); s1 = __builtin_fmaf(r3[1], w[13], s1); s2 = __builtin_fmaf(r3[2], w[14], s2); s3 = __builtin_fmaf(r3[3], w[15], s3);
;             const float pre = (s0 + s1) + (s2 + s3);
;             const float ex = __builtin_amdgcn_exp2f(-fabsf(pre) * LOG2E);
;             la[i] = (fminf(pre, 0.f) * LOG2E - __builtin_amdgcn_logf(1.f + ex)) * 0.0625f;
;         }
; #pragma unroll
;         for (int i = 0; i < 16; ++i) { g += la[i]; la[i] = g; }
	v_mov_b32_e32 v22, v34
	v_mov_b32_e32 v23, v36
	v_mov_b32_e32 v36, v35
	v_fma_f32 v20, v22, v86, v20
	v_fma_f32 v21, v23, v87, v21
	v_fma_f32 v18, v36, v92, v18
	v_fma_f32 v19, v37, v93, v19
	s_nop 0
	v_add_f32_e64 v18, v20, v18
	v_add_f32_e64 v19, v21, v19
	s_nop 0
	v_add_f32_e32 v18, v18, v19
	v_mul_f32_e64 v19, |v18|, s79
	v_exp_f32_e32 v19, v19
	v_min_f32_e32 v18, 0, v18
	v_add_f32_e32 v19, 1.0, v19
	v_log_f32_e32 v19, v19
	s_nop 0
	v_fma_f32 v48, v18, s80, -v19
	ds_read_b128 v[18:21], v32 offset:1408
	ds_read_b128 v[22:25], v32 offset:1424
	ds_read_b128 v[26:29], v32 offset:1440
	ds_read_b128 v[34:37], v32 offset:1456
	s_waitcnt lgkmcnt(3)
	v_mul_f32_e32 v31, v73, v20
	v_mov_b32_e32 v20, v19
	v_fma_f32 v30, v18, v85, v123
	v_mul_f32_e64 v18, v76, v20
	v_mul_f32_e64 v19, v77, v21
	s_waitcnt lgkmcnt(2)
	v_mov_b32_e32 v20, v22
	v_mov_b32_e32 v21, v24
	v_mov_b32_e32 v24, v23
	v_fma_f32 v20, v20, v74, v30
	v_fma_f32 v21, v21, v75, v31
	v_fma_f32 v18, v24, v78, v18
	v_fma_f32 v19, v25, v79, v19
	s_waitcnt lgkmcnt(1)
	v_mov_b32_e32 v22, v26
	v_mov_b32_e32 v23, v28
	v_mov_b32_e32 v28, v27
	v_fma_f32 v20, v22, v80, v20
	v_fma_f32 v21, v23, v81, v21
	v_fma_f32 v18, v28, v88, v18
	v_fma_f32 v19, v29, v89, v19
	s_waitcnt lgkmcnt(0)
	v_mov_b32_e32 v22, v34
	v_mov_b32_e32 v23, v36
	v_mov_b32_e32 v36, v35
	v_fma_f32 v20, v22, v86, v20
	v_fma_f32 v21, v23, v87, v21
	v_fma_f32 v18, v36, v92, v18
	v_fma_f32 v19, v37, v93, v19
	s_nop 0
	v_add_f32_e64 v18, v20, v18
	v_add_f32_e64 v19, v21, v19
	s_nop 0
	v_add_f32_e32 v18, v18, v19
	v_mul_f32_e64 v19, |v18|, s79
	v_exp_f32_e32 v19, v19
	v_min_f32_e32 v18, 0, v18
	v_add_f32_e32 v19, 1.0, v19
	v_log_f32_e32 v19, v19
	s_nop 0
	v_fma_f32 v49, v18, s80, -v19
	ds_read_b128 v[18:21], v32 offset:1536
	ds_read_b128 v[22:25], v32 offset:1552
	ds_read_b128 v[26:29], v32 offset:1568
	ds_read_b128 v[34:37], v32 offset:1584
	s_waitcnt lgkmcnt(3)
	v_mul_f32_e32 v31, v73, v20
	v_mov_b32_e32 v20, v19
	v_fma_f32 v30, v18, v85, v123
	v_mul_f32_e64 v18, v76, v20
	v_mul_f32_e64 v19, v77, v21
	s_waitcnt lgkmcnt(2)
	v_mov_b32_e32 v20, v22
	v_mov_b32_e32 v21, v24
	v_mov_b32_e32 v24, v23
	v_fma_f32 v20, v20, v74, v30
	v_fma_f32 v21, v21, v75, v31
	v_fma_f32 v18, v24, v78, v18
	v_fma_f32 v19, v25, v79, v19
	s_waitcnt lgkmcnt(1)
	v_mov_b32_e32 v22, v26
	v_mov_b32_e32 v23, v28
	v_mov_b32_e32 v28, v27
	v_fma_f32 v20, v22, v80, v20
	v_fma_f32 v21, v23, v81, v21
	v_fma_f32 v18, v28, v88, v18
	v_fma_f32 v19, v29, v89, v19
	s_waitcnt lgkmcnt(0)
	v_mov_b32_e32 v22, v34
	v_mov_b32_e32 v23, v36
	v_mov_b32_e32 v36, v35
	v_fma_f32 v20, v22, v86, v20
	v_fma_f32 v21, v23, v87, v21
	v_fma_f32 v18, v36, v92, v18
	v_fma_f32 v19, v37, v93, v19
	s_nop 0
	v_add_f32_e64 v18, v20, v18
	v_add_f32_e64 v19, v21, v19
	s_nop 0
	v_add_f32_e32 v18, v18, v19
	v_mul_f32_e64 v19, |v18|, s79
	v_exp_f32_e32 v19, v19
	v_min_f32_e32 v18, 0, v18
	v_add_f32_e32 v19, 1.0, v19
	v_log_f32_e32 v19, v19
	s_nop 0
	v_fma_f32 v50, v18, s80, -v19
	ds_read_b128 v[18:21], v32 offset:1664
	ds_read_b128 v[22:25], v32 offset:1680
	ds_read_b128 v[26:29], v32 offset:1696
	ds_read_b128 v[34:37], v32 offset:1712
	s_waitcnt lgkmcnt(3)
	v_mul_f32_e32 v31, v73, v20
	v_mov_b32_e32 v20, v19
	v_fma_f32 v30, v18, v85, v123
	v_mul_f32_e64 v18, v76, v20
	v_mul_f32_e64 v19, v77, v21
	s_waitcnt lgkmcnt(2)
	v_mov_b32_e32 v20, v22
	v_mov_b32_e32 v21, v24
	v_mov_b32_e32 v24, v23
	v_fma_f32 v20, v20, v74, v30
	v_fma_f32 v21, v21, v75, v31
	v_fma_f32 v18, v24, v78, v18
	v_fma_f32 v19, v25, v79, v19
	s_waitcnt lgkmcnt(1)
	v_mov_b32_e32 v22, v26
	v_mov_b32_e32 v23, v28
	v_mov_b32_e32 v28, v27
	v_fma_f32 v20, v22, v80, v20
	v_fma_f32 v21, v23, v81, v21
	v_fma_f32 v18, v28, v88, v18
	v_fma_f32 v19, v29, v89, v19
	s_waitcnt lgkmcnt(0)
	v_mov_b32_e32 v22, v34
	v_mov_b32_e32 v23, v36
	v_mov_b32_e32 v36, v35
	v_fma_f32 v20, v22, v86, v20
	v_fma_f32 v21, v23, v87, v21
	v_fma_f32 v18, v36, v92, v18
	v_fma_f32 v19, v37, v93, v19
	s_nop 0
	v_add_f32_e64 v18, v20, v18
	v_add_f32_e64 v19, v21, v19
	s_nop 0
	v_add_f32_e32 v18, v18, v19
	v_mul_f32_e64 v19, |v18|, s79
	v_exp_f32_e32 v19, v19
	v_min_f32_e32 v18, 0, v18
	v_add_f32_e32 v19, 1.0, v19
	v_log_f32_e32 v19, v19
	s_nop 0
	v_fma_f32 v51, v18, s80, -v19
	ds_read_b128 v[18:21], v32 offset:1792
	ds_read_b128 v[22:25], v32 offset:1808
	ds_read_b128 v[26:29], v32 offset:1824
	ds_read_b128 v[34:37], v32 offset:1840
	s_waitcnt lgkmcnt(3)
	v_mul_f32_e32 v31, v73, v20
	v_mov_b32_e32 v20, v19
	v_fma_f32 v30, v18, v85, v123
	v_mul_f32_e64 v18, v76, v20
	v_mul_f32_e64 v19, v77, v21
	s_waitcnt lgkmcnt(2)
	v_mov_b32_e32 v20, v22
	v_mov_b32_e32 v21, v24
	v_mov_b32_e32 v24, v23
	v_fma_f32 v20, v20, v74, v30
	v_fma_f32 v21, v21, v75, v31
	v_fma_f32 v18, v24, v78, v18
	v_fma_f32 v19, v25, v79, v19
	s_waitcnt lgkmcnt(1)
	v_mov_b32_e32 v22, v26
	v_mov_b32_e32 v23, v28
	v_mov_b32_e32 v28, v27
	v_fma_f32 v20, v22, v80, v20
	v_fma_f32 v21, v23, v81, v21
	v_fma_f32 v18, v28, v88, v18
	v_fma_f32 v19, v29, v89, v19
	s_waitcnt lgkmcnt(0)
	v_mov_b32_e32 v22, v34
	v_mov_b32_e32 v23, v36
	v_mov_b32_e32 v36, v35
	v_fma_f32 v20, v22, v86, v20
	v_fma_f32 v21, v23, v87, v21
	v_fma_f32 v18, v36, v92, v18
	v_fma_f32 v19, v37, v93, v19
	s_nop 0
	v_add_f32_e64 v18, v20, v18
	v_add_f32_e64 v19, v21, v19
	s_nop 0
	v_add_f32_e32 v18, v18, v19
	v_mul_f32_e64 v19, |v18|, s79
	v_exp_f32_e32 v19, v19
	v_min_f32_e32 v18, 0, v18
	v_add_f32_e32 v19, 1.0, v19
	v_log_f32_e32 v19, v19
	s_nop 0
	v_fma_f32 v52, v18, s80, -v19
	ds_read_b128 v[18:21], v32 offset:1920
	ds_read_b128 v[22:25], v32 offset:1936
	ds_read_b128 v[26:29], v32 offset:1952
	ds_read_b128 v[34:37], v32 offset:1968
	v_fmamk_f32 v32, v39, 0x3d800000, v33
	s_waitcnt lgkmcnt(3)
; DI float bf2f(bf16_t b) { return __uint_as_float(((unsigned)b) << 16); }
; DI bf16_t f2bf(float f) { return (bf16_t)(pk2(f, 0.f) & 0xffffu); }
; template <int DIR>
; DI float prep_gate_loop(const float* r_s, bf16_t* qt, bf16_t* kt, const float (&w)[16], float bias, int kk) {
;     ...
;         for (int i = 0; i < 16; ++i) {
;             const int tt = blk * 16 + i; const int t = DIR ? 63 - tt : tt;
;             const f32x4* rr = (const f32x4*)(r_s + t * 32 + DIR * 16);
;             const f32x4 r0 = rr[0], r1 = rr[1], r2 = rr[2], r3 = rr[3];
;             float s0 = __builtin_fmaf(r0[0], w[0], bias), s1 = r0[1] * w[1], s2 = r0[2] * w[2], s3 = r0[3] * w[3];
;             s0 = __builtin_fmaf(r1[0], w[4], s0); s1 = __builtin_fmaf(r1[1], w[5], s1); s2 = __builtin_fmaf(r1[2], w[6], s2); s3 = __builtin_fmaf(r1[3], w[7], s3);
;             s0 = __builtin_fmaf(r2[0], w[8], s0); s1 = __builtin_fmaf(r2[1], w[9], s1); s2 = __builtin_fmaf(r2[2], w[10], s2); s3 = __builtin_fmaf(r2[3], w[11], s3);
;             s0 = __builtin_fmaf(r3[0], w[12], s0); s1 = __builtin_fmaf(r3[1], w[13], s1); s2 = __builtin_fmaf(r3[2], w[14], s2); s3 = __builtin_fmaf(r3[3], w[15], s3);
;             const float pre = (s0 + s1) + (s2 + s3);
;             const float ex = __builtin_amdgcn_exp2f(-fabsf(pre) * LOG2E);
;             la[i] = (fminf(pre, 0.f) * LOG2E - __builtin_amdgcn_logf(1.f + ex)) * 0.0625f;
;         }
; #pragma unroll
;         for (int i = 0; i < 16; ++i) { g += la[i]; la[i] = g; }
; #pragma unroll
;         for (int i = 0; i < 16; ++i) {
;             const int tt = blk * 16 + i; const int t = DIR ? 63 - tt : tt;
;             const float e = __builtin_amdgcn_exp2f(la[i]);
;             bf16_t* qp = qt + (DIR * 64 + t) * 264 + kk; bf16_t* kp = kt + (DIR * 64 + t) * 264 + kk;
;             const float qv = bf2f(*qp), kv = bf2f(*kp);
;             *qp = f2bf(qv * 0.0625f * e);
;             *kp = f2bf(kv * __builtin_amdgcn_rcpf(e));
	v_mul_f32_e32 v31, v73, v20
	v_mov_b32_e32 v20, v19
	v_fma_f32 v30, v18, v85, v123
	v_mul_f32_e64 v18, v76, v20
	v_mul_f32_e64 v19, v77, v21
	s_waitcnt lgkmcnt(2)
	v_mov_b32_e32 v20, v22
	v_mov_b32_e32 v21, v24
	v_mov_b32_e32 v24, v23
	v_fma_f32 v20, v20, v74, v30
	v_fma_f32 v21, v21, v75, v31
	v_fma_f32 v18, v24, v78, v18
	v_fma_f32 v19, v25, v79, v19
	s_waitcnt lgkmcnt(1)
	v_mov_b32_e32 v22, v26
	v_mov_b32_e32 v23, v28
	v_mov_b32_e32 v28, v27
	v_fma_f32 v20, v22, v80, v20
	v_fma_f32 v21, v23, v81, v21
	v_fma_f32 v18, v28, v88, v18
	v_fma_f32 v19, v29, v89, v19
	s_waitcnt lgkmcnt(0)
	v_mov_b32_e32 v22, v34
	v_mov_b32_e32 v23, v36
	v_mov_b32_e32 v36, v35
	v_add_u32_e32 v34, s52, v120
	v_fma_f32 v18, v36, v92, v18
	v_fma_f32 v19, v37, v93, v19
	ds_read_u16 v36, v34 offset:8192
	v_exp_f32_e32 v33, v33
	v_add_u32_e32 v35, 0x12800, v34
	ds_read_u16 v37, v35
	v_fmamk_f32 v31, v40, 0x3d800000, v32
	s_waitcnt lgkmcnt(1)
	v_lshlrev_b32_e32 v36, 16, v36
	v_mul_f32_e32 v36, 0x3d800000, v36
	v_mul_f32_e32 v36, v33, v36
	v_rcp_f32_e32 v33, v33
	s_waitcnt lgkmcnt(0)
	v_lshlrev_b32_e32 v37, 16, v37
	v_exp_f32_e32 v32, v32
	v_cvt_pk_bf16_f32 v36, v36, s0
	v_mul_f32_e32 v33, v33, v37
	v_cvt_pk_bf16_f32 v33, v33, s0
	ds_write_b16 v35, v33
	ds_read_u16 v35, v34 offset:8720
	v_add_u32_e32 v33, 0x12a10, v34
	ds_write_b16 v34, v36 offset:8192
	ds_read_u16 v36, v33
	v_fmamk_f32 v30, v41, 0x3d800000, v31
	s_waitcnt lgkmcnt(2)
	v_lshlrev_b32_e32 v35, 16, v35
	v_mul_f32_e32 v35, 0x3d800000, v35
	v_mul_f32_e32 v35, v32, v35
	v_rcp_f32_e32 v32, v32
	s_waitcnt lgkmcnt(0)
	v_lshlrev_b32_e32 v36, 16, v36
	v_exp_f32_e32 v31, v31
	v_cvt_pk_bf16_f32 v35, v35, s0
	v_mul_f32_e32 v32, v32, v36
	v_cvt_pk_bf16_f32 v32, v32, s0
	ds_write_b16 v33, v32
	ds_read_u16 v33, v34 offset:9248
	v_add_u32_e32 v32, 0x12c20, v34
	ds_write_b16 v34, v35 offset:8720
	ds_read_u16 v35, v32
	v_fmamk_f32 v29, v42, 0x3d800000, v30
	s_waitcnt lgkmcnt(2)
	v_lshlrev_b32_e32 v33, 16, v33
	v_mul_f32_e32 v33, 0x3d800000, v33
	v_mul_f32_e32 v33, v31, v33
	v_rcp_f32_e32 v31, v31
	s_waitcnt lgkmcnt(0)
	v_lshlrev_b32_e32 v35, 16, v35
	v_exp_f32_e32 v30, v30
	v_cvt_pk_bf16_f32 v33, v33, s0
	v_mul_f32_e32 v31, v31, v35
	v_cvt_pk_bf16_f32 v31, v31, s0
	ds_write_b16 v32, v31
	ds_read_u16 v32, v34 offset:9776
	v_add_u32_e32 v31, 0x12e30, v34
	ds_write_b16 v34, v33 offset:9248
	ds_read_u16 v33, v31
	v_fmamk_f32 v28, v43, 0x3d800000, v29
	s_waitcnt lgkmcnt(2)
	v_lshlrev_b32_e32 v32, 16, v32
	v_mul_f32_e32 v32, 0x3d800000, v32
	v_mul_f32_e32 v32, v30, v32
	v_rcp_f32_e32 v30, v30
	s_waitcnt lgkmcnt(0)
	v_lshlrev_b32_e32 v33, 16, v33
	v_exp_f32_e32 v29, v29
	v_cvt_pk_bf16_f32 v32, v32, s0
	v_mul_f32_e32 v30, v30, v33
	v_cvt_pk_bf16_f32 v30, v30, s0
	ds_write_b16 v31, v30
	ds_read_u16 v31, v34 offset:10304
	v_add_u32_e32 v30, 0x13040, v34
	ds_write_b16 v34, v32 offset:9776
	ds_read_u16 v32, v30
	v_fmamk_f32 v27, v44, 0x3d800000, v28
	s_waitcnt lgkmcnt(2)
	v_lshlrev_b32_e32 v31, 16, v31
	v_mul_f32_e32 v31, 0x3d800000, v31
	v_mul_f32_e32 v31, v29, v31
	v_rcp_f32_e32 v29, v29
	s_waitcnt lgkmcnt(0)
	v_lshlrev_b32_e32 v32, 16, v32
	v_exp_f32_e32 v28, v28
	v_cvt_pk_bf16_f32 v31, v31, s0
	v_mul_f32_e32 v29, v29, v32
	v_cvt_pk_bf16_f32 v29, v29, s0
	ds_write_b16 v30, v29
	ds_read_u16 v30, v34 offset:10832
	v_add_u32_e32 v29, 0x13250, v34
	ds_write_b16 v34, v31 offset:10304
	ds_read_u16 v31, v29
	v_fmamk_f32 v26, v45, 0x3d800000, v27
	s_waitcnt lgkmcnt(2)
	v_lshlrev_b32_e32 v30, 16, v30
	v_mul_f32_e32 v30, 0x3d800000, v30
	v_mul_f32_e32 v30, v28, v30
	v_rcp_f32_e32 v28, v28
	s_waitcnt lgkmcnt(0)
	v_lshlrev_b32_e32 v31, 16, v31
	v_exp_f32_e32 v27, v27
	v_cvt_pk_bf16_f32 v30, v30, s0
	v_mul_f32_e32 v28, v28, v31
	v_cvt_pk_bf16_f32 v28, v28, s0
	ds_write_b16 v29, v28
	ds_read_u16 v29, v34 offset:11360
	v_add_u32_e32 v28, 0x13460, v34
	ds_write_b16 v34, v30 offset:10832
	ds_read_u16 v30, v28
	v_fmamk_f32 v25, v46, 0x3d800000, v26
	s_waitcnt lgkmcnt(2)
	v_lshlrev_b32_e32 v29, 16, v29
	v_mul_f32_e32 v29, 0x3d800000, v29
	v_mul_f32_e32 v29, v27, v29
	v_rcp_f32_e32 v27, v27
	s_waitcnt lgkmcnt(0)
	v_lshlrev_b32_e32 v30, 16, v30
	v_exp_f32_e32 v26, v26
	v_cvt_pk_bf16_f32 v29, v29, s0
	v_mul_f32_e32 v27, v27, v30
	v_cvt_pk_bf16_f32 v27, v27, s0
	ds_write_b16 v28, v27
	ds_read_u16 v28, v34 offset:11888
	v_add_u32_e32 v27, 0x13670, v34
	ds_write_b16 v34, v29 offset:11360
	ds_read_u16 v29, v27
	v_fmamk_f32 v24, v47, 0x3d800000, v25
	s_waitcnt lgkmcnt(2)
	v_lshlrev_b32_e32 v28, 16, v28
	v_mul_f32_e32 v28, 0x3d800000, v28
	v_mul_f32_e32 v28, v26, v28
	v_rcp_f32_e32 v26, v26
	s_waitcnt lgkmcnt(0)
; DI float bf2f(bf16_t b) { return __uint_as_float(((unsigned)b) << 16); }
; DI bf16_t f2bf(float f) { return (bf16_t)(pk2(f, 0.f) & 0xffffu); }
; template <int DIR>
; DI float prep_gate_loop(const float* r_s, bf16_t* qt, bf16_t* kt, const float (&w)[16], float bias, int kk) {
;     ...
;             float s0 = __builtin_fmaf(r0[0], w[0], bias), s1 = r0[1] * w[1], s2 = r0[2] * w[2], s3 = r0[3] * w[3];
;             s0 = __builtin_fmaf(r1[0], w[4], s0); s1 = __builtin_fmaf(r1[1], w[5], s1); s2 = __builtin_fmaf(r1[2], w[6], s2); s3 = __builtin_fmaf(r1[3], w[7], s3);
;             s0 = __builtin_fmaf(r2[0], w[8], s0); s1 = __builtin_fmaf(r2[1], w[9], s1); s2 = __builtin_fmaf(r2[2], w[10], s2); s3 = __builtin_fmaf(r2[3], w[11], s3);
;             s0 = __builtin_fmaf(r3[0], w[12], s0); s1 = __builtin_fmaf(r3[1], w[13], s1); s2 = __builtin_fmaf(r3[2], w[14], s2); s3 = __builtin_fmaf(r3[3], w[15], s3);
;             const float pre = (s0 + s1) + (s2 + s3);
;             const float ex = __builtin_amdgcn_exp2f(-fabsf(pre) * LOG2E);
;             la[i] = (fminf(pre, 0.f) * LOG2E - __builtin_amdgcn_logf(1.f + ex)) * 0.0625f;
;         }
; #pragma unroll
;         for (int i = 0; i < 16; ++i) { g += la[i]; la[i] = g; }
; #pragma unroll
;         for (int i = 0; i < 16; ++i) {
;             const int tt = blk * 16 + i; const int t = DIR ? 63 - tt : tt;
;             const float e = __builtin_amdgcn_exp2f(la[i]);
;             bf16_t* qp = qt + (DIR * 64 + t) * 264 + kk; bf16_t* kp = kt + (DIR * 64 + t) * 264 + kk;
;             const float qv = bf2f(*qp), kv = bf2f(*kp);
;             *qp = f2bf(qv * 0.0625f * e);
;             *kp = f2bf(kv * __builtin_amdgcn_rcpf(e));
;         }
;     }
;     return __builtin_amdgcn_exp2f(g);
	v_lshlrev_b32_e32 v29, 16, v29
	v_exp_f32_e32 v25, v25
	v_cvt_pk_bf16_f32 v28, v28, s0
	v_mul_f32_e32 v26, v26, v29
	v_cvt_pk_bf16_f32 v26, v26, s0
	ds_write_b16 v27, v26
	ds_read_u16 v27, v34 offset:12416
	v_add_u32_e32 v26, 0x13880, v34
	ds_write_b16 v34, v28 offset:11888
	ds_read_u16 v28, v26
	v_fma_f32 v20, v22, v86, v20
	v_fma_f32 v21, v23, v87, v21
	s_waitcnt lgkmcnt(2)
	v_lshlrev_b32_e32 v27, 16, v27
	v_mul_f32_e32 v27, 0x3d800000, v27
	v_mul_f32_e32 v27, v25, v27
	v_rcp_f32_e32 v25, v25
	s_waitcnt lgkmcnt(0)
	v_lshlrev_b32_e32 v28, 16, v28
	v_fmamk_f32 v23, v48, 0x3d800000, v24
	v_exp_f32_e32 v24, v24
	v_mul_f32_e32 v25, v25, v28
	v_cvt_pk_bf16_f32 v25, v25, s0
	ds_write_b16 v26, v25
	ds_read_u16 v26, v34 offset:12944
	v_cvt_pk_bf16_f32 v27, v27, s0
	v_add_u32_e32 v25, 0x13a90, v34
	ds_write_b16 v34, v27 offset:12416
	ds_read_u16 v27, v25
	s_waitcnt lgkmcnt(2)
	v_lshlrev_b32_e32 v26, 16, v26
	v_mul_f32_e32 v26, 0x3d800000, v26
	v_mul_f32_e32 v26, v24, v26
	v_rcp_f32_e32 v24, v24
	s_waitcnt lgkmcnt(0)
	v_lshlrev_b32_e32 v27, 16, v27
	v_fmamk_f32 v22, v49, 0x3d800000, v23
	v_exp_f32_e32 v23, v23
	v_mul_f32_e32 v24, v24, v27
	v_cvt_pk_bf16_f32 v24, v24, s0
	ds_write_b16 v25, v24
	ds_read_u16 v25, v34 offset:13472
	v_cvt_pk_bf16_f32 v26, v26, s0
	v_add_u32_e32 v24, 0x13ca0, v34
	ds_write_b16 v34, v26 offset:12944
	ds_read_u16 v26, v24
	s_waitcnt lgkmcnt(2)
	v_lshlrev_b32_e32 v25, 16, v25
	v_mul_f32_e32 v25, 0x3d800000, v25
	v_mul_f32_e32 v25, v23, v25
	v_rcp_f32_e32 v23, v23
	s_waitcnt lgkmcnt(0)
	v_lshlrev_b32_e32 v26, 16, v26
	v_add_f32_e64 v18, v20, v18
	v_add_f32_e64 v19, v21, v19
	v_fmamk_f32 v21, v50, 0x3d800000, v22
	v_mul_f32_e32 v23, v23, v26
	v_cvt_pk_bf16_f32 v23, v23, s0
	ds_write_b16 v24, v23
	ds_read_u16 v24, v34 offset:14000
	v_exp_f32_e32 v22, v22
	v_cvt_pk_bf16_f32 v25, v25, s0
	v_add_u32_e32 v23, 0x13eb0, v34
	ds_write_b16 v34, v25 offset:13472
	ds_read_u16 v25, v23
	s_waitcnt lgkmcnt(2)
	v_lshlrev_b32_e32 v24, 16, v24
	v_mul_f32_e32 v24, 0x3d800000, v24
	v_mul_f32_e32 v24, v22, v24
	v_rcp_f32_e32 v22, v22
	s_waitcnt lgkmcnt(0)
	v_lshlrev_b32_e32 v25, 16, v25
	v_fmamk_f32 v20, v51, 0x3d800000, v21
	v_exp_f32_e32 v21, v21
	v_mul_f32_e32 v22, v22, v25
	v_cvt_pk_bf16_f32 v22, v22, s0
	ds_write_b16 v23, v22
	ds_read_u16 v23, v34 offset:14528
	v_cvt_pk_bf16_f32 v24, v24, s0
	v_add_u32_e32 v22, 0x140c0, v34
	v_add_f32_e32 v18, v18, v19
	ds_write_b16 v34, v24 offset:14000
	ds_read_u16 v24, v22
	s_waitcnt lgkmcnt(2)
	v_lshlrev_b32_e32 v23, 16, v23
	v_mul_f32_e64 v19, |v18|, s79
	v_mul_f32_e32 v23, 0x3d800000, v23
	v_exp_f32_e32 v19, v19
	v_mul_f32_e32 v23, v21, v23
	v_rcp_f32_e32 v21, v21
	s_waitcnt lgkmcnt(0)
	v_lshlrev_b32_e32 v24, 16, v24
	v_add_f32_e32 v19, 1.0, v19
	v_log_f32_e32 v19, v19
	v_mul_f32_e32 v21, v21, v24
	v_cvt_pk_bf16_f32 v21, v21, s0
	ds_write_b16 v22, v21
	ds_read_u16 v22, v34 offset:15056
	v_min_f32_e32 v18, 0, v18
	v_fma_f32 v18, v18, s80, -v19
	v_fmamk_f32 v19, v52, 0x3d800000, v20
	v_exp_f32_e32 v20, v20
	v_cvt_pk_bf16_f32 v23, v23, s0
	v_add_u32_e32 v21, 0x142d0, v34
	ds_write_b16 v34, v23 offset:14528
	ds_read_u16 v23, v21
	s_waitcnt lgkmcnt(2)
	v_lshlrev_b32_e32 v22, 16, v22
	v_mul_f32_e32 v22, 0x3d800000, v22
	v_mul_f32_e32 v22, v20, v22
	v_rcp_f32_e32 v20, v20
	s_waitcnt lgkmcnt(0)
	v_lshlrev_b32_e32 v23, 16, v23
	v_fmamk_f32 v18, v18, 0x3d800000, v19
	v_exp_f32_e32 v19, v19
	v_mul_f32_e32 v20, v20, v23
	v_cvt_pk_bf16_f32 v20, v20, s0
	ds_write_b16 v21, v20
	ds_read_u16 v21, v34 offset:15584
	v_cvt_pk_bf16_f32 v22, v22, s0
	v_add_u32_e32 v20, 0x144e0, v34
	ds_write_b16 v34, v22 offset:15056
	ds_read_u16 v22, v20
	s_waitcnt lgkmcnt(2)
	v_lshlrev_b32_e32 v21, 16, v21
	v_mul_f32_e32 v21, 0x3d800000, v21
	v_mul_f32_e32 v21, v19, v21
	v_rcp_f32_e32 v19, v19
	s_waitcnt lgkmcnt(0)
	v_lshlrev_b32_e32 v22, 16, v22
	v_exp_f32_e32 v112, v18
	v_cvt_pk_bf16_f32 v21, v21, s0
	v_mul_f32_e32 v19, v19, v22
	v_cvt_pk_bf16_f32 v19, v19, s0
	ds_write_b16 v20, v19
	ds_read_u16 v20, v34 offset:16112
	v_add_u32_e32 v19, 0x146f0, v34
	ds_write_b16 v34, v21 offset:15584
	ds_read_u16 v21, v19
	s_addk_i32 s52, 0x2100
	s_waitcnt lgkmcnt(2)
	v_lshlrev_b32_e32 v20, 16, v20
	v_mul_f32_e32 v20, 0x3d800000, v20
	v_mul_f32_e32 v20, v112, v20
	v_cvt_pk_bf16_f32 v20, v20, s0
	ds_write_b16 v34, v20 offset:16112
	v_rcp_f32_e32 v20, v112
	s_waitcnt lgkmcnt(1)
	v_lshlrev_b32_e32 v21, 16, v21
	s_cmpk_eq_u32 s52, 0x8400
	v_mov_b32_e32 v33, v18
	v_mul_f32_e32 v20, v20, v21
	v_cvt_pk_bf16_f32 v20, v20, s0
	ds_write_b16 v19, v20
	s_cbranch_scc0 .LBB0_1539
	s_branch .LBB0_1532
